# GEMM K-loops: hipcc per-block s_setprio flips removed, one static s_setprio 1 for waves 4-7 per unit (strategy: static priority for the younger half); on top of v46
# baseline (speedup 1.0000x reference)
; #define PG8_STAGE(bufoff, gbase, voff) do { _Pragma("unroll") for (int _i = 0; _i < 2; ++_i) \
;         __builtin_amdgcn_global_load_lds((const unsigned*)((const char*)(gbase) + (voff)[_i]), (PG8_LAS unsigned*)(lds + (bufoff) + ldsw + _i * 8192), 16, 0, 0); } while (0)
; #define PG8_LDA(dst, b, h) do { _Pragma("unroll") for (int m = 0; m < 4; ++m) _Pragma("unroll") for (int k = 0; k < 2; ++k) dst[m][k] = *(const PG8_LAS bf16x8*)(lds + PG8_SA(b, h) + aoff + m * 2048 + k * 1024); } while (0)
; #define PG8_LDB(dst, b, h) do { _Pragma("unroll") for (int n = 0; n < 2; ++n) _Pragma("unroll") for (int k = 0; k < 2; ++k) dst[n][k] = *(const PG8_LAS bf16x8*)(lds + PG8_SB(b, h) + boff + n * 2048 + k * 1024); } while (0)
; #define PG8_MMA(ai, bj, At, Bt) do { __builtin_amdgcn_s_setprio(1); _Pragma("unroll") for (int m = 0; m < 4; ++m) _Pragma("unroll") for (int n = 0; n < 2; ++n) _Pragma("unroll") for (int k = 0; k < 2; ++k) \
;         acc[ai][bj][m][n] = __builtin_amdgcn_mfma_f32_16x16x32_bf16(Bt[n][k], At[m][k], acc[ai][bj][m][n], 0, 0, 0); __builtin_amdgcn_s_setprio(0); } while (0)
; #define PG8_WAIT_V(n) asm volatile("s_waitcnt vmcnt(" #n ")" ::: "memory")
; #define PG8_WAIT_L(n) asm volatile("s_waitcnt lgkmcnt(" #n ")" ::: "memory")
; #define PG8_BAR __builtin_amdgcn_s_barrier()
; #define PG8_SCHED __builtin_amdgcn_sched_barrier(0)
; template <class Epi, class Sched, bool ALIGN_EPI = false, bool SP2 = false>
; __device__ __forceinline__ void gemm_phase(PG8_LAS unsigned char* lds, const Gemm g, const Sched& S, const Epi& E) {
;     ...
;     Unit cur, nxt; int ui = 0;
;     if (!S.next(0, cur)) return;
;     f32x4 acc[2][2][4][2];
; #pragma unroll
;     for (int a = 0; a < 2; ++a)
; #pragma unroll
;         for (int b = 0; b < 2; ++b)
; #pragma unroll
;             for (int m = 0; m < 4; ++m)
; #pragma unroll
;                 for (int n = 0; n < 2; ++n) acc[a][b][m][n] = (f32x4){0.f, 0.f, 0.f, 0.f};
;     bf16x8 At[4][2], B0[2][2], B1[2][2];
;     const char* cA = (const char*)g.A + (size_t)cur.pm * tstep; const char* cB = (const char*)g.Bt + (size_t)cur.pn * tstep;
;     S.a_ready(cur);
;     ...
;             PG8_LDB(B0, 0, 0); PG8_LDB(B1, 0, 1); PG8_SCHED; PG8_LDA(At, 0, 0); PG8_STAGE(PG8_SA(1, 1), a1 + hstep, voffA);
;             PG8_WAIT_V(8); PG8_WAIT_L(0); PG8_BAR; PG8_MMA(0, 0, At, B0); PG8_MMA(0, 1, At, B1); PG8_BAR; PG8_SCHED;
.LBB0_187:
	s_ashr_i32 s31, s30, 31
	s_lshl_b64 s[4:5], s[30:31], 19
	s_add_u32 s36, s22, s4
	s_addc_u32 s37, s23, s5
	s_and_b64 s[4:5], s[6:7], exec
	s_cselect_b32 s8, s37, s1
	s_cselect_b32 s9, s36, s0
	s_ashr_i32 s29, s28, 31
	s_lshl_b64 s[4:5], s[28:29], 19
	s_add_u32 s38, s20, s4
	s_addc_u32 s39, s21, s5
	s_and_b64 s[4:5], s[6:7], exec
	s_cselect_b32 s29, s39, s3
	s_cselect_b32 s31, s38, s2
	s_add_u32 s0, s0, 0x40080
	s_addc_u32 s1, s1, 0
	s_add_u32 s33, s2, 0x100
	v_mov_b32_e32 v0, 0
	s_addc_u32 s40, s3, 0
	s_mov_b32 s41, -2
	v_mov_b32_e32 v1, v0
	v_mov_b32_e32 v2, v0
	v_mov_b32_e32 v3, v0
	v_mov_b32_e32 v4, v0
	v_mov_b32_e32 v5, v0
	v_mov_b32_e32 v6, v0
	v_mov_b32_e32 v7, v0
	v_mov_b32_e32 v16, v0
	v_mov_b32_e32 v17, v0
	v_mov_b32_e32 v18, v0
	v_mov_b32_e32 v19, v0
	v_mov_b32_e32 v20, v0
	v_mov_b32_e32 v21, v0
	v_mov_b32_e32 v22, v0
	v_mov_b32_e32 v23, v0
	v_mov_b32_e32 v32, v0
	v_mov_b32_e32 v33, v0
	v_mov_b32_e32 v34, v0
	v_mov_b32_e32 v35, v0
	v_mov_b32_e32 v36, v0
	v_mov_b32_e32 v37, v0
	v_mov_b32_e32 v38, v0
	v_mov_b32_e32 v39, v0
	v_mov_b32_e32 v48, v0
	v_mov_b32_e32 v49, v0
	v_mov_b32_e32 v50, v0
	v_mov_b32_e32 v51, v0
	v_mov_b32_e32 v52, v0
	v_mov_b32_e32 v53, v0
	v_mov_b32_e32 v54, v0
	v_mov_b32_e32 v55, v0
	v_mov_b32_e32 v8, v0
	v_mov_b32_e32 v9, v0
	v_mov_b32_e32 v10, v0
	v_mov_b32_e32 v11, v0
	v_mov_b32_e32 v12, v0
	v_mov_b32_e32 v13, v0
	v_mov_b32_e32 v14, v0
	v_mov_b32_e32 v15, v0
	v_mov_b32_e32 v24, v0
	v_mov_b32_e32 v25, v0
	v_mov_b32_e32 v26, v0
	v_mov_b32_e32 v27, v0
	v_mov_b32_e32 v28, v0
	v_mov_b32_e32 v29, v0
	v_mov_b32_e32 v30, v0
	v_mov_b32_e32 v31, v0
	v_mov_b32_e32 v40, v0
	v_mov_b32_e32 v41, v0
	v_mov_b32_e32 v42, v0
	v_mov_b32_e32 v43, v0
	v_mov_b32_e32 v44, v0
	v_mov_b32_e32 v45, v0
	v_mov_b32_e32 v46, v0
	v_mov_b32_e32 v47, v0
	v_mov_b32_e32 v56, v0
	v_mov_b32_e32 v57, v0
	v_mov_b32_e32 v58, v0
	v_mov_b32_e32 v59, v0
	v_mov_b32_e32 v60, v0
	v_mov_b32_e32 v61, v0
	v_mov_b32_e32 v62, v0
	v_mov_b32_e32 v63, v0
	v_mov_b32_e32 v64, v0
	v_mov_b32_e32 v65, v0
	v_mov_b32_e32 v66, v0
	v_mov_b32_e32 v67, v0
	v_mov_b32_e32 v68, v0
	v_mov_b32_e32 v69, v0
	v_mov_b32_e32 v70, v0
	v_mov_b32_e32 v71, v0
	v_mov_b32_e32 v80, v0
	v_mov_b32_e32 v81, v0
	v_mov_b32_e32 v82, v0
	v_mov_b32_e32 v83, v0
	v_mov_b32_e32 v84, v0
	v_mov_b32_e32 v85, v0
	v_mov_b32_e32 v86, v0
	v_mov_b32_e32 v87, v0
	v_mov_b32_e32 v96, v0
	v_mov_b32_e32 v97, v0
	v_mov_b32_e32 v98, v0
	v_mov_b32_e32 v99, v0
	v_mov_b32_e32 v100, v0
	v_mov_b32_e32 v101, v0
	v_mov_b32_e32 v102, v0
	v_mov_b32_e32 v103, v0
	v_mov_b32_e32 v112, v0
	v_mov_b32_e32 v113, v0
	v_mov_b32_e32 v114, v0
	v_mov_b32_e32 v115, v0
	v_mov_b32_e32 v116, v0
	v_mov_b32_e32 v117, v0
	v_mov_b32_e32 v118, v0
	v_mov_b32_e32 v119, v0
	v_mov_b32_e32 v72, v0
	v_mov_b32_e32 v73, v0
	v_mov_b32_e32 v74, v0
	v_mov_b32_e32 v75, v0
	v_mov_b32_e32 v76, v0
	v_mov_b32_e32 v77, v0
	v_mov_b32_e32 v78, v0
	v_mov_b32_e32 v79, v0
	v_mov_b32_e32 v88, v0
	v_mov_b32_e32 v89, v0
	v_mov_b32_e32 v90, v0
	v_mov_b32_e32 v91, v0
	v_mov_b32_e32 v92, v0
	v_mov_b32_e32 v93, v0
	v_mov_b32_e32 v94, v0
	v_mov_b32_e32 v95, v0
	v_mov_b32_e32 v104, v0
	v_mov_b32_e32 v105, v0
	v_mov_b32_e32 v106, v0
	v_mov_b32_e32 v107, v0
	v_mov_b32_e32 v108, v0
	v_mov_b32_e32 v109, v0
	v_mov_b32_e32 v110, v0
	v_mov_b32_e32 v111, v0
	v_mov_b32_e32 v120, v0
	v_mov_b32_e32 v121, v0
	v_mov_b32_e32 v122, v0
	v_mov_b32_e32 v123, v0
	v_mov_b32_e32 v124, v0
	v_mov_b32_e32 v125, v0
	v_mov_b32_e32 v126, v0
	v_mov_b32_e32 v127, v0
	v_readfirstlane_b32 s98, v254
	s_nop 3
	s_lshr_b32 s98, s98, 8
	s_cmp_eq_u32 s98, 1
	s_cbranch_scc0 .Lsp_0
	s_setprio 1
.Lsp_0:
.LBB0_188:
	ds_read_b128 v[128:131], v197
	ds_read_b128 v[132:135], v197 offset:1024
	ds_read_b128 v[136:139], v197 offset:2048
	ds_read_b128 v[140:143], v197 offset:3072
	ds_read_b128 v[188:191], v198
	ds_read_b128 v[200:203], v198 offset:1024
	ds_read_b128 v[204:207], v198 offset:2048
	ds_read_b128 v[208:211], v198 offset:3072
	s_add_u32 s2, s0, 0xfffc0080
	s_addc_u32 s3, s1, -1
	s_cmp_eq_u32 s41, 12
	s_cselect_b32 s5, s8, s3
	s_cselect_b32 s4, s9, s2
	s_cselect_b32 s3, s29, s40
	s_cselect_b32 s2, s31, s33
	v_lshl_add_u64 v[244:245], s[0:1], 0, v[184:185]
	s_add_i32 m0, s17, 0xc000
	ds_read_b128 v[212:215], v196
	ds_read_b128 v[216:219], v196 offset:1024
	ds_read_b128 v[220:223], v196 offset:2048
	ds_read_b128 v[224:227], v196 offset:3072
	ds_read_b128 v[228:231], v196 offset:4096
	ds_read_b128 v[232:235], v196 offset:5120
	ds_read_b128 v[236:239], v196 offset:6144
	ds_read_b128 v[240:243], v196 offset:7168
	global_load_lds_dwordx4 v[244:245], off
	v_lshl_add_u64 v[244:245], s[0:1], 0, v[186:187]
	s_add_i32 m0, s17, 0xe000
	s_nop 0
	global_load_lds_dwordx4 v[244:245], off
	s_waitcnt vmcnt(8)
	s_waitcnt lgkmcnt(0)
	s_barrier
; #define PG8_STAGE(bufoff, gbase, voff) do { _Pragma("unroll") for (int _i = 0; _i < 2; ++_i) \
;         __builtin_amdgcn_global_load_lds((const unsigned*)((const char*)(gbase) + (voff)[_i]), (PG8_LAS unsigned*)(lds + (bufoff) + ldsw + _i * 8192), 16, 0, 0); } while (0)
; #define PG8_LDA(dst, b, h) do { _Pragma("unroll") for (int m = 0; m < 4; ++m) _Pragma("unroll") for (int k = 0; k < 2; ++k) dst[m][k] = *(const PG8_LAS bf16x8*)(lds + PG8_SA(b, h) + aoff + m * 2048 + k * 1024); } while (0)
; #define PG8_MMA(ai, bj, At, Bt) do { __builtin_amdgcn_s_setprio(1); _Pragma("unroll") for (int m = 0; m < 4; ++m) _Pragma("unroll") for (int n = 0; n < 2; ++n) _Pragma("unroll") for (int k = 0; k < 2; ++k) \
;         acc[ai][bj][m][n] = __builtin_amdgcn_mfma_f32_16x16x32_bf16(Bt[n][k], At[m][k], acc[ai][bj][m][n], 0, 0, 0); __builtin_amdgcn_s_setprio(0); } while (0)
; #define PG8_WAIT_V(n) asm volatile("s_waitcnt vmcnt(" #n ")" ::: "memory")
; #define PG8_WAIT_L(n) asm volatile("s_waitcnt lgkmcnt(" #n ")" ::: "memory")
; #define PG8_BAR __builtin_amdgcn_s_barrier()
; #define PG8_SCHED __builtin_amdgcn_sched_barrier(0)
; template <class Epi, class Sched, bool ALIGN_EPI = false, bool SP2 = false>
; __device__ __forceinline__ void gemm_phase(PG8_LAS unsigned char* lds, const Gemm g, const Sched& S, const Epi& E) {
;     ...
;             PG8_WAIT_V(8); PG8_WAIT_L(0); PG8_BAR; PG8_MMA(0, 0, At, B0); PG8_MMA(0, 1, At, B1); PG8_BAR; PG8_SCHED;
;             PG8_LDA(At, 0, 1); PG8_STAGE(PG8_SB(0, 0), b2, voffB); PG8_STAGE(PG8_SB(0, 1), b2 + hstep, voffB); PG8_STAGE(PG8_SA(0, 0), a2, voffA);
;             PG8_WAIT_V(8); PG8_WAIT_L(0); PG8_BAR; PG8_MMA(1, 0, At, B0); PG8_MMA(1, 1, At, B1); PG8_BAR; PG8_SCHED;
	s_waitcnt lgkmcnt(0)
	v_mfma_f32_16x16x32_bf16 v[124:127], v[128:131], v[212:215], v[124:127]
	v_mfma_f32_16x16x32_bf16 v[120:123], v[136:139], v[212:215], v[120:123]
	v_mfma_f32_16x16x32_bf16 v[108:111], v[128:131], v[220:223], v[108:111]
	v_mfma_f32_16x16x32_bf16 v[104:107], v[136:139], v[220:223], v[104:107]
	v_mfma_f32_16x16x32_bf16 v[92:95], v[128:131], v[228:231], v[92:95]
	v_mfma_f32_16x16x32_bf16 v[88:91], v[136:139], v[228:231], v[88:91]
	v_mfma_f32_16x16x32_bf16 v[76:79], v[128:131], v[236:239], v[76:79]
	v_mfma_f32_16x16x32_bf16 v[72:75], v[136:139], v[236:239], v[72:75]
	v_mfma_f32_16x16x32_bf16 v[124:127], v[132:135], v[216:219], v[124:127]
	v_mfma_f32_16x16x32_bf16 v[120:123], v[140:143], v[216:219], v[120:123]
	v_mfma_f32_16x16x32_bf16 v[108:111], v[132:135], v[224:227], v[108:111]
	v_mfma_f32_16x16x32_bf16 v[104:107], v[140:143], v[224:227], v[104:107]
	v_mfma_f32_16x16x32_bf16 v[92:95], v[132:135], v[232:235], v[92:95]
	v_mfma_f32_16x16x32_bf16 v[88:91], v[140:143], v[232:235], v[88:91]
	v_mfma_f32_16x16x32_bf16 v[76:79], v[132:135], v[240:243], v[76:79]
	v_mfma_f32_16x16x32_bf16 v[72:75], v[140:143], v[240:243], v[72:75]
	v_mfma_f32_16x16x32_bf16 v[116:119], v[188:191], v[212:215], v[116:119]
	v_mfma_f32_16x16x32_bf16 v[112:115], v[204:207], v[212:215], v[112:115]
	v_mfma_f32_16x16x32_bf16 v[100:103], v[188:191], v[220:223], v[100:103]
	v_mfma_f32_16x16x32_bf16 v[96:99], v[204:207], v[220:223], v[96:99]
	v_mfma_f32_16x16x32_bf16 v[84:87], v[188:191], v[228:231], v[84:87]
	v_mfma_f32_16x16x32_bf16 v[80:83], v[204:207], v[228:231], v[80:83]
	v_mfma_f32_16x16x32_bf16 v[68:71], v[188:191], v[236:239], v[68:71]
	v_mfma_f32_16x16x32_bf16 v[64:67], v[204:207], v[236:239], v[64:67]
	v_mfma_f32_16x16x32_bf16 v[116:119], v[200:203], v[216:219], v[116:119]
	v_mfma_f32_16x16x32_bf16 v[112:115], v[208:211], v[216:219], v[112:115]
	v_mfma_f32_16x16x32_bf16 v[100:103], v[200:203], v[224:227], v[100:103]
	v_mfma_f32_16x16x32_bf16 v[96:99], v[208:211], v[224:227], v[96:99]
	v_mfma_f32_16x16x32_bf16 v[84:87], v[200:203], v[232:235], v[84:87]
	v_mfma_f32_16x16x32_bf16 v[80:83], v[208:211], v[232:235], v[80:83]
	v_mfma_f32_16x16x32_bf16 v[68:71], v[200:203], v[240:243], v[68:71]
	v_mfma_f32_16x16x32_bf16 v[64:67], v[208:211], v[240:243], v[64:67]
	s_barrier
	s_add_i32 s54, s51, s34
	v_lshl_add_u64 v[244:245], s[2:3], 0, v[146:147]
	s_mov_b32 m0, s54
	ds_read_b128 v[212:215], v196 offset:16384
	ds_read_b128 v[216:219], v196 offset:17408
	ds_read_b128 v[220:223], v196 offset:18432
	ds_read_b128 v[224:227], v196 offset:19456
	ds_read_b128 v[228:231], v196 offset:20480
	ds_read_b128 v[232:235], v196 offset:21504
	ds_read_b128 v[236:239], v196 offset:22528
	ds_read_b128 v[240:243], v196 offset:23552
	global_load_lds_dwordx4 v[244:245], off
	s_add_i32 m0, s54, 0x2000
	s_add_u32 s54, s2, 0x40000
	v_lshl_add_u64 v[246:247], s[2:3], 0, v[150:151]
	s_addc_u32 s55, s3, 0
	s_add_i32 s56, s52, s34
	global_load_lds_dwordx4 v[246:247], off
	v_lshl_add_u64 v[248:249], s[54:55], 0, v[146:147]
	s_mov_b32 m0, s56
	v_lshl_add_u64 v[250:251], s[4:5], 0, v[148:149]
	global_load_lds_dwordx4 v[248:249], off
	v_lshl_add_u64 v[248:249], s[54:55], 0, v[150:151]
	s_add_i32 m0, s56, 0x2000
	s_nop 0
	global_load_lds_dwordx4 v[248:249], off
	v_lshl_add_u64 v[248:249], s[4:5], 0, v[144:145]
	s_mov_b32 m0, s17
	s_nop 0
	global_load_lds_dwordx4 v[248:249], off
	s_mov_b32 m0, s19
	s_nop 0
	global_load_lds_dwordx4 v[250:251], off
	s_waitcnt vmcnt(8)
	s_waitcnt lgkmcnt(0)
	s_barrier
	s_waitcnt lgkmcnt(0)
	v_mfma_f32_16x16x32_bf16 v[60:63], v[128:131], v[212:215], v[60:63]
	v_mfma_f32_16x16x32_bf16 v[56:59], v[136:139], v[212:215], v[56:59]
	v_mfma_f32_16x16x32_bf16 v[44:47], v[128:131], v[220:223], v[44:47]
	v_mfma_f32_16x16x32_bf16 v[40:43], v[136:139], v[220:223], v[40:43]
	v_mfma_f32_16x16x32_bf16 v[28:31], v[128:131], v[228:231], v[28:31]
	v_mfma_f32_16x16x32_bf16 v[24:27], v[136:139], v[228:231], v[24:27]
	v_mfma_f32_16x16x32_bf16 v[12:15], v[128:131], v[236:239], v[12:15]
	v_mfma_f32_16x16x32_bf16 v[8:11], v[136:139], v[236:239], v[8:11]
	v_mfma_f32_16x16x32_bf16 v[60:63], v[132:135], v[216:219], v[60:63]
	v_mfma_f32_16x16x32_bf16 v[56:59], v[140:143], v[216:219], v[56:59]
	v_mfma_f32_16x16x32_bf16 v[44:47], v[132:135], v[224:227], v[44:47]
	v_mfma_f32_16x16x32_bf16 v[40:43], v[140:143], v[224:227], v[40:43]
	v_mfma_f32_16x16x32_bf16 v[28:31], v[132:135], v[232:235], v[28:31]
	v_mfma_f32_16x16x32_bf16 v[24:27], v[140:143], v[232:235], v[24:27]
	v_mfma_f32_16x16x32_bf16 v[12:15], v[132:135], v[240:243], v[12:15]
	v_mfma_f32_16x16x32_bf16 v[8:11], v[140:143], v[240:243], v[8:11]
	v_mfma_f32_16x16x32_bf16 v[52:55], v[188:191], v[212:215], v[52:55]
	v_mfma_f32_16x16x32_bf16 v[48:51], v[204:207], v[212:215], v[48:51]
	v_mfma_f32_16x16x32_bf16 v[36:39], v[188:191], v[220:223], v[36:39]
	v_mfma_f32_16x16x32_bf16 v[32:35], v[204:207], v[220:223], v[32:35]
	v_mfma_f32_16x16x32_bf16 v[20:23], v[188:191], v[228:231], v[20:23]
	v_mfma_f32_16x16x32_bf16 v[16:19], v[204:207], v[228:231], v[16:19]
	v_mfma_f32_16x16x32_bf16 v[4:7], v[188:191], v[236:239], v[4:7]
	v_mfma_f32_16x16x32_bf16 v[0:3], v[204:207], v[236:239], v[0:3]
	v_mfma_f32_16x16x32_bf16 v[52:55], v[200:203], v[216:219], v[52:55]
	v_mfma_f32_16x16x32_bf16 v[48:51], v[208:211], v[216:219], v[48:51]
	v_mfma_f32_16x16x32_bf16 v[36:39], v[200:203], v[224:227], v[36:39]
	v_mfma_f32_16x16x32_bf16 v[32:35], v[208:211], v[224:227], v[32:35]
	v_mfma_f32_16x16x32_bf16 v[20:23], v[200:203], v[232:235], v[20:23]
	v_mfma_f32_16x16x32_bf16 v[16:19], v[208:211], v[232:235], v[16:19]
	v_mfma_f32_16x16x32_bf16 v[4:7], v[200:203], v[240:243], v[4:7]
	v_mfma_f32_16x16x32_bf16 v[0:3], v[208:211], v[240:243], v[0:3]
	s_barrier
; #define PG8_STAGE(bufoff, gbase, voff) do { _Pragma("unroll") for (int _i = 0; _i < 2; ++_i) \
;         __builtin_amdgcn_global_load_lds((const unsigned*)((const char*)(gbase) + (voff)[_i]), (PG8_LAS unsigned*)(lds + (bufoff) + ldsw + _i * 8192), 16, 0, 0); } while (0)
; #define PG8_LDA(dst, b, h) do { _Pragma("unroll") for (int m = 0; m < 4; ++m) _Pragma("unroll") for (int k = 0; k < 2; ++k) dst[m][k] = *(const PG8_LAS bf16x8*)(lds + PG8_SA(b, h) + aoff + m * 2048 + k * 1024); } while (0)
; #define PG8_LDB(dst, b, h) do { _Pragma("unroll") for (int n = 0; n < 2; ++n) _Pragma("unroll") for (int k = 0; k < 2; ++k) dst[n][k] = *(const PG8_LAS bf16x8*)(lds + PG8_SB(b, h) + boff + n * 2048 + k * 1024); } while (0)
; #define PG8_MMA(ai, bj, At, Bt) do { __builtin_amdgcn_s_setprio(1); _Pragma("unroll") for (int m = 0; m < 4; ++m) _Pragma("unroll") for (int n = 0; n < 2; ++n) _Pragma("unroll") for (int k = 0; k < 2; ++k) \
;         acc[ai][bj][m][n] = __builtin_amdgcn_mfma_f32_16x16x32_bf16(Bt[n][k], At[m][k], acc[ai][bj][m][n], 0, 0, 0); __builtin_amdgcn_s_setprio(0); } while (0)
; #define PG8_WAIT_V(n) asm volatile("s_waitcnt vmcnt(" #n ")" ::: "memory")
; #define PG8_WAIT_L(n) asm volatile("s_waitcnt lgkmcnt(" #n ")" ::: "memory")
; #define PG8_BAR __builtin_amdgcn_s_barrier()
; #define PG8_SCHED __builtin_amdgcn_sched_barrier(0)
; template <class Epi, class Sched, bool ALIGN_EPI = false, bool SP2 = false>
; __device__ __forceinline__ void gemm_phase(PG8_LAS unsigned char* lds, const Gemm g, const Sched& S, const Epi& E) {
;     ...
;             PG8_LDB(B0, 1, 0); PG8_LDB(B1, 1, 1); PG8_SCHED; PG8_LDA(At, 1, 0); PG8_STAGE(PG8_SA(0, 1), a2 + hstep, voffA);
;             PG8_WAIT_V(8); PG8_WAIT_L(0); PG8_BAR; PG8_MMA(0, 0, At, B0); PG8_MMA(0, 1, At, B1); PG8_BAR; PG8_SCHED;
	s_add_i32 s54, 0, 0x18000
	s_add_i32 s55, 0, 0x1c000
	v_add_u32_e32 v140, s54, v194
	v_add_u32_e32 v192, s55, v194
	ds_read_b128 v[128:131], v140
	ds_read_b128 v[132:135], v140 offset:1024
	ds_read_b128 v[136:139], v140 offset:2048
	ds_read_b128 v[140:143], v140 offset:3072
	ds_read_b128 v[188:191], v192
	ds_read_b128 v[200:203], v192 offset:1024
	ds_read_b128 v[204:207], v192 offset:2048
	ds_read_b128 v[208:211], v192 offset:3072
	s_add_u32 s4, s4, 0x40000
	s_addc_u32 s5, s5, 0
	s_mov_b32 m0, s35
	v_lshl_add_u64 v[252:253], s[4:5], 0, v[144:145]
	ds_read_b128 v[212:215], v196 offset:32768
	ds_read_b128 v[216:219], v196 offset:33792
	ds_read_b128 v[220:223], v196 offset:34816
	ds_read_b128 v[224:227], v196 offset:35840
	ds_read_b128 v[228:231], v196 offset:36864
	ds_read_b128 v[232:235], v196 offset:37888
	ds_read_b128 v[236:239], v196 offset:38912
	ds_read_b128 v[240:243], v196 offset:39936
	global_load_lds_dwordx4 v[252:253], off
	v_lshl_add_u64 v[252:253], s[4:5], 0, v[148:149]
	s_mov_b32 m0, s42
	s_nop 0
	global_load_lds_dwordx4 v[252:253], off
	s_waitcnt vmcnt(8)
	s_waitcnt lgkmcnt(0)
	s_barrier
	s_waitcnt lgkmcnt(0)
	v_mfma_f32_16x16x32_bf16 v[124:127], v[128:131], v[212:215], v[124:127]
	v_mfma_f32_16x16x32_bf16 v[120:123], v[136:139], v[212:215], v[120:123]
	v_mfma_f32_16x16x32_bf16 v[108:111], v[128:131], v[220:223], v[108:111]
	v_mfma_f32_16x16x32_bf16 v[104:107], v[136:139], v[220:223], v[104:107]
	v_mfma_f32_16x16x32_bf16 v[92:95], v[128:131], v[228:231], v[92:95]
	v_mfma_f32_16x16x32_bf16 v[88:91], v[136:139], v[228:231], v[88:91]
	v_mfma_f32_16x16x32_bf16 v[76:79], v[128:131], v[236:239], v[76:79]
	v_mfma_f32_16x16x32_bf16 v[72:75], v[136:139], v[236:239], v[72:75]
	v_mfma_f32_16x16x32_bf16 v[124:127], v[132:135], v[216:219], v[124:127]
	v_mfma_f32_16x16x32_bf16 v[120:123], v[140:143], v[216:219], v[120:123]
	v_mfma_f32_16x16x32_bf16 v[108:111], v[132:135], v[224:227], v[108:111]
	v_mfma_f32_16x16x32_bf16 v[104:107], v[140:143], v[224:227], v[104:107]
	v_mfma_f32_16x16x32_bf16 v[92:95], v[132:135], v[232:235], v[92:95]
	v_mfma_f32_16x16x32_bf16 v[88:91], v[140:143], v[232:235], v[88:91]
	v_mfma_f32_16x16x32_bf16 v[76:79], v[132:135], v[240:243], v[76:79]
	v_mfma_f32_16x16x32_bf16 v[72:75], v[140:143], v[240:243], v[72:75]
	v_mfma_f32_16x16x32_bf16 v[116:119], v[188:191], v[212:215], v[116:119]
	v_mfma_f32_16x16x32_bf16 v[112:115], v[204:207], v[212:215], v[112:115]
	v_mfma_f32_16x16x32_bf16 v[100:103], v[188:191], v[220:223], v[100:103]
	v_mfma_f32_16x16x32_bf16 v[96:99], v[204:207], v[220:223], v[96:99]
	v_mfma_f32_16x16x32_bf16 v[84:87], v[188:191], v[228:231], v[84:87]
	v_mfma_f32_16x16x32_bf16 v[80:83], v[204:207], v[228:231], v[80:83]
	v_mfma_f32_16x16x32_bf16 v[68:71], v[188:191], v[236:239], v[68:71]
	v_mfma_f32_16x16x32_bf16 v[64:67], v[204:207], v[236:239], v[64:67]
	v_mfma_f32_16x16x32_bf16 v[116:119], v[200:203], v[216:219], v[116:119]
	v_mfma_f32_16x16x32_bf16 v[112:115], v[208:211], v[216:219], v[112:115]
	v_mfma_f32_16x16x32_bf16 v[100:103], v[200:203], v[224:227], v[100:103]
	v_mfma_f32_16x16x32_bf16 v[96:99], v[208:211], v[224:227], v[96:99]
	v_mfma_f32_16x16x32_bf16 v[84:87], v[200:203], v[232:235], v[84:87]
	v_mfma_f32_16x16x32_bf16 v[80:83], v[208:211], v[232:235], v[80:83]
	v_mfma_f32_16x16x32_bf16 v[68:71], v[200:203], v[240:243], v[68:71]
	v_mfma_f32_16x16x32_bf16 v[64:67], v[208:211], v[240:243], v[64:67]
	s_barrier
; #define PG8_STAGE(bufoff, gbase, voff) do { _Pragma("unroll") for (int _i = 0; _i < 2; ++_i) \
;         __builtin_amdgcn_global_load_lds((const unsigned*)((const char*)(gbase) + (voff)[_i]), (PG8_LAS unsigned*)(lds + (bufoff) + ldsw + _i * 8192), 16, 0, 0); } while (0)
; #define PG8_LDA(dst, b, h) do { _Pragma("unroll") for (int m = 0; m < 4; ++m) _Pragma("unroll") for (int k = 0; k < 2; ++k) dst[m][k] = *(const PG8_LAS bf16x8*)(lds + PG8_SA(b, h) + aoff + m * 2048 + k * 1024); } while (0)
; #define PG8_MMA(ai, bj, At, Bt) do { __builtin_amdgcn_s_setprio(1); _Pragma("unroll") for (int m = 0; m < 4; ++m) _Pragma("unroll") for (int n = 0; n < 2; ++n) _Pragma("unroll") for (int k = 0; k < 2; ++k) \
;         acc[ai][bj][m][n] = __builtin_amdgcn_mfma_f32_16x16x32_bf16(Bt[n][k], At[m][k], acc[ai][bj][m][n], 0, 0, 0); __builtin_amdgcn_s_setprio(0); } while (0)
; #define PG8_WAIT_V(n) asm volatile("s_waitcnt vmcnt(" #n ")" ::: "memory")
; #define PG8_WAIT_L(n) asm volatile("s_waitcnt lgkmcnt(" #n ")" ::: "memory")
; #define PG8_BAR __builtin_amdgcn_s_barrier()
; #define PG8_SCHED __builtin_amdgcn_sched_barrier(0)
; template <class Epi, class Sched, bool ALIGN_EPI = false, bool SP2 = false>
; __device__ __forceinline__ void gemm_phase(PG8_LAS unsigned char* lds, const Gemm g, const Sched& S, const Epi& E) {
;     ...
;         for (int t = 0; t < nt; t += 2) {
;     ...
;             PG8_LDA(At, 1, 1); PG8_STAGE(PG8_SB(1, 0), b3, voffB); PG8_STAGE(PG8_SB(1, 1), b3 + hstep, voffB); PG8_STAGE(PG8_SA(1, 0), a3, voffA);
;             PG8_WAIT_V(8); PG8_WAIT_L(0); PG8_BAR; PG8_MMA(1, 0, At, B0); PG8_MMA(1, 1, At, B1); PG8_BAR; PG8_SCHED;
	s_add_i32 s4, s54, s34
	v_lshl_add_u64 v[244:245], v[244:245], 0, s[14:15]
	s_mov_b32 m0, s4
	ds_read_b128 v[212:215], v196 offset:49152
	ds_read_b128 v[216:219], v196 offset:50176
	ds_read_b128 v[220:223], v196 offset:51200
	ds_read_b128 v[224:227], v196 offset:52224
	ds_read_b128 v[228:231], v196 offset:53248
	ds_read_b128 v[232:235], v196 offset:54272
	ds_read_b128 v[236:239], v196 offset:55296
	ds_read_b128 v[240:243], v196 offset:56320
	global_load_lds_dwordx4 v[244:245], off
	s_add_i32 m0, s4, 0x2000
	s_add_u32 s2, s2, 0x40080
	v_lshl_add_u64 v[244:245], v[246:247], 0, s[14:15]
	s_addc_u32 s3, s3, 0
	s_add_i32 s4, s55, s34
	global_load_lds_dwordx4 v[244:245], off
	v_lshl_add_u64 v[244:245], s[2:3], 0, v[146:147]
	s_mov_b32 m0, s4
	s_nop 0
	global_load_lds_dwordx4 v[244:245], off
	v_lshl_add_u64 v[244:245], s[2:3], 0, v[150:151]
	s_add_i32 m0, s4, 0x2000
	s_nop 0
	global_load_lds_dwordx4 v[244:245], off
	v_lshl_add_u64 v[244:245], v[248:249], 0, s[14:15]
	s_mov_b32 m0, s48
	s_nop 0
	global_load_lds_dwordx4 v[244:245], off
	v_lshl_add_u64 v[244:245], v[250:251], 0, s[14:15]
	s_mov_b32 m0, s49
	s_nop 0
	global_load_lds_dwordx4 v[244:245], off
	s_waitcnt vmcnt(8)
	s_waitcnt lgkmcnt(0)
	s_barrier
	s_waitcnt lgkmcnt(0)
	v_mfma_f32_16x16x32_bf16 v[60:63], v[128:131], v[212:215], v[60:63]
	v_mfma_f32_16x16x32_bf16 v[56:59], v[136:139], v[212:215], v[56:59]
	v_mfma_f32_16x16x32_bf16 v[44:47], v[128:131], v[220:223], v[44:47]
	v_mfma_f32_16x16x32_bf16 v[40:43], v[136:139], v[220:223], v[40:43]
	v_mfma_f32_16x16x32_bf16 v[28:31], v[128:131], v[228:231], v[28:31]
	v_mfma_f32_16x16x32_bf16 v[24:27], v[136:139], v[228:231], v[24:27]
	v_mfma_f32_16x16x32_bf16 v[12:15], v[128:131], v[236:239], v[12:15]
	v_mfma_f32_16x16x32_bf16 v[8:11], v[136:139], v[236:239], v[8:11]
	v_mfma_f32_16x16x32_bf16 v[60:63], v[132:135], v[216:219], v[60:63]
	v_mfma_f32_16x16x32_bf16 v[56:59], v[140:143], v[216:219], v[56:59]
	v_mfma_f32_16x16x32_bf16 v[44:47], v[132:135], v[224:227], v[44:47]
	v_mfma_f32_16x16x32_bf16 v[40:43], v[140:143], v[224:227], v[40:43]
	v_mfma_f32_16x16x32_bf16 v[28:31], v[132:135], v[232:235], v[28:31]
	v_mfma_f32_16x16x32_bf16 v[24:27], v[140:143], v[232:235], v[24:27]
	v_mfma_f32_16x16x32_bf16 v[12:15], v[132:135], v[240:243], v[12:15]
	v_mfma_f32_16x16x32_bf16 v[8:11], v[140:143], v[240:243], v[8:11]
	v_mfma_f32_16x16x32_bf16 v[52:55], v[188:191], v[212:215], v[52:55]
	v_mfma_f32_16x16x32_bf16 v[48:51], v[204:207], v[212:215], v[48:51]
	v_mfma_f32_16x16x32_bf16 v[36:39], v[188:191], v[220:223], v[36:39]
	v_mfma_f32_16x16x32_bf16 v[32:35], v[204:207], v[220:223], v[32:35]
	v_mfma_f32_16x16x32_bf16 v[20:23], v[188:191], v[228:231], v[20:23]
	v_mfma_f32_16x16x32_bf16 v[16:19], v[204:207], v[228:231], v[16:19]
	v_mfma_f32_16x16x32_bf16 v[4:7], v[188:191], v[236:239], v[4:7]
	v_mfma_f32_16x16x32_bf16 v[0:3], v[204:207], v[236:239], v[0:3]
	v_mfma_f32_16x16x32_bf16 v[52:55], v[200:203], v[216:219], v[52:55]
	v_mfma_f32_16x16x32_bf16 v[48:51], v[208:211], v[216:219], v[48:51]
	v_mfma_f32_16x16x32_bf16 v[36:39], v[200:203], v[224:227], v[36:39]
	v_mfma_f32_16x16x32_bf16 v[32:35], v[208:211], v[224:227], v[32:35]
	v_mfma_f32_16x16x32_bf16 v[20:23], v[200:203], v[232:235], v[20:23]
	v_mfma_f32_16x16x32_bf16 v[16:19], v[208:211], v[232:235], v[16:19]
	v_mfma_f32_16x16x32_bf16 v[4:7], v[200:203], v[240:243], v[4:7]
	v_mfma_f32_16x16x32_bf16 v[0:3], v[208:211], v[240:243], v[0:3]
	s_barrier
	s_add_i32 s41, s41, 2
	s_add_u32 s0, s0, 0x100
	s_addc_u32 s1, s1, 0
	s_add_u32 s33, s33, 0x100
	s_addc_u32 s40, s40, 0
	s_cmp_gt_u32 s41, 13
	s_cbranch_scc0 .LBB0_188
	s_setprio 0
	s_and_b64 vcc, exec, s[26:27]
	s_cbranch_vccz .LBB0_191
	s_barrier

; template <class Epi, class Sched, bool ALIGN_EPI = false, bool SP2 = false>
; __device__ __forceinline__ void gemm_phase(PG8_LAS unsigned char* lds, const Gemm g, const Sched& S, const Epi& E) {
;     ...
;         const bool has_next = S.next(ui + 1, nxt);
;         const char* nA = has_next ? (const char*)g.A + (size_t)nxt.pm * tstep : cA; const char* nB = has_next ? (const char*)g.Bt + (size_t)nxt.pn * tstep : cB;
;     ...
; #pragma unroll
;         for (int a = 0; a < 2; ++a)
; #pragma unroll
;             for (int b = 0; b < 2; ++b)
; #pragma unroll
;                 for (int m = 0; m < 4; ++m)
; #pragma unroll
;                     for (int n = 0; n < 2; ++n) acc[a][b][m][n] = (f32x4){0.f, 0.f, 0.f, 0.f};
;         cur = nxt; cA = nA; cB = nB; ++ui;
.LBB0_477:
	s_ashr_i32 s31, s30, 31
	s_lshl_b64 s[4:5], s[30:31], 19
	s_add_u32 s36, s20, s4
	s_addc_u32 s37, s21, s5
	s_and_b64 s[4:5], s[6:7], exec
	s_cselect_b32 s8, s37, s1
	s_cselect_b32 s9, s36, s0
	s_ashr_i32 s29, s28, 31
	s_lshl_b64 s[4:5], s[28:29], 19
	s_add_u32 s38, s22, s4
	s_addc_u32 s39, s23, s5
	s_and_b64 s[4:5], s[6:7], exec
	s_cselect_b32 s29, s39, s3
	s_cselect_b32 s31, s38, s2
	s_add_u32 s0, s0, 0x40080
	s_addc_u32 s1, s1, 0
	s_add_u32 s33, s2, 0x100
	v_mov_b32_e32 v0, 0
	s_addc_u32 s40, s3, 0
	s_mov_b32 s41, -2
	v_mov_b32_e32 v1, v0
	v_mov_b32_e32 v2, v0
	v_mov_b32_e32 v3, v0
	v_mov_b32_e32 v4, v0
	v_mov_b32_e32 v5, v0
	v_mov_b32_e32 v6, v0
	v_mov_b32_e32 v7, v0
	v_mov_b32_e32 v16, v0
	v_mov_b32_e32 v17, v0
	v_mov_b32_e32 v18, v0
	v_mov_b32_e32 v19, v0
	v_mov_b32_e32 v20, v0
	v_mov_b32_e32 v21, v0
	v_mov_b32_e32 v22, v0
	v_mov_b32_e32 v23, v0
	v_mov_b32_e32 v32, v0
	v_mov_b32_e32 v33, v0
	v_mov_b32_e32 v34, v0
	v_mov_b32_e32 v35, v0
	v_mov_b32_e32 v36, v0
	v_mov_b32_e32 v37, v0
	v_mov_b32_e32 v38, v0
	v_mov_b32_e32 v39, v0
	v_mov_b32_e32 v48, v0
	v_mov_b32_e32 v49, v0
	v_mov_b32_e32 v50, v0
	v_mov_b32_e32 v51, v0
	v_mov_b32_e32 v52, v0
	v_mov_b32_e32 v53, v0
	v_mov_b32_e32 v54, v0
	v_mov_b32_e32 v55, v0
	v_mov_b32_e32 v8, v0
	v_mov_b32_e32 v9, v0
	v_mov_b32_e32 v10, v0
	v_mov_b32_e32 v11, v0
	v_mov_b32_e32 v12, v0
	v_mov_b32_e32 v13, v0
	v_mov_b32_e32 v14, v0
	v_mov_b32_e32 v15, v0
	v_mov_b32_e32 v24, v0
	v_mov_b32_e32 v25, v0
	v_mov_b32_e32 v26, v0
	v_mov_b32_e32 v27, v0
	v_mov_b32_e32 v28, v0
	v_mov_b32_e32 v29, v0
	v_mov_b32_e32 v30, v0
	v_mov_b32_e32 v31, v0
	v_mov_b32_e32 v40, v0
	v_mov_b32_e32 v41, v0
	v_mov_b32_e32 v42, v0
	v_mov_b32_e32 v43, v0
	v_mov_b32_e32 v44, v0
	v_mov_b32_e32 v45, v0
	v_mov_b32_e32 v46, v0
	v_mov_b32_e32 v47, v0
	v_mov_b32_e32 v56, v0
	v_mov_b32_e32 v57, v0
	v_mov_b32_e32 v58, v0
	v_mov_b32_e32 v59, v0
	v_mov_b32_e32 v60, v0
	v_mov_b32_e32 v61, v0
	v_mov_b32_e32 v62, v0
	v_mov_b32_e32 v63, v0
	v_mov_b32_e32 v64, v0
	v_mov_b32_e32 v65, v0
	v_mov_b32_e32 v66, v0
	v_mov_b32_e32 v67, v0
	v_mov_b32_e32 v68, v0
	v_mov_b32_e32 v69, v0
	v_mov_b32_e32 v70, v0
	v_mov_b32_e32 v71, v0
	v_mov_b32_e32 v80, v0
	v_mov_b32_e32 v81, v0
	v_mov_b32_e32 v82, v0
	v_mov_b32_e32 v83, v0
	v_mov_b32_e32 v84, v0
	v_mov_b32_e32 v85, v0
	v_mov_b32_e32 v86, v0
	v_mov_b32_e32 v87, v0
	v_mov_b32_e32 v96, v0
	v_mov_b32_e32 v97, v0
	v_mov_b32_e32 v98, v0
	v_mov_b32_e32 v99, v0
	v_mov_b32_e32 v100, v0
	v_mov_b32_e32 v101, v0
	v_mov_b32_e32 v102, v0
	v_mov_b32_e32 v103, v0
	v_mov_b32_e32 v112, v0
	v_mov_b32_e32 v113, v0
	v_mov_b32_e32 v114, v0
	v_mov_b32_e32 v115, v0
	v_mov_b32_e32 v116, v0
	v_mov_b32_e32 v117, v0
	v_mov_b32_e32 v118, v0
	v_mov_b32_e32 v119, v0
	v_mov_b32_e32 v72, v0
	v_mov_b32_e32 v73, v0
	v_mov_b32_e32 v74, v0
	v_mov_b32_e32 v75, v0
	v_mov_b32_e32 v76, v0
	v_mov_b32_e32 v77, v0
	v_mov_b32_e32 v78, v0
	v_mov_b32_e32 v79, v0
	v_mov_b32_e32 v88, v0
	v_mov_b32_e32 v89, v0
	v_mov_b32_e32 v90, v0
	v_mov_b32_e32 v91, v0
	v_mov_b32_e32 v92, v0
	v_mov_b32_e32 v93, v0
	v_mov_b32_e32 v94, v0
	v_mov_b32_e32 v95, v0
	v_mov_b32_e32 v104, v0
	v_mov_b32_e32 v105, v0
	v_mov_b32_e32 v106, v0
	v_mov_b32_e32 v107, v0
	v_mov_b32_e32 v108, v0
	v_mov_b32_e32 v109, v0
	v_mov_b32_e32 v110, v0
	v_mov_b32_e32 v111, v0
	v_mov_b32_e32 v120, v0
	v_mov_b32_e32 v121, v0
	v_mov_b32_e32 v122, v0
	v_mov_b32_e32 v123, v0
	v_mov_b32_e32 v124, v0
	v_mov_b32_e32 v125, v0
	v_mov_b32_e32 v126, v0
	v_mov_b32_e32 v127, v0
	v_readfirstlane_b32 s98, v254
	s_nop 3
	s_lshr_b32 s98, s98, 8
	s_cmp_eq_u32 s98, 1
	s_cbranch_scc0 .Lsp_1
	s_setprio 1

; #define PG8_STAGE(bufoff, gbase, voff) do { _Pragma("unroll") for (int _i = 0; _i < 2; ++_i) \
;         __builtin_amdgcn_global_load_lds((const unsigned*)((const char*)(gbase) + (voff)[_i]), (PG8_LAS unsigned*)(lds + (bufoff) + ldsw + _i * 8192), 16, 0, 0); } while (0)
; #define PG8_LDA(dst, b, h) do { _Pragma("unroll") for (int m = 0; m < 4; ++m) _Pragma("unroll") for (int k = 0; k < 2; ++k) dst[m][k] = *(const PG8_LAS bf16x8*)(lds + PG8_SA(b, h) + aoff + m * 2048 + k * 1024); } while (0)
; #define PG8_LDB(dst, b, h) do { _Pragma("unroll") for (int n = 0; n < 2; ++n) _Pragma("unroll") for (int k = 0; k < 2; ++k) dst[n][k] = *(const PG8_LAS bf16x8*)(lds + PG8_SB(b, h) + boff + n * 2048 + k * 1024); } while (0)
; #define PG8_MMA(ai, bj, At, Bt) do { __builtin_amdgcn_s_setprio(1); _Pragma("unroll") for (int m = 0; m < 4; ++m) _Pragma("unroll") for (int n = 0; n < 2; ++n) _Pragma("unroll") for (int k = 0; k < 2; ++k) \
;         acc[ai][bj][m][n] = __builtin_amdgcn_mfma_f32_16x16x32_bf16(Bt[n][k], At[m][k], acc[ai][bj][m][n], 0, 0, 0); __builtin_amdgcn_s_setprio(0); } while (0)
; #define PG8_WAIT_V(n) asm volatile("s_waitcnt vmcnt(" #n ")" ::: "memory")
; #define PG8_WAIT_L(n) asm volatile("s_waitcnt lgkmcnt(" #n ")" ::: "memory")
; #define PG8_BAR __builtin_amdgcn_s_barrier()
; #define PG8_SCHED __builtin_amdgcn_sched_barrier(0)
; template <class Epi, class Sched, bool ALIGN_EPI = false, bool SP2 = false>
; __device__ __forceinline__ void gemm_phase(PG8_LAS unsigned char* lds, const Gemm g, const Sched& S, const Epi& E) {
;     ...
;         const bool has_next = S.next(ui + 1, nxt);
;         const char* nA = has_next ? (const char*)g.A + (size_t)nxt.pm * tstep : cA; const char* nB = has_next ? (const char*)g.Bt + (size_t)nxt.pn * tstep : cB;
;     ...
;             PG8_LDB(B0, 0, 0); PG8_LDB(B1, 0, 1); PG8_SCHED; PG8_LDA(At, 0, 0); PG8_STAGE(PG8_SA(1, 1), a1 + hstep, voffA);
;             PG8_WAIT_V(8); PG8_WAIT_L(0); PG8_BAR; PG8_MMA(0, 0, At, B0); PG8_MMA(0, 1, At, B1); PG8_BAR; PG8_SCHED;
;     ...
; #pragma unroll
;         for (int a = 0; a < 2; ++a)
; #pragma unroll
;             for (int b = 0; b < 2; ++b)
; #pragma unroll
;                 for (int m = 0; m < 4; ++m)
; #pragma unroll
;                     for (int n = 0; n < 2; ++n) acc[a][b][m][n] = (f32x4){0.f, 0.f, 0.f, 0.f};
;         cur = nxt; cA = nA; cB = nB; ++ui;
.LBB0_1020:
	s_add_u32 s52, s34, 0x30080
	s_addc_u32 s53, s35, 0
	s_add_u32 vcc_lo, s2, 0x100
	v_mov_b32_e32 v0, 0
	s_addc_u32 vcc_hi, s3, 0
	s_mov_b32 s57, -2
	v_mov_b32_e32 v1, v0
	v_mov_b32_e32 v2, v0
	v_mov_b32_e32 v3, v0
	v_mov_b32_e32 v4, v0
	v_mov_b32_e32 v5, v0
	v_mov_b32_e32 v6, v0
	v_mov_b32_e32 v7, v0
	v_mov_b32_e32 v12, v0
	v_mov_b32_e32 v13, v0
	v_mov_b32_e32 v14, v0
	v_mov_b32_e32 v15, v0
	v_mov_b32_e32 v20, v0
	v_mov_b32_e32 v21, v0
	v_mov_b32_e32 v22, v0
	v_mov_b32_e32 v23, v0
	v_mov_b32_e32 v28, v0
	v_mov_b32_e32 v29, v0
	v_mov_b32_e32 v30, v0
	v_mov_b32_e32 v31, v0
	v_mov_b32_e32 v36, v0
	v_mov_b32_e32 v37, v0
	v_mov_b32_e32 v38, v0
	v_mov_b32_e32 v39, v0
	v_mov_b32_e32 v44, v0
	v_mov_b32_e32 v45, v0
	v_mov_b32_e32 v46, v0
	v_mov_b32_e32 v47, v0
	v_mov_b32_e32 v52, v0
	v_mov_b32_e32 v53, v0
	v_mov_b32_e32 v54, v0
	v_mov_b32_e32 v55, v0
	v_mov_b32_e32 v8, v0
	v_mov_b32_e32 v9, v0
	v_mov_b32_e32 v10, v0
	v_mov_b32_e32 v11, v0
	v_mov_b32_e32 v16, v0
	v_mov_b32_e32 v17, v0
	v_mov_b32_e32 v18, v0
	v_mov_b32_e32 v19, v0
	v_mov_b32_e32 v24, v0
	v_mov_b32_e32 v25, v0
	v_mov_b32_e32 v26, v0
	v_mov_b32_e32 v27, v0
	v_mov_b32_e32 v32, v0
	v_mov_b32_e32 v33, v0
	v_mov_b32_e32 v34, v0
	v_mov_b32_e32 v35, v0
	v_mov_b32_e32 v40, v0
	v_mov_b32_e32 v41, v0
	v_mov_b32_e32 v42, v0
	v_mov_b32_e32 v43, v0
	v_mov_b32_e32 v48, v0
	v_mov_b32_e32 v49, v0
	v_mov_b32_e32 v50, v0
	v_mov_b32_e32 v51, v0
	v_mov_b32_e32 v56, v0
	v_mov_b32_e32 v57, v0
	v_mov_b32_e32 v58, v0
	v_mov_b32_e32 v59, v0
	v_mov_b32_e32 v60, v0
	v_mov_b32_e32 v61, v0
	v_mov_b32_e32 v62, v0
	v_mov_b32_e32 v63, v0
	v_mov_b32_e32 v64, v0
	v_mov_b32_e32 v65, v0
	v_mov_b32_e32 v66, v0
	v_mov_b32_e32 v67, v0
	v_mov_b32_e32 v68, v0
	v_mov_b32_e32 v69, v0
	v_mov_b32_e32 v70, v0
	v_mov_b32_e32 v71, v0
	v_mov_b32_e32 v76, v0
	v_mov_b32_e32 v77, v0
	v_mov_b32_e32 v78, v0
	v_mov_b32_e32 v79, v0
	v_mov_b32_e32 v84, v0
	v_mov_b32_e32 v85, v0
	v_mov_b32_e32 v86, v0
	v_mov_b32_e32 v87, v0
	v_mov_b32_e32 v92, v0
	v_mov_b32_e32 v93, v0
	v_mov_b32_e32 v94, v0
	v_mov_b32_e32 v95, v0
	v_mov_b32_e32 v100, v0
	v_mov_b32_e32 v101, v0
	v_mov_b32_e32 v102, v0
	v_mov_b32_e32 v103, v0
	v_mov_b32_e32 v104, v0
	v_mov_b32_e32 v105, v0
	v_mov_b32_e32 v106, v0
	v_mov_b32_e32 v107, v0
	v_mov_b32_e32 v108, v0
	v_mov_b32_e32 v109, v0
	v_mov_b32_e32 v110, v0
	v_mov_b32_e32 v111, v0
	v_mov_b32_e32 v72, v0
	v_mov_b32_e32 v73, v0
	v_mov_b32_e32 v74, v0
	v_mov_b32_e32 v75, v0
	v_mov_b32_e32 v80, v0
	v_mov_b32_e32 v81, v0
	v_mov_b32_e32 v82, v0
	v_mov_b32_e32 v83, v0
	v_mov_b32_e32 v88, v0
	v_mov_b32_e32 v89, v0
	v_mov_b32_e32 v90, v0
	v_mov_b32_e32 v91, v0
	v_mov_b32_e32 v96, v0
	v_mov_b32_e32 v97, v0
	v_mov_b32_e32 v98, v0
	v_mov_b32_e32 v99, v0
	v_mov_b32_e32 v112, v0
	v_mov_b32_e32 v113, v0
	v_mov_b32_e32 v114, v0
	v_mov_b32_e32 v115, v0
	v_mov_b32_e32 v116, v0
	v_mov_b32_e32 v117, v0
	v_mov_b32_e32 v118, v0
	v_mov_b32_e32 v119, v0
	v_mov_b32_e32 v120, v0
	v_mov_b32_e32 v121, v0
	v_mov_b32_e32 v122, v0
	v_mov_b32_e32 v123, v0
	v_mov_b32_e32 v124, v0
	v_mov_b32_e32 v125, v0
	v_mov_b32_e32 v126, v0
	v_mov_b32_e32 v127, v0
	v_readfirstlane_b32 s98, v254
	s_nop 3
	s_lshr_b32 s98, s98, 8
	s_cmp_eq_u32 s98, 1
	s_cbranch_scc0 .Lsp_2
	s_setprio 1
.Lsp_2:
.LBB0_1021:
	s_add_u32 s2, s52, 0xfffd0080
	s_addc_u32 s3, s53, -1
	s_add_i32 s64, 0, 0x10000
	s_cmp_eq_u32 s57, 8
	s_cselect_b32 s35, s9, s3
	s_cselect_b32 s34, s8, s2
	v_add_u32_e32 v152, s64, v154
	s_cselect_b32 s3, s51, vcc_hi
	s_cselect_b32 s2, s50, vcc_lo
	s_add_i32 s66, 0, 0x14000
	ds_read_b128 v[148:151], v152
	ds_read_b128 v[156:159], v152 offset:1024
	ds_read_b128 v[160:163], v152 offset:2048
	ds_read_b128 v[164:167], v152 offset:3072
	v_add_u32_e32 v152, s66, v154
	ds_read_b128 v[168:171], v152
	ds_read_b128 v[172:175], v152 offset:1024
	ds_read_b128 v[176:179], v152 offset:2048
	ds_read_b128 v[180:183], v152 offset:3072
	v_lshl_add_u64 v[152:153], s[52:53], 0, v[140:141]
	s_add_i32 m0, s59, 0xc000
	ds_read_b128 v[184:187], v155
	ds_read_b128 v[188:191], v155 offset:1024
	ds_read_b128 v[194:197], v155 offset:2048
	ds_read_b128 v[198:201], v155 offset:3072
	ds_read_b128 v[202:205], v155 offset:4096
	ds_read_b128 v[206:209], v155 offset:5120
	ds_read_b128 v[210:213], v155 offset:6144
	ds_read_b128 v[214:217], v155 offset:7168
	global_load_lds_dwordx4 v[152:153], off
	v_lshl_add_u64 v[152:153], s[52:53], 0, v[142:143]
	s_add_i32 m0, s59, 0xe000
	s_nop 0
	global_load_lds_dwordx4 v[152:153], off
	s_waitcnt vmcnt(8)
	s_waitcnt lgkmcnt(0)
	s_barrier
; #define PG8_STAGE(bufoff, gbase, voff) do { _Pragma("unroll") for (int _i = 0; _i < 2; ++_i) \
;         __builtin_amdgcn_global_load_lds((const unsigned*)((const char*)(gbase) + (voff)[_i]), (PG8_LAS unsigned*)(lds + (bufoff) + ldsw + _i * 8192), 16, 0, 0); } while (0)
; #define PG8_LDA(dst, b, h) do { _Pragma("unroll") for (int m = 0; m < 4; ++m) _Pragma("unroll") for (int k = 0; k < 2; ++k) dst[m][k] = *(const PG8_LAS bf16x8*)(lds + PG8_SA(b, h) + aoff + m * 2048 + k * 1024); } while (0)
; #define PG8_MMA(ai, bj, At, Bt) do { __builtin_amdgcn_s_setprio(1); _Pragma("unroll") for (int m = 0; m < 4; ++m) _Pragma("unroll") for (int n = 0; n < 2; ++n) _Pragma("unroll") for (int k = 0; k < 2; ++k) \
;         acc[ai][bj][m][n] = __builtin_amdgcn_mfma_f32_16x16x32_bf16(Bt[n][k], At[m][k], acc[ai][bj][m][n], 0, 0, 0); __builtin_amdgcn_s_setprio(0); } while (0)
; #define PG8_WAIT_V(n) asm volatile("s_waitcnt vmcnt(" #n ")" ::: "memory")
; #define PG8_WAIT_L(n) asm volatile("s_waitcnt lgkmcnt(" #n ")" ::: "memory")
; #define PG8_BAR __builtin_amdgcn_s_barrier()
; #define PG8_SCHED __builtin_amdgcn_sched_barrier(0)
; template <class Epi, class Sched, bool ALIGN_EPI = false, bool SP2 = false>
; __device__ __forceinline__ void gemm_phase(PG8_LAS unsigned char* lds, const Gemm g, const Sched& S, const Epi& E) {
;     ...
;             PG8_WAIT_V(8); PG8_WAIT_L(0); PG8_BAR; PG8_MMA(0, 0, At, B0); PG8_MMA(0, 1, At, B1); PG8_BAR; PG8_SCHED;
;             PG8_LDA(At, 0, 1); PG8_STAGE(PG8_SB(0, 0), b2, voffB); PG8_STAGE(PG8_SB(0, 1), b2 + hstep, voffB); PG8_STAGE(PG8_SA(0, 0), a2, voffA);
;             PG8_WAIT_V(8); PG8_WAIT_L(0); PG8_BAR; PG8_MMA(1, 0, At, B0); PG8_MMA(1, 1, At, B1); PG8_BAR; PG8_SCHED;
	s_waitcnt lgkmcnt(0)
	v_mfma_f32_16x16x32_bf16 v[124:127], v[148:151], v[184:187], v[124:127]
	v_mfma_f32_16x16x32_bf16 v[120:123], v[160:163], v[184:187], v[120:123]
	v_mfma_f32_16x16x32_bf16 v[116:119], v[148:151], v[194:197], v[116:119]
	v_mfma_f32_16x16x32_bf16 v[112:115], v[160:163], v[194:197], v[112:115]
	v_mfma_f32_16x16x32_bf16 v[96:99], v[148:151], v[202:205], v[96:99]
	v_mfma_f32_16x16x32_bf16 v[88:91], v[160:163], v[202:205], v[88:91]
	v_mfma_f32_16x16x32_bf16 v[80:83], v[148:151], v[210:213], v[80:83]
	v_mfma_f32_16x16x32_bf16 v[72:75], v[160:163], v[210:213], v[72:75]
	v_mfma_f32_16x16x32_bf16 v[124:127], v[156:159], v[188:191], v[124:127]
	v_mfma_f32_16x16x32_bf16 v[120:123], v[164:167], v[188:191], v[120:123]
	v_mfma_f32_16x16x32_bf16 v[116:119], v[156:159], v[198:201], v[116:119]
	v_mfma_f32_16x16x32_bf16 v[112:115], v[164:167], v[198:201], v[112:115]
	v_mfma_f32_16x16x32_bf16 v[96:99], v[156:159], v[206:209], v[96:99]
	v_mfma_f32_16x16x32_bf16 v[88:91], v[164:167], v[206:209], v[88:91]
	v_mfma_f32_16x16x32_bf16 v[80:83], v[156:159], v[214:217], v[80:83]
	v_mfma_f32_16x16x32_bf16 v[72:75], v[164:167], v[214:217], v[72:75]
	v_mfma_f32_16x16x32_bf16 v[108:111], v[168:171], v[184:187], v[108:111]
	v_mfma_f32_16x16x32_bf16 v[104:107], v[176:179], v[184:187], v[104:107]
	v_mfma_f32_16x16x32_bf16 v[100:103], v[168:171], v[194:197], v[100:103]
	v_mfma_f32_16x16x32_bf16 v[92:95], v[176:179], v[194:197], v[92:95]
	v_mfma_f32_16x16x32_bf16 v[84:87], v[168:171], v[202:205], v[84:87]
	v_mfma_f32_16x16x32_bf16 v[76:79], v[176:179], v[202:205], v[76:79]
	v_mfma_f32_16x16x32_bf16 v[68:71], v[168:171], v[210:213], v[68:71]
	v_mfma_f32_16x16x32_bf16 v[64:67], v[176:179], v[210:213], v[64:67]
	v_mfma_f32_16x16x32_bf16 v[108:111], v[172:175], v[188:191], v[108:111]
	v_mfma_f32_16x16x32_bf16 v[104:107], v[180:183], v[188:191], v[104:107]
	v_mfma_f32_16x16x32_bf16 v[100:103], v[172:175], v[198:201], v[100:103]
	v_mfma_f32_16x16x32_bf16 v[92:95], v[180:183], v[198:201], v[92:95]
	v_mfma_f32_16x16x32_bf16 v[84:87], v[172:175], v[206:209], v[84:87]
	v_mfma_f32_16x16x32_bf16 v[76:79], v[180:183], v[206:209], v[76:79]
	v_mfma_f32_16x16x32_bf16 v[68:71], v[172:175], v[214:217], v[68:71]
	v_mfma_f32_16x16x32_bf16 v[64:67], v[180:183], v[214:217], v[64:67]
	s_barrier
	s_add_i32 s64, s64, s56
	v_lshl_add_u64 v[152:153], s[2:3], 0, v[130:131]
	s_mov_b32 m0, s64
	ds_read_b128 v[184:187], v155 offset:16384
	ds_read_b128 v[188:191], v155 offset:17408
	ds_read_b128 v[194:197], v155 offset:18432
	ds_read_b128 v[198:201], v155 offset:19456
	ds_read_b128 v[202:205], v155 offset:20480
	ds_read_b128 v[206:209], v155 offset:21504
	ds_read_b128 v[210:213], v155 offset:22528
	ds_read_b128 v[214:217], v155 offset:23552
	global_load_lds_dwordx4 v[152:153], off
	s_add_i32 m0, s64, 0x2000
	s_add_u32 s64, s2, 0x30000
	v_lshl_add_u64 v[218:219], s[2:3], 0, v[134:135]
	s_addc_u32 s65, s3, 0
	s_add_i32 s66, s66, s56
	global_load_lds_dwordx4 v[218:219], off
	v_lshl_add_u64 v[220:221], s[64:65], 0, v[130:131]
	s_mov_b32 m0, s66
	v_lshl_add_u64 v[222:223], s[34:35], 0, v[132:133]
	global_load_lds_dwordx4 v[220:221], off
	v_lshl_add_u64 v[220:221], s[64:65], 0, v[134:135]
	s_add_i32 m0, s66, 0x2000
	s_nop 0
	global_load_lds_dwordx4 v[220:221], off
	v_lshl_add_u64 v[220:221], s[34:35], 0, v[128:129]
	s_mov_b32 m0, s59
	s_nop 0
	global_load_lds_dwordx4 v[220:221], off
	s_mov_b32 m0, s60
	s_nop 0
	global_load_lds_dwordx4 v[222:223], off
	s_waitcnt vmcnt(8)
	s_waitcnt lgkmcnt(0)
	s_barrier
	s_waitcnt lgkmcnt(0)
	v_mfma_f32_16x16x32_bf16 v[60:63], v[148:151], v[184:187], v[60:63]
	v_mfma_f32_16x16x32_bf16 v[56:59], v[160:163], v[184:187], v[56:59]
	v_mfma_f32_16x16x32_bf16 v[48:51], v[148:151], v[194:197], v[48:51]
	v_mfma_f32_16x16x32_bf16 v[40:43], v[160:163], v[194:197], v[40:43]
	v_mfma_f32_16x16x32_bf16 v[32:35], v[148:151], v[202:205], v[32:35]
	v_mfma_f32_16x16x32_bf16 v[24:27], v[160:163], v[202:205], v[24:27]
	v_mfma_f32_16x16x32_bf16 v[16:19], v[148:151], v[210:213], v[16:19]
	v_mfma_f32_16x16x32_bf16 v[8:11], v[160:163], v[210:213], v[8:11]
	v_mfma_f32_16x16x32_bf16 v[60:63], v[156:159], v[188:191], v[60:63]
	v_mfma_f32_16x16x32_bf16 v[56:59], v[164:167], v[188:191], v[56:59]
	v_mfma_f32_16x16x32_bf16 v[48:51], v[156:159], v[198:201], v[48:51]
	v_mfma_f32_16x16x32_bf16 v[40:43], v[164:167], v[198:201], v[40:43]
	v_mfma_f32_16x16x32_bf16 v[32:35], v[156:159], v[206:209], v[32:35]
	v_mfma_f32_16x16x32_bf16 v[24:27], v[164:167], v[206:209], v[24:27]
	v_mfma_f32_16x16x32_bf16 v[16:19], v[156:159], v[214:217], v[16:19]
	v_mfma_f32_16x16x32_bf16 v[8:11], v[164:167], v[214:217], v[8:11]
	v_mfma_f32_16x16x32_bf16 v[52:55], v[168:171], v[184:187], v[52:55]
	v_mfma_f32_16x16x32_bf16 v[44:47], v[176:179], v[184:187], v[44:47]
	v_mfma_f32_16x16x32_bf16 v[36:39], v[168:171], v[194:197], v[36:39]
	v_mfma_f32_16x16x32_bf16 v[28:31], v[176:179], v[194:197], v[28:31]
	v_mfma_f32_16x16x32_bf16 v[20:23], v[168:171], v[202:205], v[20:23]
	v_mfma_f32_16x16x32_bf16 v[12:15], v[176:179], v[202:205], v[12:15]
	v_mfma_f32_16x16x32_bf16 v[4:7], v[168:171], v[210:213], v[4:7]
	v_mfma_f32_16x16x32_bf16 v[0:3], v[176:179], v[210:213], v[0:3]
	v_mfma_f32_16x16x32_bf16 v[52:55], v[172:175], v[188:191], v[52:55]
	v_mfma_f32_16x16x32_bf16 v[44:47], v[180:183], v[188:191], v[44:47]
	v_mfma_f32_16x16x32_bf16 v[36:39], v[172:175], v[198:201], v[36:39]
	v_mfma_f32_16x16x32_bf16 v[28:31], v[180:183], v[198:201], v[28:31]
	v_mfma_f32_16x16x32_bf16 v[20:23], v[172:175], v[206:209], v[20:23]
	v_mfma_f32_16x16x32_bf16 v[12:15], v[180:183], v[206:209], v[12:15]
	v_mfma_f32_16x16x32_bf16 v[4:7], v[172:175], v[214:217], v[4:7]
	v_mfma_f32_16x16x32_bf16 v[0:3], v[180:183], v[214:217], v[0:3]
	s_barrier
; #define PG8_STAGE(bufoff, gbase, voff) do { _Pragma("unroll") for (int _i = 0; _i < 2; ++_i) \
;         __builtin_amdgcn_global_load_lds((const unsigned*)((const char*)(gbase) + (voff)[_i]), (PG8_LAS unsigned*)(lds + (bufoff) + ldsw + _i * 8192), 16, 0, 0); } while (0)
; #define PG8_LDA(dst, b, h) do { _Pragma("unroll") for (int m = 0; m < 4; ++m) _Pragma("unroll") for (int k = 0; k < 2; ++k) dst[m][k] = *(const PG8_LAS bf16x8*)(lds + PG8_SA(b, h) + aoff + m * 2048 + k * 1024); } while (0)
; #define PG8_LDB(dst, b, h) do { _Pragma("unroll") for (int n = 0; n < 2; ++n) _Pragma("unroll") for (int k = 0; k < 2; ++k) dst[n][k] = *(const PG8_LAS bf16x8*)(lds + PG8_SB(b, h) + boff + n * 2048 + k * 1024); } while (0)
; #define PG8_MMA(ai, bj, At, Bt) do { __builtin_amdgcn_s_setprio(1); _Pragma("unroll") for (int m = 0; m < 4; ++m) _Pragma("unroll") for (int n = 0; n < 2; ++n) _Pragma("unroll") for (int k = 0; k < 2; ++k) \
;         acc[ai][bj][m][n] = __builtin_amdgcn_mfma_f32_16x16x32_bf16(Bt[n][k], At[m][k], acc[ai][bj][m][n], 0, 0, 0); __builtin_amdgcn_s_setprio(0); } while (0)
; #define PG8_WAIT_V(n) asm volatile("s_waitcnt vmcnt(" #n ")" ::: "memory")
; #define PG8_WAIT_L(n) asm volatile("s_waitcnt lgkmcnt(" #n ")" ::: "memory")
; #define PG8_BAR __builtin_amdgcn_s_barrier()
; #define PG8_SCHED __builtin_amdgcn_sched_barrier(0)
; template <class Epi, class Sched, bool ALIGN_EPI = false, bool SP2 = false>
; __device__ __forceinline__ void gemm_phase(PG8_LAS unsigned char* lds, const Gemm g, const Sched& S, const Epi& E) {
;     ...
;             PG8_LDB(B0, 1, 0); PG8_LDB(B1, 1, 1); PG8_SCHED; PG8_LDA(At, 1, 0); PG8_STAGE(PG8_SA(0, 1), a2 + hstep, voffA);
;             PG8_WAIT_V(8); PG8_WAIT_L(0); PG8_BAR; PG8_MMA(0, 0, At, B0); PG8_MMA(0, 1, At, B1); PG8_BAR; PG8_SCHED;
	s_add_i32 s64, 0, 0x18000
	s_add_i32 s65, 0, 0x1c000
	v_add_u32_e32 v164, s64, v154
	v_add_u32_e32 v180, s65, v154
	ds_read_b128 v[148:151], v164
	ds_read_b128 v[156:159], v164 offset:1024
	ds_read_b128 v[160:163], v164 offset:2048
	ds_read_b128 v[164:167], v164 offset:3072
	ds_read_b128 v[168:171], v180
	ds_read_b128 v[172:175], v180 offset:1024
	ds_read_b128 v[176:179], v180 offset:2048
	ds_read_b128 v[180:183], v180 offset:3072
	s_add_u32 s34, s34, 0x30000
	s_addc_u32 s35, s35, 0
	s_mov_b32 m0, s61
	v_lshl_add_u64 v[224:225], s[34:35], 0, v[128:129]
	ds_read_b128 v[184:187], v155 offset:32768
	ds_read_b128 v[188:191], v155 offset:33792
	ds_read_b128 v[194:197], v155 offset:34816
	ds_read_b128 v[198:201], v155 offset:35840
	ds_read_b128 v[202:205], v155 offset:36864
	ds_read_b128 v[206:209], v155 offset:37888
	ds_read_b128 v[210:213], v155 offset:38912
	ds_read_b128 v[214:217], v155 offset:39936
	global_load_lds_dwordx4 v[224:225], off
	v_lshl_add_u64 v[224:225], s[34:35], 0, v[132:133]
	s_mov_b32 m0, s62
	s_nop 0
	global_load_lds_dwordx4 v[224:225], off
	s_waitcnt vmcnt(8)
	s_waitcnt lgkmcnt(0)
	s_barrier
	s_waitcnt lgkmcnt(0)
	v_mfma_f32_16x16x32_bf16 v[124:127], v[148:151], v[184:187], v[124:127]
	v_mfma_f32_16x16x32_bf16 v[120:123], v[160:163], v[184:187], v[120:123]
	v_mfma_f32_16x16x32_bf16 v[116:119], v[148:151], v[194:197], v[116:119]
	v_mfma_f32_16x16x32_bf16 v[112:115], v[160:163], v[194:197], v[112:115]
	v_mfma_f32_16x16x32_bf16 v[96:99], v[148:151], v[202:205], v[96:99]
	v_mfma_f32_16x16x32_bf16 v[88:91], v[160:163], v[202:205], v[88:91]
	v_mfma_f32_16x16x32_bf16 v[80:83], v[148:151], v[210:213], v[80:83]
	v_mfma_f32_16x16x32_bf16 v[72:75], v[160:163], v[210:213], v[72:75]
	v_mfma_f32_16x16x32_bf16 v[124:127], v[156:159], v[188:191], v[124:127]
	v_mfma_f32_16x16x32_bf16 v[120:123], v[164:167], v[188:191], v[120:123]
	v_mfma_f32_16x16x32_bf16 v[116:119], v[156:159], v[198:201], v[116:119]
	v_mfma_f32_16x16x32_bf16 v[112:115], v[164:167], v[198:201], v[112:115]
	v_mfma_f32_16x16x32_bf16 v[96:99], v[156:159], v[206:209], v[96:99]
	v_mfma_f32_16x16x32_bf16 v[88:91], v[164:167], v[206:209], v[88:91]
	v_mfma_f32_16x16x32_bf16 v[80:83], v[156:159], v[214:217], v[80:83]
	v_mfma_f32_16x16x32_bf16 v[72:75], v[164:167], v[214:217], v[72:75]
	v_mfma_f32_16x16x32_bf16 v[108:111], v[168:171], v[184:187], v[108:111]
	v_mfma_f32_16x16x32_bf16 v[104:107], v[176:179], v[184:187], v[104:107]
	v_mfma_f32_16x16x32_bf16 v[100:103], v[168:171], v[194:197], v[100:103]
	v_mfma_f32_16x16x32_bf16 v[92:95], v[176:179], v[194:197], v[92:95]
	v_mfma_f32_16x16x32_bf16 v[84:87], v[168:171], v[202:205], v[84:87]
	v_mfma_f32_16x16x32_bf16 v[76:79], v[176:179], v[202:205], v[76:79]
	v_mfma_f32_16x16x32_bf16 v[68:71], v[168:171], v[210:213], v[68:71]
	v_mfma_f32_16x16x32_bf16 v[64:67], v[176:179], v[210:213], v[64:67]
	v_mfma_f32_16x16x32_bf16 v[108:111], v[172:175], v[188:191], v[108:111]
	v_mfma_f32_16x16x32_bf16 v[104:107], v[180:183], v[188:191], v[104:107]
	v_mfma_f32_16x16x32_bf16 v[100:103], v[172:175], v[198:201], v[100:103]
	v_mfma_f32_16x16x32_bf16 v[92:95], v[180:183], v[198:201], v[92:95]
	v_mfma_f32_16x16x32_bf16 v[84:87], v[172:175], v[206:209], v[84:87]
	v_mfma_f32_16x16x32_bf16 v[76:79], v[180:183], v[206:209], v[76:79]
	v_mfma_f32_16x16x32_bf16 v[68:71], v[172:175], v[214:217], v[68:71]
	v_mfma_f32_16x16x32_bf16 v[64:67], v[180:183], v[214:217], v[64:67]
	s_barrier
; #define PG8_STAGE(bufoff, gbase, voff) do { _Pragma("unroll") for (int _i = 0; _i < 2; ++_i) \
;         __builtin_amdgcn_global_load_lds((const unsigned*)((const char*)(gbase) + (voff)[_i]), (PG8_LAS unsigned*)(lds + (bufoff) + ldsw + _i * 8192), 16, 0, 0); } while (0)
; #define PG8_LDA(dst, b, h) do { _Pragma("unroll") for (int m = 0; m < 4; ++m) _Pragma("unroll") for (int k = 0; k < 2; ++k) dst[m][k] = *(const PG8_LAS bf16x8*)(lds + PG8_SA(b, h) + aoff + m * 2048 + k * 1024); } while (0)
; #define PG8_MMA(ai, bj, At, Bt) do { __builtin_amdgcn_s_setprio(1); _Pragma("unroll") for (int m = 0; m < 4; ++m) _Pragma("unroll") for (int n = 0; n < 2; ++n) _Pragma("unroll") for (int k = 0; k < 2; ++k) \
;         acc[ai][bj][m][n] = __builtin_amdgcn_mfma_f32_16x16x32_bf16(Bt[n][k], At[m][k], acc[ai][bj][m][n], 0, 0, 0); __builtin_amdgcn_s_setprio(0); } while (0)
; #define PG8_WAIT_V(n) asm volatile("s_waitcnt vmcnt(" #n ")" ::: "memory")
; #define PG8_WAIT_L(n) asm volatile("s_waitcnt lgkmcnt(" #n ")" ::: "memory")
; #define PG8_BAR __builtin_amdgcn_s_barrier()
; #define PG8_SCHED __builtin_amdgcn_sched_barrier(0)
; template <class Epi, class Sched, bool ALIGN_EPI = false, bool SP2 = false>
; __device__ __forceinline__ void gemm_phase(PG8_LAS unsigned char* lds, const Gemm g, const Sched& S, const Epi& E) {
;     ...
;         for (int t = 0; t < nt; t += 2) {
;     ...
;             PG8_LDA(At, 1, 1); PG8_STAGE(PG8_SB(1, 0), b3, voffB); PG8_STAGE(PG8_SB(1, 1), b3 + hstep, voffB); PG8_STAGE(PG8_SA(1, 0), a3, voffA);
;             PG8_WAIT_V(8); PG8_WAIT_L(0); PG8_BAR; PG8_MMA(1, 0, At, B0); PG8_MMA(1, 1, At, B1); PG8_BAR; PG8_SCHED;
	s_add_i32 s34, s64, s56
	v_lshl_add_u64 v[152:153], v[152:153], 0, s[10:11]
	s_mov_b32 m0, s34
	ds_read_b128 v[184:187], v155 offset:49152
	ds_read_b128 v[188:191], v155 offset:50176
	ds_read_b128 v[194:197], v155 offset:51200
	ds_read_b128 v[198:201], v155 offset:52224
	ds_read_b128 v[202:205], v155 offset:53248
	ds_read_b128 v[206:209], v155 offset:54272
	ds_read_b128 v[210:213], v155 offset:55296
	ds_read_b128 v[214:217], v155 offset:56320
	global_load_lds_dwordx4 v[152:153], off
	s_add_i32 m0, s34, 0x2000
	s_add_u32 s2, s2, 0x30080
	v_lshl_add_u64 v[152:153], v[218:219], 0, s[10:11]
	s_addc_u32 s3, s3, 0
	s_add_i32 s34, s65, s56
	global_load_lds_dwordx4 v[152:153], off
	v_lshl_add_u64 v[152:153], s[2:3], 0, v[130:131]
	s_mov_b32 m0, s34
	s_nop 0
	global_load_lds_dwordx4 v[152:153], off
	v_lshl_add_u64 v[152:153], s[2:3], 0, v[134:135]
	s_add_i32 m0, s34, 0x2000
	s_nop 0
	global_load_lds_dwordx4 v[152:153], off
	v_lshl_add_u64 v[152:153], v[220:221], 0, s[10:11]
	s_mov_b32 m0, s67
	s_nop 0
	global_load_lds_dwordx4 v[152:153], off
	v_lshl_add_u64 v[152:153], v[222:223], 0, s[10:11]
	s_mov_b32 m0, s68
	s_nop 0
	global_load_lds_dwordx4 v[152:153], off
	s_waitcnt vmcnt(8)
	s_waitcnt lgkmcnt(0)
	s_barrier
	s_waitcnt lgkmcnt(0)
	v_mfma_f32_16x16x32_bf16 v[60:63], v[148:151], v[184:187], v[60:63]
	v_mfma_f32_16x16x32_bf16 v[56:59], v[160:163], v[184:187], v[56:59]
	v_mfma_f32_16x16x32_bf16 v[48:51], v[148:151], v[194:197], v[48:51]
	v_mfma_f32_16x16x32_bf16 v[40:43], v[160:163], v[194:197], v[40:43]
	v_mfma_f32_16x16x32_bf16 v[32:35], v[148:151], v[202:205], v[32:35]
	v_mfma_f32_16x16x32_bf16 v[24:27], v[160:163], v[202:205], v[24:27]
	v_mfma_f32_16x16x32_bf16 v[16:19], v[148:151], v[210:213], v[16:19]
	v_mfma_f32_16x16x32_bf16 v[8:11], v[160:163], v[210:213], v[8:11]
	v_mfma_f32_16x16x32_bf16 v[60:63], v[156:159], v[188:191], v[60:63]
	v_mfma_f32_16x16x32_bf16 v[56:59], v[164:167], v[188:191], v[56:59]
	v_mfma_f32_16x16x32_bf16 v[48:51], v[156:159], v[198:201], v[48:51]
	v_mfma_f32_16x16x32_bf16 v[40:43], v[164:167], v[198:201], v[40:43]
	v_mfma_f32_16x16x32_bf16 v[32:35], v[156:159], v[206:209], v[32:35]
	v_mfma_f32_16x16x32_bf16 v[24:27], v[164:167], v[206:209], v[24:27]
	v_mfma_f32_16x16x32_bf16 v[16:19], v[156:159], v[214:217], v[16:19]
	v_mfma_f32_16x16x32_bf16 v[8:11], v[164:167], v[214:217], v[8:11]
	v_mfma_f32_16x16x32_bf16 v[52:55], v[168:171], v[184:187], v[52:55]
	v_mfma_f32_16x16x32_bf16 v[44:47], v[176:179], v[184:187], v[44:47]
	v_mfma_f32_16x16x32_bf16 v[36:39], v[168:171], v[194:197], v[36:39]
	v_mfma_f32_16x16x32_bf16 v[28:31], v[176:179], v[194:197], v[28:31]
	v_mfma_f32_16x16x32_bf16 v[20:23], v[168:171], v[202:205], v[20:23]
	v_mfma_f32_16x16x32_bf16 v[12:15], v[176:179], v[202:205], v[12:15]
	v_mfma_f32_16x16x32_bf16 v[4:7], v[168:171], v[210:213], v[4:7]
	v_mfma_f32_16x16x32_bf16 v[0:3], v[176:179], v[210:213], v[0:3]
	v_mfma_f32_16x16x32_bf16 v[52:55], v[172:175], v[188:191], v[52:55]
	v_mfma_f32_16x16x32_bf16 v[44:47], v[180:183], v[188:191], v[44:47]
	v_mfma_f32_16x16x32_bf16 v[36:39], v[172:175], v[198:201], v[36:39]
	v_mfma_f32_16x16x32_bf16 v[28:31], v[180:183], v[198:201], v[28:31]
	v_mfma_f32_16x16x32_bf16 v[20:23], v[172:175], v[206:209], v[20:23]
	v_mfma_f32_16x16x32_bf16 v[12:15], v[180:183], v[206:209], v[12:15]
	v_mfma_f32_16x16x32_bf16 v[4:7], v[172:175], v[214:217], v[4:7]
	v_mfma_f32_16x16x32_bf16 v[0:3], v[180:183], v[214:217], v[0:3]
	s_barrier
	s_add_i32 s57, s57, 2
	s_add_u32 s52, s52, 0x100
	s_addc_u32 s53, s53, 0
	s_add_u32 vcc_lo, vcc_lo, 0x100
	s_addc_u32 vcc_hi, vcc_hi, 0
	s_cmp_gt_u32 s57, 9
	s_cbranch_scc0 .LBB0_1021
	s_setprio 0
	s_and_b64 vcc, exec, s[12:13]
	s_cbranch_vccz .LBB0_1024
	s_barrier

; #define PG8_STAGE(bufoff, gbase, voff) do { _Pragma("unroll") for (int _i = 0; _i < 2; ++_i) \
;         __builtin_amdgcn_global_load_lds((const unsigned*)((const char*)(gbase) + (voff)[_i]), (PG8_LAS unsigned*)(lds + (bufoff) + ldsw + _i * 8192), 16, 0, 0); } while (0)
; #define PG8_LDA(dst, b, h) do { _Pragma("unroll") for (int m = 0; m < 4; ++m) _Pragma("unroll") for (int k = 0; k < 2; ++k) dst[m][k] = *(const PG8_LAS bf16x8*)(lds + PG8_SA(b, h) + aoff + m * 2048 + k * 1024); } while (0)
; #define PG8_LDB(dst, b, h) do { _Pragma("unroll") for (int n = 0; n < 2; ++n) _Pragma("unroll") for (int k = 0; k < 2; ++k) dst[n][k] = *(const PG8_LAS bf16x8*)(lds + PG8_SB(b, h) + boff + n * 2048 + k * 1024); } while (0)
; #define PG8_MMA(ai, bj, At, Bt) do { __builtin_amdgcn_s_setprio(1); _Pragma("unroll") for (int m = 0; m < 4; ++m) _Pragma("unroll") for (int n = 0; n < 2; ++n) _Pragma("unroll") for (int k = 0; k < 2; ++k) \
;         acc[ai][bj][m][n] = __builtin_amdgcn_mfma_f32_16x16x32_bf16(Bt[n][k], At[m][k], acc[ai][bj][m][n], 0, 0, 0); __builtin_amdgcn_s_setprio(0); } while (0)
; #define PG8_WAIT_V(n) asm volatile("s_waitcnt vmcnt(" #n ")" ::: "memory")
; #define PG8_WAIT_L(n) asm volatile("s_waitcnt lgkmcnt(" #n ")" ::: "memory")
; #define PG8_BAR __builtin_amdgcn_s_barrier()
; #define PG8_SCHED __builtin_amdgcn_sched_barrier(0)
; template <class Epi, class Sched, bool ALIGN_EPI = false, bool SP2 = false>
; __device__ __forceinline__ void gemm_phase(PG8_LAS unsigned char* lds, const Gemm g, const Sched& S, const Epi& E) {
;     ...
;         const bool has_next = S.next(ui + 1, nxt);
;         const char* nA = has_next ? (const char*)g.A + (size_t)nxt.pm * tstep : cA; const char* nB = has_next ? (const char*)g.Bt + (size_t)nxt.pn * tstep : cB;
;     ...
;             PG8_LDB(B0, 0, 0); PG8_LDB(B1, 0, 1); PG8_SCHED; PG8_LDA(At, 0, 0); PG8_STAGE(PG8_SA(1, 1), a1 + hstep, voffA);
;             PG8_WAIT_V(8); PG8_WAIT_L(0); PG8_BAR; PG8_MMA(0, 0, At, B0); PG8_MMA(0, 1, At, B1); PG8_BAR; PG8_SCHED;
;     ...
; #pragma unroll
;         for (int a = 0; a < 2; ++a)
; #pragma unroll
;             for (int b = 0; b < 2; ++b)
; #pragma unroll
;                 for (int m = 0; m < 4; ++m)
; #pragma unroll
;                     for (int n = 0; n < 2; ++n) acc[a][b][m][n] = (f32x4){0.f, 0.f, 0.f, 0.f};
;         cur = nxt; cA = nA; cB = nB; ++ui;
.LBB0_1106:
	s_ashr_i32 s19, s18, 31
	s_lshl_b64 s[20:21], s[18:19], 19
	s_add_u32 s20, s33, s20
	s_addc_u32 s21, s34, s21
	s_and_b64 s[22:23], s[6:7], exec
	s_cselect_b32 s19, s21, s27
	s_cselect_b32 s52, s20, s26
	s_ashr_i32 s11, s10, 31
	s_lshl_b64 s[22:23], s[10:11], 19
	s_add_u32 s22, s30, s22
	s_addc_u32 s23, s31, s23
	s_and_b64 s[28:29], s[6:7], exec
	s_cselect_b32 s11, s23, s3
	s_cselect_b32 s53, s22, s2
	s_add_u32 s26, s26, 0x40080
	s_addc_u32 s27, s27, 0
	s_add_u32 s54, s2, 0x100
	v_mov_b32_e32 v0, 0
	s_addc_u32 s55, s3, 0
	s_mov_b32 s56, -2
	v_mov_b32_e32 v1, v0
	v_mov_b32_e32 v2, v0
	v_mov_b32_e32 v3, v0
	v_mov_b32_e32 v4, v0
	v_mov_b32_e32 v5, v0
	v_mov_b32_e32 v6, v0
	v_mov_b32_e32 v7, v0
	v_mov_b32_e32 v8, v0
	v_mov_b32_e32 v9, v0
	v_mov_b32_e32 v10, v0
	v_mov_b32_e32 v11, v0
	v_mov_b32_e32 v12, v0
	v_mov_b32_e32 v13, v0
	v_mov_b32_e32 v14, v0
	v_mov_b32_e32 v15, v0
	v_mov_b32_e32 v32, v0
	v_mov_b32_e32 v33, v0
	v_mov_b32_e32 v34, v0
	v_mov_b32_e32 v35, v0
	v_mov_b32_e32 v36, v0
	v_mov_b32_e32 v37, v0
	v_mov_b32_e32 v38, v0
	v_mov_b32_e32 v39, v0
	v_mov_b32_e32 v40, v0
	v_mov_b32_e32 v41, v0
	v_mov_b32_e32 v42, v0
	v_mov_b32_e32 v43, v0
	v_mov_b32_e32 v44, v0
	v_mov_b32_e32 v45, v0
	v_mov_b32_e32 v46, v0
	v_mov_b32_e32 v47, v0
	v_mov_b32_e32 v16, v0
	v_mov_b32_e32 v17, v0
	v_mov_b32_e32 v18, v0
	v_mov_b32_e32 v19, v0
	v_mov_b32_e32 v20, v0
	v_mov_b32_e32 v21, v0
	v_mov_b32_e32 v22, v0
	v_mov_b32_e32 v23, v0
	v_mov_b32_e32 v24, v0
	v_mov_b32_e32 v25, v0
	v_mov_b32_e32 v26, v0
	v_mov_b32_e32 v27, v0
	v_mov_b32_e32 v28, v0
	v_mov_b32_e32 v29, v0
	v_mov_b32_e32 v30, v0
	v_mov_b32_e32 v31, v0
	v_mov_b32_e32 v48, v0
	v_mov_b32_e32 v49, v0
	v_mov_b32_e32 v50, v0
	v_mov_b32_e32 v51, v0
	v_mov_b32_e32 v52, v0
	v_mov_b32_e32 v53, v0
	v_mov_b32_e32 v54, v0
	v_mov_b32_e32 v55, v0
	v_mov_b32_e32 v56, v0
	v_mov_b32_e32 v57, v0
	v_mov_b32_e32 v58, v0
	v_mov_b32_e32 v59, v0
	v_mov_b32_e32 v60, v0
	v_mov_b32_e32 v61, v0
	v_mov_b32_e32 v62, v0
	v_mov_b32_e32 v63, v0
	v_mov_b32_e32 v64, v0
	v_mov_b32_e32 v65, v0
	v_mov_b32_e32 v66, v0
	v_mov_b32_e32 v67, v0
	v_mov_b32_e32 v68, v0
	v_mov_b32_e32 v69, v0
	v_mov_b32_e32 v70, v0
	v_mov_b32_e32 v71, v0
	v_mov_b32_e32 v72, v0
	v_mov_b32_e32 v73, v0
	v_mov_b32_e32 v74, v0
	v_mov_b32_e32 v75, v0
	v_mov_b32_e32 v76, v0
	v_mov_b32_e32 v77, v0
	v_mov_b32_e32 v78, v0
	v_mov_b32_e32 v79, v0
	v_mov_b32_e32 v96, v0
	v_mov_b32_e32 v97, v0
	v_mov_b32_e32 v98, v0
	v_mov_b32_e32 v99, v0
	v_mov_b32_e32 v100, v0
	v_mov_b32_e32 v101, v0
	v_mov_b32_e32 v102, v0
	v_mov_b32_e32 v103, v0
	v_mov_b32_e32 v104, v0
	v_mov_b32_e32 v105, v0
	v_mov_b32_e32 v106, v0
	v_mov_b32_e32 v107, v0
	v_mov_b32_e32 v108, v0
	v_mov_b32_e32 v109, v0
	v_mov_b32_e32 v110, v0
	v_mov_b32_e32 v111, v0
	v_mov_b32_e32 v80, v0
	v_mov_b32_e32 v81, v0
	v_mov_b32_e32 v82, v0
	v_mov_b32_e32 v83, v0
	v_mov_b32_e32 v84, v0
	v_mov_b32_e32 v85, v0
	v_mov_b32_e32 v86, v0
	v_mov_b32_e32 v87, v0
	v_mov_b32_e32 v88, v0
	v_mov_b32_e32 v89, v0
	v_mov_b32_e32 v90, v0
	v_mov_b32_e32 v91, v0
	v_mov_b32_e32 v92, v0
	v_mov_b32_e32 v93, v0
	v_mov_b32_e32 v94, v0
	v_mov_b32_e32 v95, v0
	v_mov_b32_e32 v112, v0
	v_mov_b32_e32 v113, v0
	v_mov_b32_e32 v114, v0
	v_mov_b32_e32 v115, v0
	v_mov_b32_e32 v116, v0
	v_mov_b32_e32 v117, v0
	v_mov_b32_e32 v118, v0
	v_mov_b32_e32 v119, v0
	v_mov_b32_e32 v120, v0
	v_mov_b32_e32 v121, v0
	v_mov_b32_e32 v122, v0
	v_mov_b32_e32 v123, v0
	v_mov_b32_e32 v124, v0
	v_mov_b32_e32 v125, v0
	v_mov_b32_e32 v126, v0
	v_mov_b32_e32 v127, v0
	v_readfirstlane_b32 s98, v254
	s_nop 3
	s_lshr_b32 s98, s98, 8
	s_cmp_eq_u32 s98, 1
	s_cbranch_scc0 .Lsp_3
	s_setprio 1
.Lsp_3:
.LBB0_1107:
	ds_read_b128 v[128:131], v169
	ds_read_b128 v[132:135], v169 offset:1024
	ds_read_b128 v[136:139], v169 offset:2048
	ds_read_b128 v[140:143], v169 offset:3072
	ds_read_b128 v[160:163], v170
	ds_read_b128 v[172:175], v170 offset:1024
	ds_read_b128 v[176:179], v170 offset:2048
	ds_read_b128 v[180:183], v170 offset:3072
	s_add_u32 s2, s26, 0xfffc0080
	s_addc_u32 s3, s27, -1
	s_cmp_eq_u32 s56, 12
	s_cselect_b32 s29, s19, s3
	s_cselect_b32 s28, s52, s2
	s_cselect_b32 s3, s11, s55
	s_cselect_b32 s2, s53, s54
	v_lshl_add_u64 v[164:165], s[26:27], 0, v[152:153]
	s_add_i32 m0, s25, 0xc000
	ds_read_b128 v[184:187], v171
	ds_read_b128 v[188:191], v171 offset:1024
	ds_read_b128 v[194:197], v171 offset:2048
	ds_read_b128 v[198:201], v171 offset:3072
	ds_read_b128 v[202:205], v171 offset:4096
	ds_read_b128 v[206:209], v171 offset:5120
	ds_read_b128 v[210:213], v171 offset:6144
	ds_read_b128 v[214:217], v171 offset:7168
	global_load_lds_dwordx4 v[164:165], off
	v_lshl_add_u64 v[164:165], s[26:27], 0, v[154:155]
	s_add_i32 m0, s25, 0xe000
	s_nop 0
	global_load_lds_dwordx4 v[164:165], off
	s_waitcnt vmcnt(8)
	s_waitcnt lgkmcnt(0)
	s_barrier
; #define PG8_STAGE(bufoff, gbase, voff) do { _Pragma("unroll") for (int _i = 0; _i < 2; ++_i) \
;         __builtin_amdgcn_global_load_lds((const unsigned*)((const char*)(gbase) + (voff)[_i]), (PG8_LAS unsigned*)(lds + (bufoff) + ldsw + _i * 8192), 16, 0, 0); } while (0)
; #define PG8_LDA(dst, b, h) do { _Pragma("unroll") for (int m = 0; m < 4; ++m) _Pragma("unroll") for (int k = 0; k < 2; ++k) dst[m][k] = *(const PG8_LAS bf16x8*)(lds + PG8_SA(b, h) + aoff + m * 2048 + k * 1024); } while (0)
; #define PG8_MMA(ai, bj, At, Bt) do { __builtin_amdgcn_s_setprio(1); _Pragma("unroll") for (int m = 0; m < 4; ++m) _Pragma("unroll") for (int n = 0; n < 2; ++n) _Pragma("unroll") for (int k = 0; k < 2; ++k) \
;         acc[ai][bj][m][n] = __builtin_amdgcn_mfma_f32_16x16x32_bf16(Bt[n][k], At[m][k], acc[ai][bj][m][n], 0, 0, 0); __builtin_amdgcn_s_setprio(0); } while (0)
; #define PG8_WAIT_V(n) asm volatile("s_waitcnt vmcnt(" #n ")" ::: "memory")
; #define PG8_WAIT_L(n) asm volatile("s_waitcnt lgkmcnt(" #n ")" ::: "memory")
; #define PG8_BAR __builtin_amdgcn_s_barrier()
; #define PG8_SCHED __builtin_amdgcn_sched_barrier(0)
; template <class Epi, class Sched, bool ALIGN_EPI = false, bool SP2 = false>
; __device__ __forceinline__ void gemm_phase(PG8_LAS unsigned char* lds, const Gemm g, const Sched& S, const Epi& E) {
;     ...
;             PG8_WAIT_V(8); PG8_WAIT_L(0); PG8_BAR; PG8_MMA(0, 0, At, B0); PG8_MMA(0, 1, At, B1); PG8_BAR; PG8_SCHED;
;             PG8_LDA(At, 0, 1); PG8_STAGE(PG8_SB(0, 0), b2, voffB); PG8_STAGE(PG8_SB(0, 1), b2 + hstep, voffB); PG8_STAGE(PG8_SA(0, 0), a2, voffA);
;             PG8_WAIT_V(8); PG8_WAIT_L(0); PG8_BAR; PG8_MMA(1, 0, At, B0); PG8_MMA(1, 1, At, B1); PG8_BAR; PG8_SCHED;
	s_waitcnt lgkmcnt(0)
	v_mfma_f32_16x16x32_bf16 v[124:127], v[128:131], v[184:187], v[124:127]
	v_mfma_f32_16x16x32_bf16 v[120:123], v[136:139], v[184:187], v[120:123]
	v_mfma_f32_16x16x32_bf16 v[116:119], v[128:131], v[194:197], v[116:119]
	v_mfma_f32_16x16x32_bf16 v[112:115], v[136:139], v[194:197], v[112:115]
	v_mfma_f32_16x16x32_bf16 v[92:95], v[128:131], v[202:205], v[92:95]
	v_mfma_f32_16x16x32_bf16 v[88:91], v[136:139], v[202:205], v[88:91]
	v_mfma_f32_16x16x32_bf16 v[84:87], v[128:131], v[210:213], v[84:87]
	v_mfma_f32_16x16x32_bf16 v[80:83], v[136:139], v[210:213], v[80:83]
	v_mfma_f32_16x16x32_bf16 v[124:127], v[132:135], v[188:191], v[124:127]
	v_mfma_f32_16x16x32_bf16 v[120:123], v[140:143], v[188:191], v[120:123]
	v_mfma_f32_16x16x32_bf16 v[116:119], v[132:135], v[198:201], v[116:119]
	v_mfma_f32_16x16x32_bf16 v[112:115], v[140:143], v[198:201], v[112:115]
	v_mfma_f32_16x16x32_bf16 v[92:95], v[132:135], v[206:209], v[92:95]
	v_mfma_f32_16x16x32_bf16 v[88:91], v[140:143], v[206:209], v[88:91]
	v_mfma_f32_16x16x32_bf16 v[84:87], v[132:135], v[214:217], v[84:87]
	v_mfma_f32_16x16x32_bf16 v[80:83], v[140:143], v[214:217], v[80:83]
	v_mfma_f32_16x16x32_bf16 v[108:111], v[160:163], v[184:187], v[108:111]
	v_mfma_f32_16x16x32_bf16 v[104:107], v[176:179], v[184:187], v[104:107]
	v_mfma_f32_16x16x32_bf16 v[100:103], v[160:163], v[194:197], v[100:103]
	v_mfma_f32_16x16x32_bf16 v[96:99], v[176:179], v[194:197], v[96:99]
	v_mfma_f32_16x16x32_bf16 v[76:79], v[160:163], v[202:205], v[76:79]
	v_mfma_f32_16x16x32_bf16 v[72:75], v[176:179], v[202:205], v[72:75]
	v_mfma_f32_16x16x32_bf16 v[68:71], v[160:163], v[210:213], v[68:71]
	v_mfma_f32_16x16x32_bf16 v[64:67], v[176:179], v[210:213], v[64:67]
	v_mfma_f32_16x16x32_bf16 v[108:111], v[172:175], v[188:191], v[108:111]
	v_mfma_f32_16x16x32_bf16 v[104:107], v[180:183], v[188:191], v[104:107]
	v_mfma_f32_16x16x32_bf16 v[100:103], v[172:175], v[198:201], v[100:103]
	v_mfma_f32_16x16x32_bf16 v[96:99], v[180:183], v[198:201], v[96:99]
	v_mfma_f32_16x16x32_bf16 v[76:79], v[172:175], v[206:209], v[76:79]
	v_mfma_f32_16x16x32_bf16 v[72:75], v[180:183], v[206:209], v[72:75]
	v_mfma_f32_16x16x32_bf16 v[68:71], v[172:175], v[214:217], v[68:71]
	v_mfma_f32_16x16x32_bf16 v[64:67], v[180:183], v[214:217], v[64:67]
	s_barrier
	s_add_i32 s57, s49, s35
	v_lshl_add_u64 v[164:165], s[2:3], 0, v[146:147]
	s_mov_b32 m0, s57
	ds_read_b128 v[184:187], v171 offset:16384
	ds_read_b128 v[188:191], v171 offset:17408
	ds_read_b128 v[194:197], v171 offset:18432
	ds_read_b128 v[198:201], v171 offset:19456
	ds_read_b128 v[202:205], v171 offset:20480
	ds_read_b128 v[206:209], v171 offset:21504
	ds_read_b128 v[210:213], v171 offset:22528
	ds_read_b128 v[214:217], v171 offset:23552
	global_load_lds_dwordx4 v[164:165], off
	s_add_i32 m0, s57, 0x2000
	s_add_u32 s58, s2, 0x40000
	v_lshl_add_u64 v[192:193], s[2:3], 0, v[150:151]
	s_addc_u32 s59, s3, 0
	s_add_i32 s57, s50, s35
	global_load_lds_dwordx4 v[192:193], off
	v_lshl_add_u64 v[218:219], s[58:59], 0, v[146:147]
	s_mov_b32 m0, s57
	v_lshl_add_u64 v[220:221], s[28:29], 0, v[148:149]
	global_load_lds_dwordx4 v[218:219], off
	v_lshl_add_u64 v[218:219], s[58:59], 0, v[150:151]
	s_add_i32 m0, s57, 0x2000
	s_nop 0
	global_load_lds_dwordx4 v[218:219], off
	v_lshl_add_u64 v[218:219], s[28:29], 0, v[144:145]
	s_mov_b32 m0, s25
	s_nop 0
	global_load_lds_dwordx4 v[218:219], off
	s_mov_b32 m0, s38
	s_nop 0
	global_load_lds_dwordx4 v[220:221], off
	s_waitcnt vmcnt(8)
	s_waitcnt lgkmcnt(0)
	s_barrier
	s_waitcnt lgkmcnt(0)
	v_mfma_f32_16x16x32_bf16 v[60:63], v[128:131], v[184:187], v[60:63]
	v_mfma_f32_16x16x32_bf16 v[56:59], v[136:139], v[184:187], v[56:59]
	v_mfma_f32_16x16x32_bf16 v[52:55], v[128:131], v[194:197], v[52:55]
	v_mfma_f32_16x16x32_bf16 v[48:51], v[136:139], v[194:197], v[48:51]
	v_mfma_f32_16x16x32_bf16 v[28:31], v[128:131], v[202:205], v[28:31]
	v_mfma_f32_16x16x32_bf16 v[24:27], v[136:139], v[202:205], v[24:27]
	v_mfma_f32_16x16x32_bf16 v[20:23], v[128:131], v[210:213], v[20:23]
	v_mfma_f32_16x16x32_bf16 v[16:19], v[136:139], v[210:213], v[16:19]
	v_mfma_f32_16x16x32_bf16 v[60:63], v[132:135], v[188:191], v[60:63]
	v_mfma_f32_16x16x32_bf16 v[56:59], v[140:143], v[188:191], v[56:59]
	v_mfma_f32_16x16x32_bf16 v[52:55], v[132:135], v[198:201], v[52:55]
	v_mfma_f32_16x16x32_bf16 v[48:51], v[140:143], v[198:201], v[48:51]
	v_mfma_f32_16x16x32_bf16 v[28:31], v[132:135], v[206:209], v[28:31]
	v_mfma_f32_16x16x32_bf16 v[24:27], v[140:143], v[206:209], v[24:27]
	v_mfma_f32_16x16x32_bf16 v[20:23], v[132:135], v[214:217], v[20:23]
	v_mfma_f32_16x16x32_bf16 v[16:19], v[140:143], v[214:217], v[16:19]
	v_mfma_f32_16x16x32_bf16 v[44:47], v[160:163], v[184:187], v[44:47]
	v_mfma_f32_16x16x32_bf16 v[40:43], v[176:179], v[184:187], v[40:43]
	v_mfma_f32_16x16x32_bf16 v[36:39], v[160:163], v[194:197], v[36:39]
	v_mfma_f32_16x16x32_bf16 v[32:35], v[176:179], v[194:197], v[32:35]
	v_mfma_f32_16x16x32_bf16 v[12:15], v[160:163], v[202:205], v[12:15]
	v_mfma_f32_16x16x32_bf16 v[8:11], v[176:179], v[202:205], v[8:11]
	v_mfma_f32_16x16x32_bf16 v[4:7], v[160:163], v[210:213], v[4:7]
	v_mfma_f32_16x16x32_bf16 v[0:3], v[176:179], v[210:213], v[0:3]
	v_mfma_f32_16x16x32_bf16 v[44:47], v[172:175], v[188:191], v[44:47]
	v_mfma_f32_16x16x32_bf16 v[40:43], v[180:183], v[188:191], v[40:43]
	v_mfma_f32_16x16x32_bf16 v[36:39], v[172:175], v[198:201], v[36:39]
	v_mfma_f32_16x16x32_bf16 v[32:35], v[180:183], v[198:201], v[32:35]
	v_mfma_f32_16x16x32_bf16 v[12:15], v[172:175], v[206:209], v[12:15]
	v_mfma_f32_16x16x32_bf16 v[8:11], v[180:183], v[206:209], v[8:11]
	v_mfma_f32_16x16x32_bf16 v[4:7], v[172:175], v[214:217], v[4:7]
	v_mfma_f32_16x16x32_bf16 v[0:3], v[180:183], v[214:217], v[0:3]
	s_barrier
; #define PG8_STAGE(bufoff, gbase, voff) do { _Pragma("unroll") for (int _i = 0; _i < 2; ++_i) \
;         __builtin_amdgcn_global_load_lds((const unsigned*)((const char*)(gbase) + (voff)[_i]), (PG8_LAS unsigned*)(lds + (bufoff) + ldsw + _i * 8192), 16, 0, 0); } while (0)
; #define PG8_LDA(dst, b, h) do { _Pragma("unroll") for (int m = 0; m < 4; ++m) _Pragma("unroll") for (int k = 0; k < 2; ++k) dst[m][k] = *(const PG8_LAS bf16x8*)(lds + PG8_SA(b, h) + aoff + m * 2048 + k * 1024); } while (0)
; #define PG8_LDB(dst, b, h) do { _Pragma("unroll") for (int n = 0; n < 2; ++n) _Pragma("unroll") for (int k = 0; k < 2; ++k) dst[n][k] = *(const PG8_LAS bf16x8*)(lds + PG8_SB(b, h) + boff + n * 2048 + k * 1024); } while (0)
; #define PG8_MMA(ai, bj, At, Bt) do { __builtin_amdgcn_s_setprio(1); _Pragma("unroll") for (int m = 0; m < 4; ++m) _Pragma("unroll") for (int n = 0; n < 2; ++n) _Pragma("unroll") for (int k = 0; k < 2; ++k) \
;         acc[ai][bj][m][n] = __builtin_amdgcn_mfma_f32_16x16x32_bf16(Bt[n][k], At[m][k], acc[ai][bj][m][n], 0, 0, 0); __builtin_amdgcn_s_setprio(0); } while (0)
; #define PG8_WAIT_V(n) asm volatile("s_waitcnt vmcnt(" #n ")" ::: "memory")
; #define PG8_WAIT_L(n) asm volatile("s_waitcnt lgkmcnt(" #n ")" ::: "memory")
; #define PG8_BAR __builtin_amdgcn_s_barrier()
; #define PG8_SCHED __builtin_amdgcn_sched_barrier(0)
; template <class Epi, class Sched, bool ALIGN_EPI = false, bool SP2 = false>
; __device__ __forceinline__ void gemm_phase(PG8_LAS unsigned char* lds, const Gemm g, const Sched& S, const Epi& E) {
;     ...
;             PG8_LDB(B0, 1, 0); PG8_LDB(B1, 1, 1); PG8_SCHED; PG8_LDA(At, 1, 0); PG8_STAGE(PG8_SA(0, 1), a2 + hstep, voffA);
;             PG8_WAIT_V(8); PG8_WAIT_L(0); PG8_BAR; PG8_MMA(0, 0, At, B0); PG8_MMA(0, 1, At, B1); PG8_BAR; PG8_SCHED;
	s_add_i32 s57, 0, 0x18000
	s_add_i32 s58, 0, 0x1c000
	v_add_u32_e32 v140, s57, v167
	v_add_u32_e32 v180, s58, v167
	ds_read_b128 v[128:131], v140
	ds_read_b128 v[132:135], v140 offset:1024
	ds_read_b128 v[136:139], v140 offset:2048
	ds_read_b128 v[140:143], v140 offset:3072
	ds_read_b128 v[160:163], v180
	ds_read_b128 v[172:175], v180 offset:1024
	ds_read_b128 v[176:179], v180 offset:2048
	ds_read_b128 v[180:183], v180 offset:3072
	s_add_u32 s28, s28, 0x40000
	s_addc_u32 s29, s29, 0
	s_mov_b32 m0, s39
	v_lshl_add_u64 v[222:223], s[28:29], 0, v[144:145]
	ds_read_b128 v[184:187], v171 offset:32768
	ds_read_b128 v[188:191], v171 offset:33792
	ds_read_b128 v[194:197], v171 offset:34816
	ds_read_b128 v[198:201], v171 offset:35840
	ds_read_b128 v[202:205], v171 offset:36864
	ds_read_b128 v[206:209], v171 offset:37888
	ds_read_b128 v[210:213], v171 offset:38912
	ds_read_b128 v[214:217], v171 offset:39936
	global_load_lds_dwordx4 v[222:223], off
	v_lshl_add_u64 v[222:223], s[28:29], 0, v[148:149]
	s_mov_b32 m0, s40
	s_nop 0
	global_load_lds_dwordx4 v[222:223], off
	s_waitcnt vmcnt(8)
	s_waitcnt lgkmcnt(0)
	s_barrier
	s_waitcnt lgkmcnt(0)
	v_mfma_f32_16x16x32_bf16 v[124:127], v[128:131], v[184:187], v[124:127]
	v_mfma_f32_16x16x32_bf16 v[120:123], v[136:139], v[184:187], v[120:123]
	v_mfma_f32_16x16x32_bf16 v[116:119], v[128:131], v[194:197], v[116:119]
	v_mfma_f32_16x16x32_bf16 v[112:115], v[136:139], v[194:197], v[112:115]
	v_mfma_f32_16x16x32_bf16 v[92:95], v[128:131], v[202:205], v[92:95]
	v_mfma_f32_16x16x32_bf16 v[88:91], v[136:139], v[202:205], v[88:91]
	v_mfma_f32_16x16x32_bf16 v[84:87], v[128:131], v[210:213], v[84:87]
	v_mfma_f32_16x16x32_bf16 v[80:83], v[136:139], v[210:213], v[80:83]
	v_mfma_f32_16x16x32_bf16 v[124:127], v[132:135], v[188:191], v[124:127]
	v_mfma_f32_16x16x32_bf16 v[120:123], v[140:143], v[188:191], v[120:123]
	v_mfma_f32_16x16x32_bf16 v[116:119], v[132:135], v[198:201], v[116:119]
	v_mfma_f32_16x16x32_bf16 v[112:115], v[140:143], v[198:201], v[112:115]
	v_mfma_f32_16x16x32_bf16 v[92:95], v[132:135], v[206:209], v[92:95]
	v_mfma_f32_16x16x32_bf16 v[88:91], v[140:143], v[206:209], v[88:91]
	v_mfma_f32_16x16x32_bf16 v[84:87], v[132:135], v[214:217], v[84:87]
	v_mfma_f32_16x16x32_bf16 v[80:83], v[140:143], v[214:217], v[80:83]
	v_mfma_f32_16x16x32_bf16 v[108:111], v[160:163], v[184:187], v[108:111]
	v_mfma_f32_16x16x32_bf16 v[104:107], v[176:179], v[184:187], v[104:107]
	v_mfma_f32_16x16x32_bf16 v[100:103], v[160:163], v[194:197], v[100:103]
	v_mfma_f32_16x16x32_bf16 v[96:99], v[176:179], v[194:197], v[96:99]
	v_mfma_f32_16x16x32_bf16 v[76:79], v[160:163], v[202:205], v[76:79]
	v_mfma_f32_16x16x32_bf16 v[72:75], v[176:179], v[202:205], v[72:75]
	v_mfma_f32_16x16x32_bf16 v[68:71], v[160:163], v[210:213], v[68:71]
	v_mfma_f32_16x16x32_bf16 v[64:67], v[176:179], v[210:213], v[64:67]
	v_mfma_f32_16x16x32_bf16 v[108:111], v[172:175], v[188:191], v[108:111]
	v_mfma_f32_16x16x32_bf16 v[104:107], v[180:183], v[188:191], v[104:107]
	v_mfma_f32_16x16x32_bf16 v[100:103], v[172:175], v[198:201], v[100:103]
	v_mfma_f32_16x16x32_bf16 v[96:99], v[180:183], v[198:201], v[96:99]
	v_mfma_f32_16x16x32_bf16 v[76:79], v[172:175], v[206:209], v[76:79]
	v_mfma_f32_16x16x32_bf16 v[72:75], v[180:183], v[206:209], v[72:75]
	v_mfma_f32_16x16x32_bf16 v[68:71], v[172:175], v[214:217], v[68:71]
	v_mfma_f32_16x16x32_bf16 v[64:67], v[180:183], v[214:217], v[64:67]
	s_barrier
; #define PG8_STAGE(bufoff, gbase, voff) do { _Pragma("unroll") for (int _i = 0; _i < 2; ++_i) \
;         __builtin_amdgcn_global_load_lds((const unsigned*)((const char*)(gbase) + (voff)[_i]), (PG8_LAS unsigned*)(lds + (bufoff) + ldsw + _i * 8192), 16, 0, 0); } while (0)
; #define PG8_LDA(dst, b, h) do { _Pragma("unroll") for (int m = 0; m < 4; ++m) _Pragma("unroll") for (int k = 0; k < 2; ++k) dst[m][k] = *(const PG8_LAS bf16x8*)(lds + PG8_SA(b, h) + aoff + m * 2048 + k * 1024); } while (0)
; #define PG8_MMA(ai, bj, At, Bt) do { __builtin_amdgcn_s_setprio(1); _Pragma("unroll") for (int m = 0; m < 4; ++m) _Pragma("unroll") for (int n = 0; n < 2; ++n) _Pragma("unroll") for (int k = 0; k < 2; ++k) \
;         acc[ai][bj][m][n] = __builtin_amdgcn_mfma_f32_16x16x32_bf16(Bt[n][k], At[m][k], acc[ai][bj][m][n], 0, 0, 0); __builtin_amdgcn_s_setprio(0); } while (0)
; #define PG8_WAIT_V(n) asm volatile("s_waitcnt vmcnt(" #n ")" ::: "memory")
; #define PG8_WAIT_L(n) asm volatile("s_waitcnt lgkmcnt(" #n ")" ::: "memory")
; #define PG8_BAR __builtin_amdgcn_s_barrier()
; #define PG8_SCHED __builtin_amdgcn_sched_barrier(0)
; template <class Epi, class Sched, bool ALIGN_EPI = false, bool SP2 = false>
; __device__ __forceinline__ void gemm_phase(PG8_LAS unsigned char* lds, const Gemm g, const Sched& S, const Epi& E) {
;     ...
;         for (int t = 0; t < nt; t += 2) {
;     ...
;             PG8_LDA(At, 1, 1); PG8_STAGE(PG8_SB(1, 0), b3, voffB); PG8_STAGE(PG8_SB(1, 1), b3 + hstep, voffB); PG8_STAGE(PG8_SA(1, 0), a3, voffA);
;             PG8_WAIT_V(8); PG8_WAIT_L(0); PG8_BAR; PG8_MMA(1, 0, At, B0); PG8_MMA(1, 1, At, B1); PG8_BAR; PG8_SCHED;
	s_add_i32 s28, s57, s35
	v_lshl_add_u64 v[164:165], v[164:165], 0, s[14:15]
	s_mov_b32 m0, s28
	ds_read_b128 v[184:187], v171 offset:49152
	ds_read_b128 v[188:191], v171 offset:50176
	ds_read_b128 v[194:197], v171 offset:51200
	ds_read_b128 v[198:201], v171 offset:52224
	ds_read_b128 v[202:205], v171 offset:53248
	ds_read_b128 v[206:209], v171 offset:54272
	ds_read_b128 v[210:213], v171 offset:55296
	ds_read_b128 v[214:217], v171 offset:56320
	global_load_lds_dwordx4 v[164:165], off
	s_add_i32 m0, s28, 0x2000
	s_add_u32 s2, s2, 0x40080
	v_lshl_add_u64 v[164:165], v[192:193], 0, s[14:15]
	s_addc_u32 s3, s3, 0
	s_add_i32 s28, s58, s35
	global_load_lds_dwordx4 v[164:165], off
	v_lshl_add_u64 v[164:165], s[2:3], 0, v[146:147]
	s_mov_b32 m0, s28
	s_nop 0
	global_load_lds_dwordx4 v[164:165], off
	v_lshl_add_u64 v[164:165], s[2:3], 0, v[150:151]
	s_add_i32 m0, s28, 0x2000
	s_nop 0
	global_load_lds_dwordx4 v[164:165], off
	v_lshl_add_u64 v[164:165], v[218:219], 0, s[14:15]
	s_mov_b32 m0, s45
	s_nop 0
	global_load_lds_dwordx4 v[164:165], off
	v_lshl_add_u64 v[164:165], v[220:221], 0, s[14:15]
	s_mov_b32 m0, s46
	s_nop 0
	global_load_lds_dwordx4 v[164:165], off
	s_waitcnt vmcnt(8)
	s_waitcnt lgkmcnt(0)
	s_barrier
	s_waitcnt lgkmcnt(0)
	v_mfma_f32_16x16x32_bf16 v[60:63], v[128:131], v[184:187], v[60:63]
	v_mfma_f32_16x16x32_bf16 v[56:59], v[136:139], v[184:187], v[56:59]
	v_mfma_f32_16x16x32_bf16 v[52:55], v[128:131], v[194:197], v[52:55]
	v_mfma_f32_16x16x32_bf16 v[48:51], v[136:139], v[194:197], v[48:51]
	v_mfma_f32_16x16x32_bf16 v[28:31], v[128:131], v[202:205], v[28:31]
	v_mfma_f32_16x16x32_bf16 v[24:27], v[136:139], v[202:205], v[24:27]
	v_mfma_f32_16x16x32_bf16 v[20:23], v[128:131], v[210:213], v[20:23]
	v_mfma_f32_16x16x32_bf16 v[16:19], v[136:139], v[210:213], v[16:19]
	v_mfma_f32_16x16x32_bf16 v[60:63], v[132:135], v[188:191], v[60:63]
	v_mfma_f32_16x16x32_bf16 v[56:59], v[140:143], v[188:191], v[56:59]
	v_mfma_f32_16x16x32_bf16 v[52:55], v[132:135], v[198:201], v[52:55]
	v_mfma_f32_16x16x32_bf16 v[48:51], v[140:143], v[198:201], v[48:51]
	v_mfma_f32_16x16x32_bf16 v[28:31], v[132:135], v[206:209], v[28:31]
	v_mfma_f32_16x16x32_bf16 v[24:27], v[140:143], v[206:209], v[24:27]
	v_mfma_f32_16x16x32_bf16 v[20:23], v[132:135], v[214:217], v[20:23]
	v_mfma_f32_16x16x32_bf16 v[16:19], v[140:143], v[214:217], v[16:19]
	v_mfma_f32_16x16x32_bf16 v[44:47], v[160:163], v[184:187], v[44:47]
	v_mfma_f32_16x16x32_bf16 v[40:43], v[176:179], v[184:187], v[40:43]
	v_mfma_f32_16x16x32_bf16 v[36:39], v[160:163], v[194:197], v[36:39]
	v_mfma_f32_16x16x32_bf16 v[32:35], v[176:179], v[194:197], v[32:35]
	v_mfma_f32_16x16x32_bf16 v[12:15], v[160:163], v[202:205], v[12:15]
	v_mfma_f32_16x16x32_bf16 v[8:11], v[176:179], v[202:205], v[8:11]
	v_mfma_f32_16x16x32_bf16 v[4:7], v[160:163], v[210:213], v[4:7]
	v_mfma_f32_16x16x32_bf16 v[0:3], v[176:179], v[210:213], v[0:3]
	v_mfma_f32_16x16x32_bf16 v[44:47], v[172:175], v[188:191], v[44:47]
	v_mfma_f32_16x16x32_bf16 v[40:43], v[180:183], v[188:191], v[40:43]
	v_mfma_f32_16x16x32_bf16 v[36:39], v[172:175], v[198:201], v[36:39]
	v_mfma_f32_16x16x32_bf16 v[32:35], v[180:183], v[198:201], v[32:35]
	v_mfma_f32_16x16x32_bf16 v[12:15], v[172:175], v[206:209], v[12:15]
	v_mfma_f32_16x16x32_bf16 v[8:11], v[180:183], v[206:209], v[8:11]
	v_mfma_f32_16x16x32_bf16 v[4:7], v[172:175], v[214:217], v[4:7]
	v_mfma_f32_16x16x32_bf16 v[0:3], v[180:183], v[214:217], v[0:3]
	s_barrier
	s_add_i32 s56, s56, 2
	s_add_u32 s26, s26, 0x100
	s_addc_u32 s27, s27, 0
	s_add_u32 s54, s54, 0x100
	s_addc_u32 s55, s55, 0
	s_cmp_gt_u32 s56, 13
	s_cbranch_scc0 .LBB0_1107
	s_setprio 0
	s_and_b64 vcc, exec, s[16:17]
	s_cbranch_vccz .LBB0_1110
	s_barrier

; #define PG8_STAGE(bufoff, gbase, voff) do { _Pragma("unroll") for (int _i = 0; _i < 2; ++_i) \
;         __builtin_amdgcn_global_load_lds((const unsigned*)((const char*)(gbase) + (voff)[_i]), (PG8_LAS unsigned*)(lds + (bufoff) + ldsw + _i * 8192), 16, 0, 0); } while (0)
; #define PG8_LDA(dst, b, h) do { _Pragma("unroll") for (int m = 0; m < 4; ++m) _Pragma("unroll") for (int k = 0; k < 2; ++k) dst[m][k] = *(const PG8_LAS bf16x8*)(lds + PG8_SA(b, h) + aoff + m * 2048 + k * 1024); } while (0)
; #define PG8_LDB(dst, b, h) do { _Pragma("unroll") for (int n = 0; n < 2; ++n) _Pragma("unroll") for (int k = 0; k < 2; ++k) dst[n][k] = *(const PG8_LAS bf16x8*)(lds + PG8_SB(b, h) + boff + n * 2048 + k * 1024); } while (0)
; #define PG8_WAIT_V(n) asm volatile("s_waitcnt vmcnt(" #n ")" ::: "memory")
; #define PG8_WAIT_L(n) asm volatile("s_waitcnt lgkmcnt(" #n ")" ::: "memory")
; #define PG8_BAR __builtin_amdgcn_s_barrier()
; template <class Epi, class Sched, bool ALIGN_EPI = false, bool SP2 = false>
; __device__ __forceinline__ void gemm_phase(PG8_LAS unsigned char* lds, const Gemm g, const Sched& S, const Epi& E) {
;     ...
;         const bool has_next = S.next(ui + 1, nxt);
;         const char* nA = has_next ? (const char*)g.A + (size_t)nxt.pm * tstep : cA; const char* nB = has_next ? (const char*)g.Bt + (size_t)nxt.pn * tstep : cB;
;         for (int t = 0; t < nt; t += 2) {
;             const bool last = (t == nt - 2);
;             const char* a1 = cA + (size_t)(t + 1) * kstep;
;             const char* a2 = last ? nA : cA + (size_t)(t + 2) * kstep; const char* b2 = last ? nB : cB + (size_t)(t + 2) * kstep;
;             const char* a3 = a2 + kstep; const char* b3 = b2 + kstep;
;             if (last && has_next) S.a_ready(nxt);
;             if constexpr (SP2) {
;             PG8_LDB(B0, 0, 0); PG8_LDB(B1, 0, 1); PG8_SCHED; PG8_LDA(At, 0, 0); PG8_STAGE(PG8_SA(1, 1), a1 + hstep, voffA);
;             PG8_WAIT_V(8); PG8_WAIT_L(0); PG8_BAR; PG8_MMA(0, 0, At, B0); PG8_MMA(0, 1, At, B1); PG8_BAR; PG8_SCHED;
;     ...
; #pragma unroll
;         for (int a = 0; a < 2; ++a)
; #pragma unroll
;             for (int b = 0; b < 2; ++b)
; #pragma unroll
;                 for (int m = 0; m < 4; ++m)
; #pragma unroll
;                     for (int n = 0; n < 2; ++n) acc[a][b][m][n] = (f32x4){0.f, 0.f, 0.f, 0.f};
;         cur = nxt; cA = nA; cB = nB; ++ui;
.LBB0_1241:
	s_ashr_i32 s25, s24, 31
	s_lshl_b64 s[26:27], s[24:25], 19
	s_add_u32 s26, s39, s26
	s_addc_u32 s27, s40, s27
	s_and_b64 s[28:29], s[6:7], exec
	s_cselect_b32 s25, s27, s35
	s_cselect_b32 s58, s26, s34
	s_ashr_i32 s23, s22, 31
	s_lshl_b64 s[28:29], s[22:23], 19
	s_add_u32 s28, s33, s28
	s_addc_u32 s29, s38, s29
	s_and_b64 s[36:37], s[6:7], exec
	s_cselect_b32 s23, s29, s3
	s_cselect_b32 s59, s28, s2
	s_add_u32 s36, s34, 0x40080
	s_addc_u32 s37, s35, 0
	s_add_u32 s60, s2, 0x100
	v_mov_b32_e32 v0, 0
	s_addc_u32 s61, s3, 0
	s_mov_b32 s62, -2
	v_mov_b32_e32 v1, v0
	v_mov_b32_e32 v2, v0
	v_mov_b32_e32 v3, v0
	v_mov_b32_e32 v4, v0
	v_mov_b32_e32 v5, v0
	v_mov_b32_e32 v6, v0
	v_mov_b32_e32 v7, v0
	v_mov_b32_e32 v16, v0
	v_mov_b32_e32 v17, v0
	v_mov_b32_e32 v18, v0
	v_mov_b32_e32 v19, v0
	v_mov_b32_e32 v20, v0
	v_mov_b32_e32 v21, v0
	v_mov_b32_e32 v22, v0
	v_mov_b32_e32 v23, v0
	v_mov_b32_e32 v32, v0
	v_mov_b32_e32 v33, v0
	v_mov_b32_e32 v34, v0
	v_mov_b32_e32 v35, v0
	v_mov_b32_e32 v36, v0
	v_mov_b32_e32 v37, v0
	v_mov_b32_e32 v38, v0
	v_mov_b32_e32 v39, v0
	v_mov_b32_e32 v48, v0
	v_mov_b32_e32 v49, v0
	v_mov_b32_e32 v50, v0
	v_mov_b32_e32 v51, v0
	v_mov_b32_e32 v52, v0
	v_mov_b32_e32 v53, v0
	v_mov_b32_e32 v54, v0
	v_mov_b32_e32 v55, v0
	v_mov_b32_e32 v8, v0
	v_mov_b32_e32 v9, v0
	v_mov_b32_e32 v10, v0
	v_mov_b32_e32 v11, v0
	v_mov_b32_e32 v12, v0
	v_mov_b32_e32 v13, v0
	v_mov_b32_e32 v14, v0
	v_mov_b32_e32 v15, v0
	v_mov_b32_e32 v24, v0
	v_mov_b32_e32 v25, v0
	v_mov_b32_e32 v26, v0
	v_mov_b32_e32 v27, v0
	v_mov_b32_e32 v28, v0
	v_mov_b32_e32 v29, v0
	v_mov_b32_e32 v30, v0
	v_mov_b32_e32 v31, v0
	v_mov_b32_e32 v40, v0
	v_mov_b32_e32 v41, v0
	v_mov_b32_e32 v42, v0
	v_mov_b32_e32 v43, v0
	v_mov_b32_e32 v44, v0
	v_mov_b32_e32 v45, v0
	v_mov_b32_e32 v46, v0
	v_mov_b32_e32 v47, v0
	v_mov_b32_e32 v56, v0
	v_mov_b32_e32 v57, v0
	v_mov_b32_e32 v58, v0
	v_mov_b32_e32 v59, v0
	v_mov_b32_e32 v60, v0
	v_mov_b32_e32 v61, v0
	v_mov_b32_e32 v62, v0
	v_mov_b32_e32 v63, v0
	v_mov_b32_e32 v64, v0
	v_mov_b32_e32 v65, v0
	v_mov_b32_e32 v66, v0
	v_mov_b32_e32 v67, v0
	v_mov_b32_e32 v68, v0
	v_mov_b32_e32 v69, v0
	v_mov_b32_e32 v70, v0
	v_mov_b32_e32 v71, v0
	v_mov_b32_e32 v80, v0
	v_mov_b32_e32 v81, v0
	v_mov_b32_e32 v82, v0
	v_mov_b32_e32 v83, v0
	v_mov_b32_e32 v84, v0
	v_mov_b32_e32 v85, v0
	v_mov_b32_e32 v86, v0
	v_mov_b32_e32 v87, v0
	v_mov_b32_e32 v96, v0
	v_mov_b32_e32 v97, v0
	v_mov_b32_e32 v98, v0
	v_mov_b32_e32 v99, v0
	v_mov_b32_e32 v100, v0
	v_mov_b32_e32 v101, v0
	v_mov_b32_e32 v102, v0
	v_mov_b32_e32 v103, v0
	v_mov_b32_e32 v112, v0
	v_mov_b32_e32 v113, v0
	v_mov_b32_e32 v114, v0
	v_mov_b32_e32 v115, v0
	v_mov_b32_e32 v116, v0
	v_mov_b32_e32 v117, v0
	v_mov_b32_e32 v118, v0
	v_mov_b32_e32 v119, v0
	v_mov_b32_e32 v72, v0
	v_mov_b32_e32 v73, v0
	v_mov_b32_e32 v74, v0
	v_mov_b32_e32 v75, v0
	v_mov_b32_e32 v76, v0
	v_mov_b32_e32 v77, v0
	v_mov_b32_e32 v78, v0
	v_mov_b32_e32 v79, v0
	v_mov_b32_e32 v88, v0
	v_mov_b32_e32 v89, v0
	v_mov_b32_e32 v90, v0
	v_mov_b32_e32 v91, v0
	v_mov_b32_e32 v92, v0
	v_mov_b32_e32 v93, v0
	v_mov_b32_e32 v94, v0
	v_mov_b32_e32 v95, v0
	v_mov_b32_e32 v104, v0
	v_mov_b32_e32 v105, v0
	v_mov_b32_e32 v106, v0
	v_mov_b32_e32 v107, v0
	v_mov_b32_e32 v108, v0
	v_mov_b32_e32 v109, v0
	v_mov_b32_e32 v110, v0
	v_mov_b32_e32 v111, v0
	v_mov_b32_e32 v120, v0
	v_mov_b32_e32 v121, v0
	v_mov_b32_e32 v122, v0
	v_mov_b32_e32 v123, v0
	v_mov_b32_e32 v124, v0
	v_mov_b32_e32 v125, v0
	v_mov_b32_e32 v126, v0
	v_mov_b32_e32 v127, v0
	v_readfirstlane_b32 s98, v254
	s_nop 3
	s_lshr_b32 s98, s98, 8
	s_cmp_eq_u32 s98, 1
	s_cbranch_scc0 .Lsp_4
	s_setprio 1
.Lsp_4:
.LBB0_1242:
	ds_read_b128 v[152:155], v149
	ds_read_b128 v[156:159], v149 offset:1024
	ds_read_b128 v[160:163], v149 offset:2048
	ds_read_b128 v[164:167], v149 offset:3072
	ds_read_b128 v[168:171], v150
	ds_read_b128 v[172:175], v150 offset:1024
	ds_read_b128 v[176:179], v150 offset:2048
	ds_read_b128 v[180:183], v150 offset:3072
	s_add_u32 s2, s36, 0xfffc0080
	s_addc_u32 s3, s37, -1
	s_cmp_eq_u32 s62, 12
	s_cselect_b32 s35, s25, s3
	s_cselect_b32 s34, s58, s2
	s_cselect_b32 s3, s23, s61
	s_cselect_b32 s2, s59, s60
	v_lshl_add_u64 v[144:145], s[36:37], 0, v[136:137]
	s_add_i32 m0, s31, 0xc000
	ds_read_b128 v[184:187], v151
	ds_read_b128 v[188:191], v151 offset:1024
	ds_read_b128 v[194:197], v151 offset:2048
	ds_read_b128 v[198:201], v151 offset:3072
	ds_read_b128 v[202:205], v151 offset:4096
	ds_read_b128 v[206:209], v151 offset:5120
	ds_read_b128 v[210:213], v151 offset:6144
	ds_read_b128 v[214:217], v151 offset:7168
	global_load_lds_dwordx4 v[144:145], off
	v_lshl_add_u64 v[144:145], s[36:37], 0, v[138:139]
	s_add_i32 m0, s31, 0xe000
	s_nop 0
	global_load_lds_dwordx4 v[144:145], off
	s_waitcnt vmcnt(8)
	s_waitcnt lgkmcnt(0)
	s_barrier
; #define PG8_STAGE(bufoff, gbase, voff) do { _Pragma("unroll") for (int _i = 0; _i < 2; ++_i) \
;         __builtin_amdgcn_global_load_lds((const unsigned*)((const char*)(gbase) + (voff)[_i]), (PG8_LAS unsigned*)(lds + (bufoff) + ldsw + _i * 8192), 16, 0, 0); } while (0)
; #define PG8_LDA(dst, b, h) do { _Pragma("unroll") for (int m = 0; m < 4; ++m) _Pragma("unroll") for (int k = 0; k < 2; ++k) dst[m][k] = *(const PG8_LAS bf16x8*)(lds + PG8_SA(b, h) + aoff + m * 2048 + k * 1024); } while (0)
; #define PG8_MMA(ai, bj, At, Bt) do { __builtin_amdgcn_s_setprio(1); _Pragma("unroll") for (int m = 0; m < 4; ++m) _Pragma("unroll") for (int n = 0; n < 2; ++n) _Pragma("unroll") for (int k = 0; k < 2; ++k) \
;         acc[ai][bj][m][n] = __builtin_amdgcn_mfma_f32_16x16x32_bf16(Bt[n][k], At[m][k], acc[ai][bj][m][n], 0, 0, 0); __builtin_amdgcn_s_setprio(0); } while (0)
; #define PG8_WAIT_V(n) asm volatile("s_waitcnt vmcnt(" #n ")" ::: "memory")
; #define PG8_WAIT_L(n) asm volatile("s_waitcnt lgkmcnt(" #n ")" ::: "memory")
; #define PG8_BAR __builtin_amdgcn_s_barrier()
; #define PG8_SCHED __builtin_amdgcn_sched_barrier(0)
; template <class Epi, class Sched, bool ALIGN_EPI = false, bool SP2 = false>
; __device__ __forceinline__ void gemm_phase(PG8_LAS unsigned char* lds, const Gemm g, const Sched& S, const Epi& E) {
;     ...
;             PG8_WAIT_V(8); PG8_WAIT_L(0); PG8_BAR; PG8_MMA(0, 0, At, B0); PG8_MMA(0, 1, At, B1); PG8_BAR; PG8_SCHED;
;             PG8_LDA(At, 0, 1); PG8_STAGE(PG8_SB(0, 0), b2, voffB); PG8_STAGE(PG8_SB(0, 1), b2 + hstep, voffB); PG8_STAGE(PG8_SA(0, 0), a2, voffA);
;             PG8_WAIT_V(8); PG8_WAIT_L(0); PG8_BAR; PG8_MMA(1, 0, At, B0); PG8_MMA(1, 1, At, B1); PG8_BAR; PG8_SCHED;
	s_waitcnt lgkmcnt(0)
	v_mfma_f32_16x16x32_bf16 v[124:127], v[152:155], v[184:187], v[124:127]
	v_mfma_f32_16x16x32_bf16 v[120:123], v[160:163], v[184:187], v[120:123]
	v_mfma_f32_16x16x32_bf16 v[108:111], v[152:155], v[194:197], v[108:111]
	v_mfma_f32_16x16x32_bf16 v[104:107], v[160:163], v[194:197], v[104:107]
	v_mfma_f32_16x16x32_bf16 v[92:95], v[152:155], v[202:205], v[92:95]
	v_mfma_f32_16x16x32_bf16 v[88:91], v[160:163], v[202:205], v[88:91]
	v_mfma_f32_16x16x32_bf16 v[76:79], v[152:155], v[210:213], v[76:79]
	v_mfma_f32_16x16x32_bf16 v[72:75], v[160:163], v[210:213], v[72:75]
	v_mfma_f32_16x16x32_bf16 v[124:127], v[156:159], v[188:191], v[124:127]
	v_mfma_f32_16x16x32_bf16 v[120:123], v[164:167], v[188:191], v[120:123]
	v_mfma_f32_16x16x32_bf16 v[108:111], v[156:159], v[198:201], v[108:111]
	v_mfma_f32_16x16x32_bf16 v[104:107], v[164:167], v[198:201], v[104:107]
	v_mfma_f32_16x16x32_bf16 v[92:95], v[156:159], v[206:209], v[92:95]
	v_mfma_f32_16x16x32_bf16 v[88:91], v[164:167], v[206:209], v[88:91]
	v_mfma_f32_16x16x32_bf16 v[76:79], v[156:159], v[214:217], v[76:79]
	v_mfma_f32_16x16x32_bf16 v[72:75], v[164:167], v[214:217], v[72:75]
	v_mfma_f32_16x16x32_bf16 v[116:119], v[168:171], v[184:187], v[116:119]
	v_mfma_f32_16x16x32_bf16 v[112:115], v[176:179], v[184:187], v[112:115]
	v_mfma_f32_16x16x32_bf16 v[100:103], v[168:171], v[194:197], v[100:103]
	v_mfma_f32_16x16x32_bf16 v[96:99], v[176:179], v[194:197], v[96:99]
	v_mfma_f32_16x16x32_bf16 v[84:87], v[168:171], v[202:205], v[84:87]
	v_mfma_f32_16x16x32_bf16 v[80:83], v[176:179], v[202:205], v[80:83]
	v_mfma_f32_16x16x32_bf16 v[68:71], v[168:171], v[210:213], v[68:71]
	v_mfma_f32_16x16x32_bf16 v[64:67], v[176:179], v[210:213], v[64:67]
	v_mfma_f32_16x16x32_bf16 v[116:119], v[172:175], v[188:191], v[116:119]
	v_mfma_f32_16x16x32_bf16 v[112:115], v[180:183], v[188:191], v[112:115]
	v_mfma_f32_16x16x32_bf16 v[100:103], v[172:175], v[198:201], v[100:103]
	v_mfma_f32_16x16x32_bf16 v[96:99], v[180:183], v[198:201], v[96:99]
	v_mfma_f32_16x16x32_bf16 v[84:87], v[172:175], v[206:209], v[84:87]
	v_mfma_f32_16x16x32_bf16 v[80:83], v[180:183], v[206:209], v[80:83]
	v_mfma_f32_16x16x32_bf16 v[68:71], v[172:175], v[214:217], v[68:71]
	v_mfma_f32_16x16x32_bf16 v[64:67], v[180:183], v[214:217], v[64:67]
	s_barrier
	s_add_i32 s63, s51, s41
	v_lshl_add_u64 v[144:145], s[2:3], 0, v[130:131]
	s_mov_b32 m0, s63
	ds_read_b128 v[184:187], v151 offset:16384
	ds_read_b128 v[188:191], v151 offset:17408
	ds_read_b128 v[194:197], v151 offset:18432
	ds_read_b128 v[198:201], v151 offset:19456
	ds_read_b128 v[202:205], v151 offset:20480
	ds_read_b128 v[206:209], v151 offset:21504
	ds_read_b128 v[210:213], v151 offset:22528
	ds_read_b128 v[214:217], v151 offset:23552
	global_load_lds_dwordx4 v[144:145], off
	s_add_i32 m0, s63, 0x2000
	s_add_u32 s64, s2, 0x40000
	v_lshl_add_u64 v[192:193], s[2:3], 0, v[134:135]
	s_addc_u32 s65, s3, 0
	s_add_i32 s63, s52, s41
	global_load_lds_dwordx4 v[192:193], off
	v_lshl_add_u64 v[218:219], s[64:65], 0, v[130:131]
	s_mov_b32 m0, s63
	v_lshl_add_u64 v[220:221], s[34:35], 0, v[132:133]
	global_load_lds_dwordx4 v[218:219], off
	v_lshl_add_u64 v[218:219], s[64:65], 0, v[134:135]
	s_add_i32 m0, s63, 0x2000
	s_nop 0
	global_load_lds_dwordx4 v[218:219], off
	v_lshl_add_u64 v[218:219], s[34:35], 0, v[128:129]
	s_mov_b32 m0, s31
	s_nop 0
	global_load_lds_dwordx4 v[218:219], off
	s_mov_b32 m0, s44
	s_nop 0
	global_load_lds_dwordx4 v[220:221], off
	s_waitcnt vmcnt(8)
	s_waitcnt lgkmcnt(0)
	s_barrier
	s_waitcnt lgkmcnt(0)
	v_mfma_f32_16x16x32_bf16 v[60:63], v[152:155], v[184:187], v[60:63]
	v_mfma_f32_16x16x32_bf16 v[56:59], v[160:163], v[184:187], v[56:59]
	v_mfma_f32_16x16x32_bf16 v[44:47], v[152:155], v[194:197], v[44:47]
	v_mfma_f32_16x16x32_bf16 v[40:43], v[160:163], v[194:197], v[40:43]
	v_mfma_f32_16x16x32_bf16 v[28:31], v[152:155], v[202:205], v[28:31]
	v_mfma_f32_16x16x32_bf16 v[24:27], v[160:163], v[202:205], v[24:27]
	v_mfma_f32_16x16x32_bf16 v[12:15], v[152:155], v[210:213], v[12:15]
	v_mfma_f32_16x16x32_bf16 v[8:11], v[160:163], v[210:213], v[8:11]
	v_mfma_f32_16x16x32_bf16 v[60:63], v[156:159], v[188:191], v[60:63]
	v_mfma_f32_16x16x32_bf16 v[56:59], v[164:167], v[188:191], v[56:59]
	v_mfma_f32_16x16x32_bf16 v[44:47], v[156:159], v[198:201], v[44:47]
	v_mfma_f32_16x16x32_bf16 v[40:43], v[164:167], v[198:201], v[40:43]
	v_mfma_f32_16x16x32_bf16 v[28:31], v[156:159], v[206:209], v[28:31]
	v_mfma_f32_16x16x32_bf16 v[24:27], v[164:167], v[206:209], v[24:27]
	v_mfma_f32_16x16x32_bf16 v[12:15], v[156:159], v[214:217], v[12:15]
	v_mfma_f32_16x16x32_bf16 v[8:11], v[164:167], v[214:217], v[8:11]
	v_mfma_f32_16x16x32_bf16 v[52:55], v[168:171], v[184:187], v[52:55]
	v_mfma_f32_16x16x32_bf16 v[48:51], v[176:179], v[184:187], v[48:51]
	v_mfma_f32_16x16x32_bf16 v[36:39], v[168:171], v[194:197], v[36:39]
	v_mfma_f32_16x16x32_bf16 v[32:35], v[176:179], v[194:197], v[32:35]
	v_mfma_f32_16x16x32_bf16 v[20:23], v[168:171], v[202:205], v[20:23]
	v_mfma_f32_16x16x32_bf16 v[16:19], v[176:179], v[202:205], v[16:19]
	v_mfma_f32_16x16x32_bf16 v[4:7], v[168:171], v[210:213], v[4:7]
	v_mfma_f32_16x16x32_bf16 v[0:3], v[176:179], v[210:213], v[0:3]
	v_mfma_f32_16x16x32_bf16 v[52:55], v[172:175], v[188:191], v[52:55]
	v_mfma_f32_16x16x32_bf16 v[48:51], v[180:183], v[188:191], v[48:51]
	v_mfma_f32_16x16x32_bf16 v[36:39], v[172:175], v[198:201], v[36:39]
	v_mfma_f32_16x16x32_bf16 v[32:35], v[180:183], v[198:201], v[32:35]
	v_mfma_f32_16x16x32_bf16 v[20:23], v[172:175], v[206:209], v[20:23]
	v_mfma_f32_16x16x32_bf16 v[16:19], v[180:183], v[206:209], v[16:19]
	v_mfma_f32_16x16x32_bf16 v[4:7], v[172:175], v[214:217], v[4:7]
	v_mfma_f32_16x16x32_bf16 v[0:3], v[180:183], v[214:217], v[0:3]
	s_barrier
; #define PG8_STAGE(bufoff, gbase, voff) do { _Pragma("unroll") for (int _i = 0; _i < 2; ++_i) \
;         __builtin_amdgcn_global_load_lds((const unsigned*)((const char*)(gbase) + (voff)[_i]), (PG8_LAS unsigned*)(lds + (bufoff) + ldsw + _i * 8192), 16, 0, 0); } while (0)
; #define PG8_LDA(dst, b, h) do { _Pragma("unroll") for (int m = 0; m < 4; ++m) _Pragma("unroll") for (int k = 0; k < 2; ++k) dst[m][k] = *(const PG8_LAS bf16x8*)(lds + PG8_SA(b, h) + aoff + m * 2048 + k * 1024); } while (0)
; #define PG8_LDB(dst, b, h) do { _Pragma("unroll") for (int n = 0; n < 2; ++n) _Pragma("unroll") for (int k = 0; k < 2; ++k) dst[n][k] = *(const PG8_LAS bf16x8*)(lds + PG8_SB(b, h) + boff + n * 2048 + k * 1024); } while (0)
; #define PG8_MMA(ai, bj, At, Bt) do { __builtin_amdgcn_s_setprio(1); _Pragma("unroll") for (int m = 0; m < 4; ++m) _Pragma("unroll") for (int n = 0; n < 2; ++n) _Pragma("unroll") for (int k = 0; k < 2; ++k) \
;         acc[ai][bj][m][n] = __builtin_amdgcn_mfma_f32_16x16x32_bf16(Bt[n][k], At[m][k], acc[ai][bj][m][n], 0, 0, 0); __builtin_amdgcn_s_setprio(0); } while (0)
; #define PG8_WAIT_V(n) asm volatile("s_waitcnt vmcnt(" #n ")" ::: "memory")
; #define PG8_WAIT_L(n) asm volatile("s_waitcnt lgkmcnt(" #n ")" ::: "memory")
; #define PG8_BAR __builtin_amdgcn_s_barrier()
; #define PG8_SCHED __builtin_amdgcn_sched_barrier(0)
; template <class Epi, class Sched, bool ALIGN_EPI = false, bool SP2 = false>
; __device__ __forceinline__ void gemm_phase(PG8_LAS unsigned char* lds, const Gemm g, const Sched& S, const Epi& E) {
;     ...
;             PG8_LDB(B0, 1, 0); PG8_LDB(B1, 1, 1); PG8_SCHED; PG8_LDA(At, 1, 0); PG8_STAGE(PG8_SA(0, 1), a2 + hstep, voffA);
;             PG8_WAIT_V(8); PG8_WAIT_L(0); PG8_BAR; PG8_MMA(0, 0, At, B0); PG8_MMA(0, 1, At, B1); PG8_BAR; PG8_SCHED;
	s_add_i32 s63, 0, 0x18000
	s_add_i32 s64, 0, 0x1c000
	v_add_u32_e32 v164, s63, v147
	v_add_u32_e32 v180, s64, v147
	ds_read_b128 v[152:155], v164
	ds_read_b128 v[156:159], v164 offset:1024
	ds_read_b128 v[160:163], v164 offset:2048
	ds_read_b128 v[164:167], v164 offset:3072
	ds_read_b128 v[168:171], v180
	ds_read_b128 v[172:175], v180 offset:1024
	ds_read_b128 v[176:179], v180 offset:2048
	ds_read_b128 v[180:183], v180 offset:3072
	s_add_u32 s34, s34, 0x40000
	s_addc_u32 s35, s35, 0
	s_mov_b32 m0, s45
	v_lshl_add_u64 v[222:223], s[34:35], 0, v[128:129]
	ds_read_b128 v[184:187], v151 offset:32768
	ds_read_b128 v[188:191], v151 offset:33792
	ds_read_b128 v[194:197], v151 offset:34816
	ds_read_b128 v[198:201], v151 offset:35840
	ds_read_b128 v[202:205], v151 offset:36864
	ds_read_b128 v[206:209], v151 offset:37888
	ds_read_b128 v[210:213], v151 offset:38912
	ds_read_b128 v[214:217], v151 offset:39936
	global_load_lds_dwordx4 v[222:223], off
	v_lshl_add_u64 v[222:223], s[34:35], 0, v[132:133]
	s_mov_b32 m0, s46
	s_nop 0
	global_load_lds_dwordx4 v[222:223], off
	s_waitcnt vmcnt(8)
	s_waitcnt lgkmcnt(0)
	s_barrier
	s_waitcnt lgkmcnt(0)
	v_mfma_f32_16x16x32_bf16 v[124:127], v[152:155], v[184:187], v[124:127]
	v_mfma_f32_16x16x32_bf16 v[120:123], v[160:163], v[184:187], v[120:123]
	v_mfma_f32_16x16x32_bf16 v[108:111], v[152:155], v[194:197], v[108:111]
	v_mfma_f32_16x16x32_bf16 v[104:107], v[160:163], v[194:197], v[104:107]
	v_mfma_f32_16x16x32_bf16 v[92:95], v[152:155], v[202:205], v[92:95]
	v_mfma_f32_16x16x32_bf16 v[88:91], v[160:163], v[202:205], v[88:91]
	v_mfma_f32_16x16x32_bf16 v[76:79], v[152:155], v[210:213], v[76:79]
	v_mfma_f32_16x16x32_bf16 v[72:75], v[160:163], v[210:213], v[72:75]
	v_mfma_f32_16x16x32_bf16 v[124:127], v[156:159], v[188:191], v[124:127]
	v_mfma_f32_16x16x32_bf16 v[120:123], v[164:167], v[188:191], v[120:123]
	v_mfma_f32_16x16x32_bf16 v[108:111], v[156:159], v[198:201], v[108:111]
	v_mfma_f32_16x16x32_bf16 v[104:107], v[164:167], v[198:201], v[104:107]
	v_mfma_f32_16x16x32_bf16 v[92:95], v[156:159], v[206:209], v[92:95]
	v_mfma_f32_16x16x32_bf16 v[88:91], v[164:167], v[206:209], v[88:91]
	v_mfma_f32_16x16x32_bf16 v[76:79], v[156:159], v[214:217], v[76:79]
	v_mfma_f32_16x16x32_bf16 v[72:75], v[164:167], v[214:217], v[72:75]
	v_mfma_f32_16x16x32_bf16 v[116:119], v[168:171], v[184:187], v[116:119]
	v_mfma_f32_16x16x32_bf16 v[112:115], v[176:179], v[184:187], v[112:115]
	v_mfma_f32_16x16x32_bf16 v[100:103], v[168:171], v[194:197], v[100:103]
	v_mfma_f32_16x16x32_bf16 v[96:99], v[176:179], v[194:197], v[96:99]
	v_mfma_f32_16x16x32_bf16 v[84:87], v[168:171], v[202:205], v[84:87]
	v_mfma_f32_16x16x32_bf16 v[80:83], v[176:179], v[202:205], v[80:83]
	v_mfma_f32_16x16x32_bf16 v[68:71], v[168:171], v[210:213], v[68:71]
	v_mfma_f32_16x16x32_bf16 v[64:67], v[176:179], v[210:213], v[64:67]
	v_mfma_f32_16x16x32_bf16 v[116:119], v[172:175], v[188:191], v[116:119]
	v_mfma_f32_16x16x32_bf16 v[112:115], v[180:183], v[188:191], v[112:115]
	v_mfma_f32_16x16x32_bf16 v[100:103], v[172:175], v[198:201], v[100:103]
	v_mfma_f32_16x16x32_bf16 v[96:99], v[180:183], v[198:201], v[96:99]
	v_mfma_f32_16x16x32_bf16 v[84:87], v[172:175], v[206:209], v[84:87]
	v_mfma_f32_16x16x32_bf16 v[80:83], v[180:183], v[206:209], v[80:83]
	v_mfma_f32_16x16x32_bf16 v[68:71], v[172:175], v[214:217], v[68:71]
	v_mfma_f32_16x16x32_bf16 v[64:67], v[180:183], v[214:217], v[64:67]
	s_barrier
; #define PG8_STAGE(bufoff, gbase, voff) do { _Pragma("unroll") for (int _i = 0; _i < 2; ++_i) \
;         __builtin_amdgcn_global_load_lds((const unsigned*)((const char*)(gbase) + (voff)[_i]), (PG8_LAS unsigned*)(lds + (bufoff) + ldsw + _i * 8192), 16, 0, 0); } while (0)
; #define PG8_LDA(dst, b, h) do { _Pragma("unroll") for (int m = 0; m < 4; ++m) _Pragma("unroll") for (int k = 0; k < 2; ++k) dst[m][k] = *(const PG8_LAS bf16x8*)(lds + PG8_SA(b, h) + aoff + m * 2048 + k * 1024); } while (0)
; #define PG8_MMA(ai, bj, At, Bt) do { __builtin_amdgcn_s_setprio(1); _Pragma("unroll") for (int m = 0; m < 4; ++m) _Pragma("unroll") for (int n = 0; n < 2; ++n) _Pragma("unroll") for (int k = 0; k < 2; ++k) \
;         acc[ai][bj][m][n] = __builtin_amdgcn_mfma_f32_16x16x32_bf16(Bt[n][k], At[m][k], acc[ai][bj][m][n], 0, 0, 0); __builtin_amdgcn_s_setprio(0); } while (0)
; #define PG8_WAIT_V(n) asm volatile("s_waitcnt vmcnt(" #n ")" ::: "memory")
; #define PG8_WAIT_L(n) asm volatile("s_waitcnt lgkmcnt(" #n ")" ::: "memory")
; #define PG8_BAR __builtin_amdgcn_s_barrier()
; #define PG8_SCHED __builtin_amdgcn_sched_barrier(0)
; template <class Epi, class Sched, bool ALIGN_EPI = false, bool SP2 = false>
; __device__ __forceinline__ void gemm_phase(PG8_LAS unsigned char* lds, const Gemm g, const Sched& S, const Epi& E) {
;     ...
;         for (int t = 0; t < nt; t += 2) {
;     ...
;             PG8_LDA(At, 1, 1); PG8_STAGE(PG8_SB(1, 0), b3, voffB); PG8_STAGE(PG8_SB(1, 1), b3 + hstep, voffB); PG8_STAGE(PG8_SA(1, 0), a3, voffA);
;             PG8_WAIT_V(8); PG8_WAIT_L(0); PG8_BAR; PG8_MMA(1, 0, At, B0); PG8_MMA(1, 1, At, B1); PG8_BAR; PG8_SCHED;
	s_add_i32 s34, s63, s41
	v_lshl_add_u64 v[144:145], v[144:145], 0, s[10:11]
	s_mov_b32 m0, s34
	ds_read_b128 v[184:187], v151 offset:49152
	ds_read_b128 v[188:191], v151 offset:50176
	ds_read_b128 v[194:197], v151 offset:51200
	ds_read_b128 v[198:201], v151 offset:52224
	ds_read_b128 v[202:205], v151 offset:53248
	ds_read_b128 v[206:209], v151 offset:54272
	ds_read_b128 v[210:213], v151 offset:55296
	ds_read_b128 v[214:217], v151 offset:56320
	global_load_lds_dwordx4 v[144:145], off
	s_add_i32 m0, s34, 0x2000
	s_add_u32 s2, s2, 0x40080
	v_lshl_add_u64 v[144:145], v[192:193], 0, s[10:11]
	s_addc_u32 s3, s3, 0
	s_add_i32 s34, s64, s41
	global_load_lds_dwordx4 v[144:145], off
	v_lshl_add_u64 v[144:145], s[2:3], 0, v[130:131]
	s_mov_b32 m0, s34
	s_nop 0
	global_load_lds_dwordx4 v[144:145], off
	v_lshl_add_u64 v[144:145], s[2:3], 0, v[134:135]
	s_add_i32 m0, s34, 0x2000
	s_nop 0
	global_load_lds_dwordx4 v[144:145], off
	v_lshl_add_u64 v[144:145], v[218:219], 0, s[10:11]
	s_mov_b32 m0, s49
	s_nop 0
	global_load_lds_dwordx4 v[144:145], off
	v_lshl_add_u64 v[144:145], v[220:221], 0, s[10:11]
	s_mov_b32 m0, s50
	s_nop 0
	global_load_lds_dwordx4 v[144:145], off
	s_waitcnt vmcnt(8)
	s_waitcnt lgkmcnt(0)
	s_barrier
	s_waitcnt lgkmcnt(0)
	v_mfma_f32_16x16x32_bf16 v[60:63], v[152:155], v[184:187], v[60:63]
	v_mfma_f32_16x16x32_bf16 v[56:59], v[160:163], v[184:187], v[56:59]
	v_mfma_f32_16x16x32_bf16 v[44:47], v[152:155], v[194:197], v[44:47]
	v_mfma_f32_16x16x32_bf16 v[40:43], v[160:163], v[194:197], v[40:43]
	v_mfma_f32_16x16x32_bf16 v[28:31], v[152:155], v[202:205], v[28:31]
	v_mfma_f32_16x16x32_bf16 v[24:27], v[160:163], v[202:205], v[24:27]
	v_mfma_f32_16x16x32_bf16 v[12:15], v[152:155], v[210:213], v[12:15]
	v_mfma_f32_16x16x32_bf16 v[8:11], v[160:163], v[210:213], v[8:11]
	v_mfma_f32_16x16x32_bf16 v[60:63], v[156:159], v[188:191], v[60:63]
	v_mfma_f32_16x16x32_bf16 v[56:59], v[164:167], v[188:191], v[56:59]
	v_mfma_f32_16x16x32_bf16 v[44:47], v[156:159], v[198:201], v[44:47]
	v_mfma_f32_16x16x32_bf16 v[40:43], v[164:167], v[198:201], v[40:43]
	v_mfma_f32_16x16x32_bf16 v[28:31], v[156:159], v[206:209], v[28:31]
	v_mfma_f32_16x16x32_bf16 v[24:27], v[164:167], v[206:209], v[24:27]
	v_mfma_f32_16x16x32_bf16 v[12:15], v[156:159], v[214:217], v[12:15]
	v_mfma_f32_16x16x32_bf16 v[8:11], v[164:167], v[214:217], v[8:11]
	v_mfma_f32_16x16x32_bf16 v[52:55], v[168:171], v[184:187], v[52:55]
	v_mfma_f32_16x16x32_bf16 v[48:51], v[176:179], v[184:187], v[48:51]
	v_mfma_f32_16x16x32_bf16 v[36:39], v[168:171], v[194:197], v[36:39]
	v_mfma_f32_16x16x32_bf16 v[32:35], v[176:179], v[194:197], v[32:35]
	v_mfma_f32_16x16x32_bf16 v[20:23], v[168:171], v[202:205], v[20:23]
	v_mfma_f32_16x16x32_bf16 v[16:19], v[176:179], v[202:205], v[16:19]
	v_mfma_f32_16x16x32_bf16 v[4:7], v[168:171], v[210:213], v[4:7]
	v_mfma_f32_16x16x32_bf16 v[0:3], v[176:179], v[210:213], v[0:3]
	v_mfma_f32_16x16x32_bf16 v[52:55], v[172:175], v[188:191], v[52:55]
	v_mfma_f32_16x16x32_bf16 v[48:51], v[180:183], v[188:191], v[48:51]
	v_mfma_f32_16x16x32_bf16 v[36:39], v[172:175], v[198:201], v[36:39]
	v_mfma_f32_16x16x32_bf16 v[32:35], v[180:183], v[198:201], v[32:35]
	v_mfma_f32_16x16x32_bf16 v[20:23], v[172:175], v[206:209], v[20:23]
	v_mfma_f32_16x16x32_bf16 v[16:19], v[180:183], v[206:209], v[16:19]
	v_mfma_f32_16x16x32_bf16 v[4:7], v[172:175], v[214:217], v[4:7]
	v_mfma_f32_16x16x32_bf16 v[0:3], v[180:183], v[214:217], v[0:3]
	s_barrier
	s_add_i32 s62, s62, 2
	s_add_u32 s36, s36, 0x100
	s_addc_u32 s37, s37, 0
	s_add_u32 s60, s60, 0x100
	s_addc_u32 s61, s61, 0
	s_cmp_gt_u32 s62, 13
	s_cbranch_scc0 .LBB0_1242
	s_setprio 0
	s_and_b64 vcc, exec, s[12:13]
	s_cbranch_vccz .LBB0_1245
	s_barrier

; #define PG8_STAGE(bufoff, gbase, voff) do { _Pragma("unroll") for (int _i = 0; _i < 2; ++_i) \
;         __builtin_amdgcn_global_load_lds((const unsigned*)((const char*)(gbase) + (voff)[_i]), (PG8_LAS unsigned*)(lds + (bufoff) + ldsw + _i * 8192), 16, 0, 0); } while (0)
; #define PG8_LDA(dst, b, h) do { _Pragma("unroll") for (int m = 0; m < 4; ++m) _Pragma("unroll") for (int k = 0; k < 2; ++k) dst[m][k] = *(const PG8_LAS bf16x8*)(lds + PG8_SA(b, h) + aoff + m * 2048 + k * 1024); } while (0)
; #define PG8_LDB(dst, b, h) do { _Pragma("unroll") for (int n = 0; n < 2; ++n) _Pragma("unroll") for (int k = 0; k < 2; ++k) dst[n][k] = *(const PG8_LAS bf16x8*)(lds + PG8_SB(b, h) + boff + n * 2048 + k * 1024); } while (0)
; #define PG8_WAIT_V(n) asm volatile("s_waitcnt vmcnt(" #n ")" ::: "memory")
; #define PG8_WAIT_L(n) asm volatile("s_waitcnt lgkmcnt(" #n ")" ::: "memory")
; #define PG8_BAR __builtin_amdgcn_s_barrier()
; template <class Epi, class Sched, bool ALIGN_EPI = false, bool SP2 = false>
; __device__ __forceinline__ void gemm_phase(PG8_LAS unsigned char* lds, const Gemm g, const Sched& S, const Epi& E) {
;     ...
;         const bool has_next = S.next(ui + 1, nxt);
;         const char* nA = has_next ? (const char*)g.A + (size_t)nxt.pm * tstep : cA; const char* nB = has_next ? (const char*)g.Bt + (size_t)nxt.pn * tstep : cB;
;         for (int t = 0; t < nt; t += 2) {
;             const bool last = (t == nt - 2);
;             const char* a1 = cA + (size_t)(t + 1) * kstep;
;             const char* a2 = last ? nA : cA + (size_t)(t + 2) * kstep; const char* b2 = last ? nB : cB + (size_t)(t + 2) * kstep;
;             const char* a3 = a2 + kstep; const char* b3 = b2 + kstep;
;             if (last && has_next) S.a_ready(nxt);
;             if constexpr (SP2) {
;             PG8_LDB(B0, 0, 0); PG8_LDB(B1, 0, 1); PG8_SCHED; PG8_LDA(At, 0, 0); PG8_STAGE(PG8_SA(1, 1), a1 + hstep, voffA);
;             PG8_WAIT_V(8); PG8_WAIT_L(0); PG8_BAR; PG8_MMA(0, 0, At, B0); PG8_MMA(0, 1, At, B1); PG8_BAR; PG8_SCHED;
;     ...
; #pragma unroll
;         for (int a = 0; a < 2; ++a)
; #pragma unroll
;             for (int b = 0; b < 2; ++b)
; #pragma unroll
;                 for (int m = 0; m < 4; ++m)
; #pragma unroll
;                     for (int n = 0; n < 2; ++n) acc[a][b][m][n] = (f32x4){0.f, 0.f, 0.f, 0.f};
;         cur = nxt; cA = nA; cB = nB; ++ui;
.LBB0_1312:
	s_ashr_i32 s19, s18, 31
	s_lshl_b64 s[20:21], s[18:19], 21
	s_add_u32 s20, s33, s20
	s_addc_u32 s21, s34, s21
	s_and_b64 s[22:23], s[6:7], exec
	s_cselect_b32 s19, s21, s27
	s_cselect_b32 s50, s20, s26
	s_ashr_i32 s17, s16, 31
	s_lshl_b64 s[22:23], s[16:17], 21
	s_add_u32 s22, s30, s22
	s_addc_u32 s23, s31, s23
	s_and_b64 s[28:29], s[6:7], exec
	s_cselect_b32 s17, s23, s3
	s_cselect_b32 s51, s22, s2
	s_add_u32 s26, s26, 0x100080
	s_addc_u32 s27, s27, 0
	s_add_u32 s52, s2, 0x100
	v_mov_b32_e32 v0, 0
	s_addc_u32 s53, s3, 0
	s_mov_b32 s54, -2
	v_mov_b32_e32 v1, v0
	v_mov_b32_e32 v2, v0
	v_mov_b32_e32 v3, v0
	v_mov_b32_e32 v4, v0
	v_mov_b32_e32 v5, v0
	v_mov_b32_e32 v6, v0
	v_mov_b32_e32 v7, v0
	v_mov_b32_e32 v12, v0
	v_mov_b32_e32 v13, v0
	v_mov_b32_e32 v14, v0
	v_mov_b32_e32 v15, v0
	v_mov_b32_e32 v20, v0
	v_mov_b32_e32 v21, v0
	v_mov_b32_e32 v22, v0
	v_mov_b32_e32 v23, v0
	v_mov_b32_e32 v28, v0
	v_mov_b32_e32 v29, v0
	v_mov_b32_e32 v30, v0
	v_mov_b32_e32 v31, v0
	v_mov_b32_e32 v36, v0
	v_mov_b32_e32 v37, v0
	v_mov_b32_e32 v38, v0
	v_mov_b32_e32 v39, v0
	v_mov_b32_e32 v44, v0
	v_mov_b32_e32 v45, v0
	v_mov_b32_e32 v46, v0
	v_mov_b32_e32 v47, v0
	v_mov_b32_e32 v52, v0
	v_mov_b32_e32 v53, v0
	v_mov_b32_e32 v54, v0
	v_mov_b32_e32 v55, v0
	v_mov_b32_e32 v8, v0
	v_mov_b32_e32 v9, v0
	v_mov_b32_e32 v10, v0
	v_mov_b32_e32 v11, v0
	v_mov_b32_e32 v16, v0
	v_mov_b32_e32 v17, v0
	v_mov_b32_e32 v18, v0
	v_mov_b32_e32 v19, v0
	v_mov_b32_e32 v24, v0
	v_mov_b32_e32 v25, v0
	v_mov_b32_e32 v26, v0
	v_mov_b32_e32 v27, v0
	v_mov_b32_e32 v32, v0
	v_mov_b32_e32 v33, v0
	v_mov_b32_e32 v34, v0
	v_mov_b32_e32 v35, v0
	v_mov_b32_e32 v40, v0
	v_mov_b32_e32 v41, v0
	v_mov_b32_e32 v42, v0
	v_mov_b32_e32 v43, v0
	v_mov_b32_e32 v48, v0
	v_mov_b32_e32 v49, v0
	v_mov_b32_e32 v50, v0
	v_mov_b32_e32 v51, v0
	v_mov_b32_e32 v56, v0
	v_mov_b32_e32 v57, v0
	v_mov_b32_e32 v58, v0
	v_mov_b32_e32 v59, v0
	v_mov_b32_e32 v60, v0
	v_mov_b32_e32 v61, v0
	v_mov_b32_e32 v62, v0
	v_mov_b32_e32 v63, v0
	v_mov_b32_e32 v64, v0
	v_mov_b32_e32 v65, v0
	v_mov_b32_e32 v66, v0
	v_mov_b32_e32 v67, v0
	v_mov_b32_e32 v68, v0
	v_mov_b32_e32 v69, v0
	v_mov_b32_e32 v70, v0
	v_mov_b32_e32 v71, v0
	v_mov_b32_e32 v76, v0
	v_mov_b32_e32 v77, v0
	v_mov_b32_e32 v78, v0
	v_mov_b32_e32 v79, v0
	v_mov_b32_e32 v84, v0
	v_mov_b32_e32 v85, v0
	v_mov_b32_e32 v86, v0
	v_mov_b32_e32 v87, v0
	v_mov_b32_e32 v92, v0
	v_mov_b32_e32 v93, v0
	v_mov_b32_e32 v94, v0
	v_mov_b32_e32 v95, v0
	v_mov_b32_e32 v100, v0
	v_mov_b32_e32 v101, v0
	v_mov_b32_e32 v102, v0
	v_mov_b32_e32 v103, v0
	v_mov_b32_e32 v104, v0
	v_mov_b32_e32 v105, v0
	v_mov_b32_e32 v106, v0
	v_mov_b32_e32 v107, v0
	v_mov_b32_e32 v112, v0
	v_mov_b32_e32 v113, v0
	v_mov_b32_e32 v114, v0
	v_mov_b32_e32 v115, v0
	v_mov_b32_e32 v72, v0
	v_mov_b32_e32 v73, v0
	v_mov_b32_e32 v74, v0
	v_mov_b32_e32 v75, v0
	v_mov_b32_e32 v80, v0
	v_mov_b32_e32 v81, v0
	v_mov_b32_e32 v82, v0
	v_mov_b32_e32 v83, v0
	v_mov_b32_e32 v88, v0
	v_mov_b32_e32 v89, v0
	v_mov_b32_e32 v90, v0
	v_mov_b32_e32 v91, v0
	v_mov_b32_e32 v96, v0
	v_mov_b32_e32 v97, v0
	v_mov_b32_e32 v98, v0
	v_mov_b32_e32 v99, v0
	v_mov_b32_e32 v108, v0
	v_mov_b32_e32 v109, v0
	v_mov_b32_e32 v110, v0
	v_mov_b32_e32 v111, v0
	v_mov_b32_e32 v116, v0
	v_mov_b32_e32 v117, v0
	v_mov_b32_e32 v118, v0
	v_mov_b32_e32 v119, v0
	v_mov_b32_e32 v120, v0
	v_mov_b32_e32 v121, v0
	v_mov_b32_e32 v122, v0
	v_mov_b32_e32 v123, v0
	v_mov_b32_e32 v124, v0
	v_mov_b32_e32 v125, v0
	v_mov_b32_e32 v126, v0
	v_mov_b32_e32 v127, v0
	v_readfirstlane_b32 s98, v254
	s_nop 3
	s_lshr_b32 s98, s98, 8
	s_cmp_eq_u32 s98, 1
	s_cbranch_scc0 .Lsp_5
	s_setprio 1
.Lsp_5:
.LBB0_1313:
	ds_read_b128 v[128:131], v167
	ds_read_b128 v[132:135], v167 offset:1024
	ds_read_b128 v[136:139], v167 offset:2048
	ds_read_b128 v[140:143], v167 offset:3072
	ds_read_b128 v[156:159], v168
	ds_read_b128 v[160:163], v168 offset:1024
	ds_read_b128 v[170:173], v168 offset:2048
	ds_read_b128 v[174:177], v168 offset:3072
	s_add_u32 s2, s26, 0xfff00080
	s_addc_u32 s3, s27, -1
	s_cmp_eq_u32 s54, 60
	s_cselect_b32 s29, s19, s3
	s_cselect_b32 s28, s50, s2
	s_cselect_b32 s3, s17, s53
	s_cselect_b32 s2, s51, s52
	v_lshl_add_u64 v[190:191], s[26:27], 0, v[148:149]
	s_add_i32 m0, s25, 0xc000
	ds_read_b128 v[178:181], v169
	ds_read_b128 v[182:185], v169 offset:1024
	ds_read_b128 v[186:189], v169 offset:2048
	ds_read_b128 v[194:197], v169 offset:3072
	ds_read_b128 v[198:201], v169 offset:4096
	ds_read_b128 v[202:205], v169 offset:5120
	ds_read_b128 v[206:209], v169 offset:6144
	ds_read_b128 v[210:213], v169 offset:7168
	global_load_lds_dwordx4 v[190:191], off
	v_lshl_add_u64 v[190:191], s[26:27], 0, v[150:151]
	s_add_i32 m0, s25, 0xe000
	s_nop 0
	global_load_lds_dwordx4 v[190:191], off
	s_waitcnt vmcnt(8)
	s_waitcnt lgkmcnt(0)
	s_barrier
; #define PG8_STAGE(bufoff, gbase, voff) do { _Pragma("unroll") for (int _i = 0; _i < 2; ++_i) \
;         __builtin_amdgcn_global_load_lds((const unsigned*)((const char*)(gbase) + (voff)[_i]), (PG8_LAS unsigned*)(lds + (bufoff) + ldsw + _i * 8192), 16, 0, 0); } while (0)
; #define PG8_LDA(dst, b, h) do { _Pragma("unroll") for (int m = 0; m < 4; ++m) _Pragma("unroll") for (int k = 0; k < 2; ++k) dst[m][k] = *(const PG8_LAS bf16x8*)(lds + PG8_SA(b, h) + aoff + m * 2048 + k * 1024); } while (0)
; #define PG8_MMA(ai, bj, At, Bt) do { __builtin_amdgcn_s_setprio(1); _Pragma("unroll") for (int m = 0; m < 4; ++m) _Pragma("unroll") for (int n = 0; n < 2; ++n) _Pragma("unroll") for (int k = 0; k < 2; ++k) \
;         acc[ai][bj][m][n] = __builtin_amdgcn_mfma_f32_16x16x32_bf16(Bt[n][k], At[m][k], acc[ai][bj][m][n], 0, 0, 0); __builtin_amdgcn_s_setprio(0); } while (0)
; #define PG8_WAIT_V(n) asm volatile("s_waitcnt vmcnt(" #n ")" ::: "memory")
; #define PG8_WAIT_L(n) asm volatile("s_waitcnt lgkmcnt(" #n ")" ::: "memory")
; #define PG8_BAR __builtin_amdgcn_s_barrier()
; #define PG8_SCHED __builtin_amdgcn_sched_barrier(0)
; template <class Epi, class Sched, bool ALIGN_EPI = false, bool SP2 = false>
; __device__ __forceinline__ void gemm_phase(PG8_LAS unsigned char* lds, const Gemm g, const Sched& S, const Epi& E) {
;     ...
;             PG8_WAIT_V(8); PG8_WAIT_L(0); PG8_BAR; PG8_MMA(0, 0, At, B0); PG8_MMA(0, 1, At, B1); PG8_BAR; PG8_SCHED;
;             PG8_LDA(At, 0, 1); PG8_STAGE(PG8_SB(0, 0), b2, voffB); PG8_STAGE(PG8_SB(0, 1), b2 + hstep, voffB); PG8_STAGE(PG8_SA(0, 0), a2, voffA);
;             PG8_WAIT_V(8); PG8_WAIT_L(0); PG8_BAR; PG8_MMA(1, 0, At, B0); PG8_MMA(1, 1, At, B1); PG8_BAR; PG8_SCHED;
	s_waitcnt lgkmcnt(0)
	v_mfma_f32_16x16x32_bf16 v[124:127], v[128:131], v[178:181], v[124:127]
	v_mfma_f32_16x16x32_bf16 v[120:123], v[136:139], v[178:181], v[120:123]
	v_mfma_f32_16x16x32_bf16 v[116:119], v[128:131], v[186:189], v[116:119]
	v_mfma_f32_16x16x32_bf16 v[108:111], v[136:139], v[186:189], v[108:111]
	v_mfma_f32_16x16x32_bf16 v[96:99], v[128:131], v[198:201], v[96:99]
	v_mfma_f32_16x16x32_bf16 v[88:91], v[136:139], v[198:201], v[88:91]
	v_mfma_f32_16x16x32_bf16 v[80:83], v[128:131], v[206:209], v[80:83]
	v_mfma_f32_16x16x32_bf16 v[72:75], v[136:139], v[206:209], v[72:75]
	v_mfma_f32_16x16x32_bf16 v[124:127], v[132:135], v[182:185], v[124:127]
	v_mfma_f32_16x16x32_bf16 v[120:123], v[140:143], v[182:185], v[120:123]
	v_mfma_f32_16x16x32_bf16 v[116:119], v[132:135], v[194:197], v[116:119]
	v_mfma_f32_16x16x32_bf16 v[108:111], v[140:143], v[194:197], v[108:111]
	v_mfma_f32_16x16x32_bf16 v[96:99], v[132:135], v[202:205], v[96:99]
	v_mfma_f32_16x16x32_bf16 v[88:91], v[140:143], v[202:205], v[88:91]
	v_mfma_f32_16x16x32_bf16 v[80:83], v[132:135], v[210:213], v[80:83]
	v_mfma_f32_16x16x32_bf16 v[72:75], v[140:143], v[210:213], v[72:75]
	v_mfma_f32_16x16x32_bf16 v[112:115], v[156:159], v[178:181], v[112:115]
	v_mfma_f32_16x16x32_bf16 v[104:107], v[170:173], v[178:181], v[104:107]
	v_mfma_f32_16x16x32_bf16 v[100:103], v[156:159], v[186:189], v[100:103]
	v_mfma_f32_16x16x32_bf16 v[92:95], v[170:173], v[186:189], v[92:95]
	v_mfma_f32_16x16x32_bf16 v[84:87], v[156:159], v[198:201], v[84:87]
	v_mfma_f32_16x16x32_bf16 v[76:79], v[170:173], v[198:201], v[76:79]
	v_mfma_f32_16x16x32_bf16 v[68:71], v[156:159], v[206:209], v[68:71]
	v_mfma_f32_16x16x32_bf16 v[64:67], v[170:173], v[206:209], v[64:67]
	v_mfma_f32_16x16x32_bf16 v[112:115], v[160:163], v[182:185], v[112:115]
	v_mfma_f32_16x16x32_bf16 v[104:107], v[174:177], v[182:185], v[104:107]
	v_mfma_f32_16x16x32_bf16 v[100:103], v[160:163], v[194:197], v[100:103]
	v_mfma_f32_16x16x32_bf16 v[92:95], v[174:177], v[194:197], v[92:95]
	v_mfma_f32_16x16x32_bf16 v[84:87], v[160:163], v[202:205], v[84:87]
	v_mfma_f32_16x16x32_bf16 v[76:79], v[174:177], v[202:205], v[76:79]
	v_mfma_f32_16x16x32_bf16 v[68:71], v[160:163], v[210:213], v[68:71]
	v_mfma_f32_16x16x32_bf16 v[64:67], v[174:177], v[210:213], v[64:67]
	s_barrier
	s_add_i32 s55, s47, s35
	v_lshl_add_u64 v[190:191], s[2:3], 0, v[144:145]
	s_mov_b32 m0, s55
	ds_read_b128 v[178:181], v169 offset:16384
	ds_read_b128 v[182:185], v169 offset:17408
	ds_read_b128 v[186:189], v169 offset:18432
	ds_read_b128 v[194:197], v169 offset:19456
	ds_read_b128 v[198:201], v169 offset:20480
	ds_read_b128 v[202:205], v169 offset:21504
	ds_read_b128 v[206:209], v169 offset:22528
	ds_read_b128 v[210:213], v169 offset:23552
	global_load_lds_dwordx4 v[190:191], off
	s_add_i32 m0, s55, 0x2000
	s_add_u32 s56, s2, 0x100000
	v_lshl_add_u64 v[192:193], s[2:3], 0, v[146:147]
	s_addc_u32 s57, s3, 0
	s_add_i32 s55, s48, s35
	global_load_lds_dwordx4 v[192:193], off
	v_lshl_add_u64 v[214:215], s[56:57], 0, v[144:145]
	s_mov_b32 m0, s55
	v_lshl_add_u64 v[216:217], s[28:29], 0, v[146:147]
	global_load_lds_dwordx4 v[214:215], off
	v_lshl_add_u64 v[214:215], s[56:57], 0, v[146:147]
	s_add_i32 m0, s55, 0x2000
	s_nop 0
	global_load_lds_dwordx4 v[214:215], off
	v_lshl_add_u64 v[214:215], s[28:29], 0, v[144:145]
	s_mov_b32 m0, s25
	s_nop 0
	global_load_lds_dwordx4 v[214:215], off
	s_mov_b32 m0, s38
	s_nop 0
	global_load_lds_dwordx4 v[216:217], off
	s_waitcnt vmcnt(8)
	s_waitcnt lgkmcnt(0)
	s_barrier
	s_waitcnt lgkmcnt(0)
	v_mfma_f32_16x16x32_bf16 v[60:63], v[128:131], v[178:181], v[60:63]
	v_mfma_f32_16x16x32_bf16 v[56:59], v[136:139], v[178:181], v[56:59]
	v_mfma_f32_16x16x32_bf16 v[48:51], v[128:131], v[186:189], v[48:51]
	v_mfma_f32_16x16x32_bf16 v[40:43], v[136:139], v[186:189], v[40:43]
	v_mfma_f32_16x16x32_bf16 v[32:35], v[128:131], v[198:201], v[32:35]
	v_mfma_f32_16x16x32_bf16 v[24:27], v[136:139], v[198:201], v[24:27]
	v_mfma_f32_16x16x32_bf16 v[16:19], v[128:131], v[206:209], v[16:19]
	v_mfma_f32_16x16x32_bf16 v[8:11], v[136:139], v[206:209], v[8:11]
	v_mfma_f32_16x16x32_bf16 v[60:63], v[132:135], v[182:185], v[60:63]
	v_mfma_f32_16x16x32_bf16 v[56:59], v[140:143], v[182:185], v[56:59]
	v_mfma_f32_16x16x32_bf16 v[48:51], v[132:135], v[194:197], v[48:51]
	v_mfma_f32_16x16x32_bf16 v[40:43], v[140:143], v[194:197], v[40:43]
	v_mfma_f32_16x16x32_bf16 v[32:35], v[132:135], v[202:205], v[32:35]
	v_mfma_f32_16x16x32_bf16 v[24:27], v[140:143], v[202:205], v[24:27]
	v_mfma_f32_16x16x32_bf16 v[16:19], v[132:135], v[210:213], v[16:19]
	v_mfma_f32_16x16x32_bf16 v[8:11], v[140:143], v[210:213], v[8:11]
	v_mfma_f32_16x16x32_bf16 v[52:55], v[156:159], v[178:181], v[52:55]
	v_mfma_f32_16x16x32_bf16 v[44:47], v[170:173], v[178:181], v[44:47]
	v_mfma_f32_16x16x32_bf16 v[36:39], v[156:159], v[186:189], v[36:39]
	v_mfma_f32_16x16x32_bf16 v[28:31], v[170:173], v[186:189], v[28:31]
	v_mfma_f32_16x16x32_bf16 v[20:23], v[156:159], v[198:201], v[20:23]
	v_mfma_f32_16x16x32_bf16 v[12:15], v[170:173], v[198:201], v[12:15]
	v_mfma_f32_16x16x32_bf16 v[4:7], v[156:159], v[206:209], v[4:7]
	v_mfma_f32_16x16x32_bf16 v[0:3], v[170:173], v[206:209], v[0:3]
	v_mfma_f32_16x16x32_bf16 v[52:55], v[160:163], v[182:185], v[52:55]
	v_mfma_f32_16x16x32_bf16 v[44:47], v[174:177], v[182:185], v[44:47]
	v_mfma_f32_16x16x32_bf16 v[36:39], v[160:163], v[194:197], v[36:39]
	v_mfma_f32_16x16x32_bf16 v[28:31], v[174:177], v[194:197], v[28:31]
	v_mfma_f32_16x16x32_bf16 v[20:23], v[160:163], v[202:205], v[20:23]
	v_mfma_f32_16x16x32_bf16 v[12:15], v[174:177], v[202:205], v[12:15]
	v_mfma_f32_16x16x32_bf16 v[4:7], v[160:163], v[210:213], v[4:7]
	v_mfma_f32_16x16x32_bf16 v[0:3], v[174:177], v[210:213], v[0:3]
	s_barrier
; #define PG8_STAGE(bufoff, gbase, voff) do { _Pragma("unroll") for (int _i = 0; _i < 2; ++_i) \
;         __builtin_amdgcn_global_load_lds((const unsigned*)((const char*)(gbase) + (voff)[_i]), (PG8_LAS unsigned*)(lds + (bufoff) + ldsw + _i * 8192), 16, 0, 0); } while (0)
; #define PG8_LDA(dst, b, h) do { _Pragma("unroll") for (int m = 0; m < 4; ++m) _Pragma("unroll") for (int k = 0; k < 2; ++k) dst[m][k] = *(const PG8_LAS bf16x8*)(lds + PG8_SA(b, h) + aoff + m * 2048 + k * 1024); } while (0)
; #define PG8_LDB(dst, b, h) do { _Pragma("unroll") for (int n = 0; n < 2; ++n) _Pragma("unroll") for (int k = 0; k < 2; ++k) dst[n][k] = *(const PG8_LAS bf16x8*)(lds + PG8_SB(b, h) + boff + n * 2048 + k * 1024); } while (0)
; #define PG8_MMA(ai, bj, At, Bt) do { __builtin_amdgcn_s_setprio(1); _Pragma("unroll") for (int m = 0; m < 4; ++m) _Pragma("unroll") for (int n = 0; n < 2; ++n) _Pragma("unroll") for (int k = 0; k < 2; ++k) \
;         acc[ai][bj][m][n] = __builtin_amdgcn_mfma_f32_16x16x32_bf16(Bt[n][k], At[m][k], acc[ai][bj][m][n], 0, 0, 0); __builtin_amdgcn_s_setprio(0); } while (0)
; #define PG8_WAIT_V(n) asm volatile("s_waitcnt vmcnt(" #n ")" ::: "memory")
; #define PG8_WAIT_L(n) asm volatile("s_waitcnt lgkmcnt(" #n ")" ::: "memory")
; #define PG8_BAR __builtin_amdgcn_s_barrier()
; #define PG8_SCHED __builtin_amdgcn_sched_barrier(0)
; template <class Epi, class Sched, bool ALIGN_EPI = false, bool SP2 = false>
; __device__ __forceinline__ void gemm_phase(PG8_LAS unsigned char* lds, const Gemm g, const Sched& S, const Epi& E) {
;     ...
;             PG8_LDB(B0, 1, 0); PG8_LDB(B1, 1, 1); PG8_SCHED; PG8_LDA(At, 1, 0); PG8_STAGE(PG8_SA(0, 1), a2 + hstep, voffA);
;             PG8_WAIT_V(8); PG8_WAIT_L(0); PG8_BAR; PG8_MMA(0, 0, At, B0); PG8_MMA(0, 1, At, B1); PG8_BAR; PG8_SCHED;
	s_add_i32 s55, 0, 0x18000
	s_add_i32 s56, 0, 0x1c000
	v_add_u32_e32 v140, s55, v165
	v_add_u32_e32 v174, s56, v165
	ds_read_b128 v[128:131], v140
	ds_read_b128 v[132:135], v140 offset:1024
	ds_read_b128 v[136:139], v140 offset:2048
	ds_read_b128 v[140:143], v140 offset:3072
	ds_read_b128 v[156:159], v174
	ds_read_b128 v[160:163], v174 offset:1024
	ds_read_b128 v[170:173], v174 offset:2048
	ds_read_b128 v[174:177], v174 offset:3072
	s_add_u32 s28, s28, 0x100000
	s_addc_u32 s29, s29, 0
	s_mov_b32 m0, s39
	v_lshl_add_u64 v[218:219], s[28:29], 0, v[144:145]
	ds_read_b128 v[178:181], v169 offset:32768
	ds_read_b128 v[182:185], v169 offset:33792
	ds_read_b128 v[186:189], v169 offset:34816
	ds_read_b128 v[194:197], v169 offset:35840
	ds_read_b128 v[198:201], v169 offset:36864
	ds_read_b128 v[202:205], v169 offset:37888
	ds_read_b128 v[206:209], v169 offset:38912
	ds_read_b128 v[210:213], v169 offset:39936
	global_load_lds_dwordx4 v[218:219], off
	v_lshl_add_u64 v[218:219], s[28:29], 0, v[146:147]
	s_mov_b32 m0, s40
	s_nop 0
	global_load_lds_dwordx4 v[218:219], off
	s_waitcnt vmcnt(8)
	s_waitcnt lgkmcnt(0)
	s_barrier
	s_waitcnt lgkmcnt(0)
	v_mfma_f32_16x16x32_bf16 v[124:127], v[128:131], v[178:181], v[124:127]
	v_mfma_f32_16x16x32_bf16 v[120:123], v[136:139], v[178:181], v[120:123]
	v_mfma_f32_16x16x32_bf16 v[116:119], v[128:131], v[186:189], v[116:119]
	v_mfma_f32_16x16x32_bf16 v[108:111], v[136:139], v[186:189], v[108:111]
	v_mfma_f32_16x16x32_bf16 v[96:99], v[128:131], v[198:201], v[96:99]
	v_mfma_f32_16x16x32_bf16 v[88:91], v[136:139], v[198:201], v[88:91]
	v_mfma_f32_16x16x32_bf16 v[80:83], v[128:131], v[206:209], v[80:83]
	v_mfma_f32_16x16x32_bf16 v[72:75], v[136:139], v[206:209], v[72:75]
	v_mfma_f32_16x16x32_bf16 v[124:127], v[132:135], v[182:185], v[124:127]
	v_mfma_f32_16x16x32_bf16 v[120:123], v[140:143], v[182:185], v[120:123]
	v_mfma_f32_16x16x32_bf16 v[116:119], v[132:135], v[194:197], v[116:119]
	v_mfma_f32_16x16x32_bf16 v[108:111], v[140:143], v[194:197], v[108:111]
	v_mfma_f32_16x16x32_bf16 v[96:99], v[132:135], v[202:205], v[96:99]
	v_mfma_f32_16x16x32_bf16 v[88:91], v[140:143], v[202:205], v[88:91]
	v_mfma_f32_16x16x32_bf16 v[80:83], v[132:135], v[210:213], v[80:83]
	v_mfma_f32_16x16x32_bf16 v[72:75], v[140:143], v[210:213], v[72:75]
	v_mfma_f32_16x16x32_bf16 v[112:115], v[156:159], v[178:181], v[112:115]
	v_mfma_f32_16x16x32_bf16 v[104:107], v[170:173], v[178:181], v[104:107]
	v_mfma_f32_16x16x32_bf16 v[100:103], v[156:159], v[186:189], v[100:103]
	v_mfma_f32_16x16x32_bf16 v[92:95], v[170:173], v[186:189], v[92:95]
	v_mfma_f32_16x16x32_bf16 v[84:87], v[156:159], v[198:201], v[84:87]
	v_mfma_f32_16x16x32_bf16 v[76:79], v[170:173], v[198:201], v[76:79]
	v_mfma_f32_16x16x32_bf16 v[68:71], v[156:159], v[206:209], v[68:71]
	v_mfma_f32_16x16x32_bf16 v[64:67], v[170:173], v[206:209], v[64:67]
	v_mfma_f32_16x16x32_bf16 v[112:115], v[160:163], v[182:185], v[112:115]
	v_mfma_f32_16x16x32_bf16 v[104:107], v[174:177], v[182:185], v[104:107]
	v_mfma_f32_16x16x32_bf16 v[100:103], v[160:163], v[194:197], v[100:103]
	v_mfma_f32_16x16x32_bf16 v[92:95], v[174:177], v[194:197], v[92:95]
	v_mfma_f32_16x16x32_bf16 v[84:87], v[160:163], v[202:205], v[84:87]
	v_mfma_f32_16x16x32_bf16 v[76:79], v[174:177], v[202:205], v[76:79]
	v_mfma_f32_16x16x32_bf16 v[68:71], v[160:163], v[210:213], v[68:71]
	v_mfma_f32_16x16x32_bf16 v[64:67], v[174:177], v[210:213], v[64:67]
	s_barrier
; #define PG8_STAGE(bufoff, gbase, voff) do { _Pragma("unroll") for (int _i = 0; _i < 2; ++_i) \
;         __builtin_amdgcn_global_load_lds((const unsigned*)((const char*)(gbase) + (voff)[_i]), (PG8_LAS unsigned*)(lds + (bufoff) + ldsw + _i * 8192), 16, 0, 0); } while (0)
; #define PG8_LDA(dst, b, h) do { _Pragma("unroll") for (int m = 0; m < 4; ++m) _Pragma("unroll") for (int k = 0; k < 2; ++k) dst[m][k] = *(const PG8_LAS bf16x8*)(lds + PG8_SA(b, h) + aoff + m * 2048 + k * 1024); } while (0)
; #define PG8_MMA(ai, bj, At, Bt) do { __builtin_amdgcn_s_setprio(1); _Pragma("unroll") for (int m = 0; m < 4; ++m) _Pragma("unroll") for (int n = 0; n < 2; ++n) _Pragma("unroll") for (int k = 0; k < 2; ++k) \
;         acc[ai][bj][m][n] = __builtin_amdgcn_mfma_f32_16x16x32_bf16(Bt[n][k], At[m][k], acc[ai][bj][m][n], 0, 0, 0); __builtin_amdgcn_s_setprio(0); } while (0)
; #define PG8_WAIT_V(n) asm volatile("s_waitcnt vmcnt(" #n ")" ::: "memory")
; #define PG8_WAIT_L(n) asm volatile("s_waitcnt lgkmcnt(" #n ")" ::: "memory")
; #define PG8_BAR __builtin_amdgcn_s_barrier()
; #define PG8_SCHED __builtin_amdgcn_sched_barrier(0)
; template <class Epi, class Sched, bool ALIGN_EPI = false, bool SP2 = false>
; __device__ __forceinline__ void gemm_phase(PG8_LAS unsigned char* lds, const Gemm g, const Sched& S, const Epi& E) {
;     ...
;         for (int t = 0; t < nt; t += 2) {
;     ...
;             PG8_LDA(At, 1, 1); PG8_STAGE(PG8_SB(1, 0), b3, voffB); PG8_STAGE(PG8_SB(1, 1), b3 + hstep, voffB); PG8_STAGE(PG8_SA(1, 0), a3, voffA);
;             PG8_WAIT_V(8); PG8_WAIT_L(0); PG8_BAR; PG8_MMA(1, 0, At, B0); PG8_MMA(1, 1, At, B1); PG8_BAR; PG8_SCHED;
	s_add_i32 s28, s55, s35
	v_lshl_add_u64 v[190:191], v[190:191], 0, s[10:11]
	s_mov_b32 m0, s28
	ds_read_b128 v[178:181], v169 offset:49152
	ds_read_b128 v[182:185], v169 offset:50176
	ds_read_b128 v[186:189], v169 offset:51200
	ds_read_b128 v[194:197], v169 offset:52224
	ds_read_b128 v[198:201], v169 offset:53248
	ds_read_b128 v[202:205], v169 offset:54272
	ds_read_b128 v[206:209], v169 offset:55296
	ds_read_b128 v[210:213], v169 offset:56320
	global_load_lds_dwordx4 v[190:191], off
	s_add_i32 m0, s28, 0x2000
	s_add_u32 s2, s2, 0x100080
	v_lshl_add_u64 v[190:191], v[192:193], 0, s[10:11]
	s_addc_u32 s3, s3, 0
	s_add_i32 s28, s56, s35
	global_load_lds_dwordx4 v[190:191], off
	v_lshl_add_u64 v[190:191], s[2:3], 0, v[144:145]
	s_mov_b32 m0, s28
	s_nop 0
	global_load_lds_dwordx4 v[190:191], off
	v_lshl_add_u64 v[190:191], s[2:3], 0, v[146:147]
	s_add_i32 m0, s28, 0x2000
	s_nop 0
	global_load_lds_dwordx4 v[190:191], off
	v_lshl_add_u64 v[190:191], v[214:215], 0, s[10:11]
	s_mov_b32 m0, s45
	s_nop 0
	global_load_lds_dwordx4 v[190:191], off
	v_lshl_add_u64 v[190:191], v[216:217], 0, s[10:11]
	s_mov_b32 m0, s46
	s_nop 0
	global_load_lds_dwordx4 v[190:191], off
	s_waitcnt vmcnt(8)
	s_waitcnt lgkmcnt(0)
	s_barrier
	s_waitcnt lgkmcnt(0)
	v_mfma_f32_16x16x32_bf16 v[60:63], v[128:131], v[178:181], v[60:63]
	v_mfma_f32_16x16x32_bf16 v[56:59], v[136:139], v[178:181], v[56:59]
	v_mfma_f32_16x16x32_bf16 v[48:51], v[128:131], v[186:189], v[48:51]
	v_mfma_f32_16x16x32_bf16 v[40:43], v[136:139], v[186:189], v[40:43]
	v_mfma_f32_16x16x32_bf16 v[32:35], v[128:131], v[198:201], v[32:35]
	v_mfma_f32_16x16x32_bf16 v[24:27], v[136:139], v[198:201], v[24:27]
	v_mfma_f32_16x16x32_bf16 v[16:19], v[128:131], v[206:209], v[16:19]
	v_mfma_f32_16x16x32_bf16 v[8:11], v[136:139], v[206:209], v[8:11]
	v_mfma_f32_16x16x32_bf16 v[60:63], v[132:135], v[182:185], v[60:63]
	v_mfma_f32_16x16x32_bf16 v[56:59], v[140:143], v[182:185], v[56:59]
	v_mfma_f32_16x16x32_bf16 v[48:51], v[132:135], v[194:197], v[48:51]
	v_mfma_f32_16x16x32_bf16 v[40:43], v[140:143], v[194:197], v[40:43]
	v_mfma_f32_16x16x32_bf16 v[32:35], v[132:135], v[202:205], v[32:35]
	v_mfma_f32_16x16x32_bf16 v[24:27], v[140:143], v[202:205], v[24:27]
	v_mfma_f32_16x16x32_bf16 v[16:19], v[132:135], v[210:213], v[16:19]
	v_mfma_f32_16x16x32_bf16 v[8:11], v[140:143], v[210:213], v[8:11]
	v_mfma_f32_16x16x32_bf16 v[52:55], v[156:159], v[178:181], v[52:55]
	v_mfma_f32_16x16x32_bf16 v[44:47], v[170:173], v[178:181], v[44:47]
	v_mfma_f32_16x16x32_bf16 v[36:39], v[156:159], v[186:189], v[36:39]
	v_mfma_f32_16x16x32_bf16 v[28:31], v[170:173], v[186:189], v[28:31]
	v_mfma_f32_16x16x32_bf16 v[20:23], v[156:159], v[198:201], v[20:23]
	v_mfma_f32_16x16x32_bf16 v[12:15], v[170:173], v[198:201], v[12:15]
	v_mfma_f32_16x16x32_bf16 v[4:7], v[156:159], v[206:209], v[4:7]
	v_mfma_f32_16x16x32_bf16 v[0:3], v[170:173], v[206:209], v[0:3]
	v_mfma_f32_16x16x32_bf16 v[52:55], v[160:163], v[182:185], v[52:55]
	v_mfma_f32_16x16x32_bf16 v[44:47], v[174:177], v[182:185], v[44:47]
	v_mfma_f32_16x16x32_bf16 v[36:39], v[160:163], v[194:197], v[36:39]
	v_mfma_f32_16x16x32_bf16 v[28:31], v[174:177], v[194:197], v[28:31]
	v_mfma_f32_16x16x32_bf16 v[20:23], v[160:163], v[202:205], v[20:23]
	v_mfma_f32_16x16x32_bf16 v[12:15], v[174:177], v[202:205], v[12:15]
	v_mfma_f32_16x16x32_bf16 v[4:7], v[160:163], v[210:213], v[4:7]
	v_mfma_f32_16x16x32_bf16 v[0:3], v[174:177], v[210:213], v[0:3]
	s_barrier
	s_add_i32 s54, s54, 2
	s_add_u32 s26, s26, 0x100
	s_addc_u32 s27, s27, 0
	s_add_u32 s52, s52, 0x100
	s_addc_u32 s53, s53, 0
	s_cmp_gt_u32 s54, 61
	s_cbranch_scc0 .LBB0_1313
	s_setprio 0
	s_and_b64 vcc, exec, s[14:15]
	s_cbranch_vccz .LBB0_1316
	s_barrier

; #define PG8_STAGE(bufoff, gbase, voff) do { _Pragma("unroll") for (int _i = 0; _i < 2; ++_i) \
;         __builtin_amdgcn_global_load_lds((const unsigned*)((const char*)(gbase) + (voff)[_i]), (PG8_LAS unsigned*)(lds + (bufoff) + ldsw + _i * 8192), 16, 0, 0); } while (0)
; #define PG8_LDA(dst, b, h) do { _Pragma("unroll") for (int m = 0; m < 4; ++m) _Pragma("unroll") for (int k = 0; k < 2; ++k) dst[m][k] = *(const PG8_LAS bf16x8*)(lds + PG8_SA(b, h) + aoff + m * 2048 + k * 1024); } while (0)
; #define PG8_LDB(dst, b, h) do { _Pragma("unroll") for (int n = 0; n < 2; ++n) _Pragma("unroll") for (int k = 0; k < 2; ++k) dst[n][k] = *(const PG8_LAS bf16x8*)(lds + PG8_SB(b, h) + boff + n * 2048 + k * 1024); } while (0)
; #define PG8_WAIT_V(n) asm volatile("s_waitcnt vmcnt(" #n ")" ::: "memory")
; #define PG8_WAIT_L(n) asm volatile("s_waitcnt lgkmcnt(" #n ")" ::: "memory")
; #define PG8_BAR __builtin_amdgcn_s_barrier()
; template <class Epi, class Sched, bool ALIGN_EPI = false, bool SP2 = false>
; __device__ __forceinline__ void gemm_phase(PG8_LAS unsigned char* lds, const Gemm g, const Sched& S, const Epi& E) {
;     ...
;         const bool has_next = S.next(ui + 1, nxt);
;         const char* nA = has_next ? (const char*)g.A + (size_t)nxt.pm * tstep : cA; const char* nB = has_next ? (const char*)g.Bt + (size_t)nxt.pn * tstep : cB;
;         for (int t = 0; t < nt; t += 2) {
;             const bool last = (t == nt - 2);
;             const char* a1 = cA + (size_t)(t + 1) * kstep;
;             const char* a2 = last ? nA : cA + (size_t)(t + 2) * kstep; const char* b2 = last ? nB : cB + (size_t)(t + 2) * kstep;
;             const char* a3 = a2 + kstep; const char* b3 = b2 + kstep;
;             if (last && has_next) S.a_ready(nxt);
;             if constexpr (SP2) {
;             PG8_LDB(B0, 0, 0); PG8_LDB(B1, 0, 1); PG8_SCHED; PG8_LDA(At, 0, 0); PG8_STAGE(PG8_SA(1, 1), a1 + hstep, voffA);
;             PG8_WAIT_V(8); PG8_WAIT_L(0); PG8_BAR; PG8_MMA(0, 0, At, B0); PG8_MMA(0, 1, At, B1); PG8_BAR; PG8_SCHED;
;     ...
; #pragma unroll
;         for (int a = 0; a < 2; ++a)
; #pragma unroll
;             for (int b = 0; b < 2; ++b)
; #pragma unroll
;                 for (int m = 0; m < 4; ++m)
; #pragma unroll
;                     for (int n = 0; n < 2; ++n) acc[a][b][m][n] = (f32x4){0.f, 0.f, 0.f, 0.f};
;         cur = nxt; cA = nA; cB = nB; ++ui;
.LBB0_1454:
	s_ashr_i32 s17, s16, 31
	s_lshl_b64 s[18:19], s[16:17], 21
	s_add_u32 s18, s30, s18
	s_addc_u32 s19, s31, s19
	s_and_b64 s[20:21], s[0:1], exec
	s_cselect_b32 s17, s19, s25
	s_cselect_b32 s48, s18, s24
	s_ashr_i32 s15, s14, 31
	s_lshl_b64 s[20:21], s[14:15], 21
	s_add_u32 s20, s28, s20
	s_addc_u32 s21, s29, s21
	s_and_b64 s[26:27], s[0:1], exec
	s_cselect_b32 s15, s21, s3
	s_cselect_b32 s49, s20, s2
	s_add_u32 s24, s24, 0x100080
	s_addc_u32 s25, s25, 0
	s_add_u32 s50, s2, 0x100
	v_mov_b32_e32 v0, 0
	s_addc_u32 s51, s3, 0
	s_mov_b32 s52, -2
	v_mov_b32_e32 v1, v0
	v_mov_b32_e32 v2, v0
	v_mov_b32_e32 v3, v0
	v_mov_b32_e32 v4, v0
	v_mov_b32_e32 v5, v0
	v_mov_b32_e32 v6, v0
	v_mov_b32_e32 v7, v0
	v_mov_b32_e32 v12, v0
	v_mov_b32_e32 v13, v0
	v_mov_b32_e32 v14, v0
	v_mov_b32_e32 v15, v0
	v_mov_b32_e32 v20, v0
	v_mov_b32_e32 v21, v0
	v_mov_b32_e32 v22, v0
	v_mov_b32_e32 v23, v0
	v_mov_b32_e32 v28, v0
	v_mov_b32_e32 v29, v0
	v_mov_b32_e32 v30, v0
	v_mov_b32_e32 v31, v0
	v_mov_b32_e32 v36, v0
	v_mov_b32_e32 v37, v0
	v_mov_b32_e32 v38, v0
	v_mov_b32_e32 v39, v0
	v_mov_b32_e32 v44, v0
	v_mov_b32_e32 v45, v0
	v_mov_b32_e32 v46, v0
	v_mov_b32_e32 v47, v0
	v_mov_b32_e32 v52, v0
	v_mov_b32_e32 v53, v0
	v_mov_b32_e32 v54, v0
	v_mov_b32_e32 v55, v0
	v_mov_b32_e32 v8, v0
	v_mov_b32_e32 v9, v0
	v_mov_b32_e32 v10, v0
	v_mov_b32_e32 v11, v0
	v_mov_b32_e32 v16, v0
	v_mov_b32_e32 v17, v0
	v_mov_b32_e32 v18, v0
	v_mov_b32_e32 v19, v0
	v_mov_b32_e32 v24, v0
	v_mov_b32_e32 v25, v0
	v_mov_b32_e32 v26, v0
	v_mov_b32_e32 v27, v0
	v_mov_b32_e32 v32, v0
	v_mov_b32_e32 v33, v0
	v_mov_b32_e32 v34, v0
	v_mov_b32_e32 v35, v0
	v_mov_b32_e32 v40, v0
	v_mov_b32_e32 v41, v0
	v_mov_b32_e32 v42, v0
	v_mov_b32_e32 v43, v0
	v_mov_b32_e32 v48, v0
	v_mov_b32_e32 v49, v0
	v_mov_b32_e32 v50, v0
	v_mov_b32_e32 v51, v0
	v_mov_b32_e32 v56, v0
	v_mov_b32_e32 v57, v0
	v_mov_b32_e32 v58, v0
	v_mov_b32_e32 v59, v0
	v_mov_b32_e32 v60, v0
	v_mov_b32_e32 v61, v0
	v_mov_b32_e32 v62, v0
	v_mov_b32_e32 v63, v0
	v_mov_b32_e32 v64, v0
	v_mov_b32_e32 v65, v0
	v_mov_b32_e32 v66, v0
	v_mov_b32_e32 v67, v0
	v_mov_b32_e32 v68, v0
	v_mov_b32_e32 v69, v0
	v_mov_b32_e32 v70, v0
	v_mov_b32_e32 v71, v0
	v_mov_b32_e32 v76, v0
	v_mov_b32_e32 v77, v0
	v_mov_b32_e32 v78, v0
	v_mov_b32_e32 v79, v0
	v_mov_b32_e32 v84, v0
	v_mov_b32_e32 v85, v0
	v_mov_b32_e32 v86, v0
	v_mov_b32_e32 v87, v0
	v_mov_b32_e32 v92, v0
	v_mov_b32_e32 v93, v0
	v_mov_b32_e32 v94, v0
	v_mov_b32_e32 v95, v0
	v_mov_b32_e32 v100, v0
	v_mov_b32_e32 v101, v0
	v_mov_b32_e32 v102, v0
	v_mov_b32_e32 v103, v0
	v_mov_b32_e32 v104, v0
	v_mov_b32_e32 v105, v0
	v_mov_b32_e32 v106, v0
	v_mov_b32_e32 v107, v0
	v_mov_b32_e32 v112, v0
	v_mov_b32_e32 v113, v0
	v_mov_b32_e32 v114, v0
	v_mov_b32_e32 v115, v0
	v_mov_b32_e32 v72, v0
	v_mov_b32_e32 v73, v0
	v_mov_b32_e32 v74, v0
	v_mov_b32_e32 v75, v0
	v_mov_b32_e32 v80, v0
	v_mov_b32_e32 v81, v0
	v_mov_b32_e32 v82, v0
	v_mov_b32_e32 v83, v0
	v_mov_b32_e32 v88, v0
	v_mov_b32_e32 v89, v0
	v_mov_b32_e32 v90, v0
	v_mov_b32_e32 v91, v0
	v_mov_b32_e32 v96, v0
	v_mov_b32_e32 v97, v0
	v_mov_b32_e32 v98, v0
	v_mov_b32_e32 v99, v0
	v_mov_b32_e32 v108, v0
	v_mov_b32_e32 v109, v0
	v_mov_b32_e32 v110, v0
	v_mov_b32_e32 v111, v0
	v_mov_b32_e32 v116, v0
	v_mov_b32_e32 v117, v0
	v_mov_b32_e32 v118, v0
	v_mov_b32_e32 v119, v0
	v_mov_b32_e32 v120, v0
	v_mov_b32_e32 v121, v0
	v_mov_b32_e32 v122, v0
	v_mov_b32_e32 v123, v0
	v_mov_b32_e32 v124, v0
	v_mov_b32_e32 v125, v0
	v_mov_b32_e32 v126, v0
	v_mov_b32_e32 v127, v0
	v_readfirstlane_b32 s98, v254
	s_nop 3
	s_lshr_b32 s98, s98, 8
	s_cmp_eq_u32 s98, 1
	s_cbranch_scc0 .Lsp_7
	s_setprio 1
.Lsp_7:
.LBB0_1455:
	ds_read_b128 v[128:131], v167
	ds_read_b128 v[132:135], v167 offset:1024
	ds_read_b128 v[136:139], v167 offset:2048
	ds_read_b128 v[140:143], v167 offset:3072
	ds_read_b128 v[156:159], v168
	ds_read_b128 v[160:163], v168 offset:1024
	ds_read_b128 v[170:173], v168 offset:2048
	ds_read_b128 v[174:177], v168 offset:3072
	s_add_u32 s2, s24, 0xfff00080
	s_addc_u32 s3, s25, -1
	s_cmp_eq_u32 s52, 60
	s_cselect_b32 s27, s17, s3
	s_cselect_b32 s26, s48, s2
	s_cselect_b32 s3, s15, s51
	s_cselect_b32 s2, s49, s50
	v_lshl_add_u64 v[210:211], s[24:25], 0, v[148:149]
	s_add_i32 m0, s23, 0xc000
	ds_read_b128 v[178:181], v169
	ds_read_b128 v[182:185], v169 offset:1024
	ds_read_b128 v[186:189], v169 offset:2048
	ds_read_b128 v[190:193], v169 offset:3072
	ds_read_b128 v[194:197], v169 offset:4096
	ds_read_b128 v[198:201], v169 offset:5120
	ds_read_b128 v[202:205], v169 offset:6144
	ds_read_b128 v[206:209], v169 offset:7168
	global_load_lds_dwordx4 v[210:211], off
	v_lshl_add_u64 v[210:211], s[24:25], 0, v[150:151]
	s_add_i32 m0, s23, 0xe000
	s_nop 0
	global_load_lds_dwordx4 v[210:211], off
	s_waitcnt vmcnt(8)
	s_waitcnt lgkmcnt(0)
	s_barrier
; #define PG8_STAGE(bufoff, gbase, voff) do { _Pragma("unroll") for (int _i = 0; _i < 2; ++_i) \
;         __builtin_amdgcn_global_load_lds((const unsigned*)((const char*)(gbase) + (voff)[_i]), (PG8_LAS unsigned*)(lds + (bufoff) + ldsw + _i * 8192), 16, 0, 0); } while (0)
; #define PG8_LDA(dst, b, h) do { _Pragma("unroll") for (int m = 0; m < 4; ++m) _Pragma("unroll") for (int k = 0; k < 2; ++k) dst[m][k] = *(const PG8_LAS bf16x8*)(lds + PG8_SA(b, h) + aoff + m * 2048 + k * 1024); } while (0)
; #define PG8_MMA(ai, bj, At, Bt) do { __builtin_amdgcn_s_setprio(1); _Pragma("unroll") for (int m = 0; m < 4; ++m) _Pragma("unroll") for (int n = 0; n < 2; ++n) _Pragma("unroll") for (int k = 0; k < 2; ++k) \
;         acc[ai][bj][m][n] = __builtin_amdgcn_mfma_f32_16x16x32_bf16(Bt[n][k], At[m][k], acc[ai][bj][m][n], 0, 0, 0); __builtin_amdgcn_s_setprio(0); } while (0)
; #define PG8_WAIT_V(n) asm volatile("s_waitcnt vmcnt(" #n ")" ::: "memory")
; #define PG8_WAIT_L(n) asm volatile("s_waitcnt lgkmcnt(" #n ")" ::: "memory")
; #define PG8_BAR __builtin_amdgcn_s_barrier()
; #define PG8_SCHED __builtin_amdgcn_sched_barrier(0)
; template <class Epi, class Sched, bool ALIGN_EPI = false, bool SP2 = false>
; __device__ __forceinline__ void gemm_phase(PG8_LAS unsigned char* lds, const Gemm g, const Sched& S, const Epi& E) {
;     ...
;             PG8_WAIT_V(8); PG8_WAIT_L(0); PG8_BAR; PG8_MMA(0, 0, At, B0); PG8_MMA(0, 1, At, B1); PG8_BAR; PG8_SCHED;
;             PG8_LDA(At, 0, 1); PG8_STAGE(PG8_SB(0, 0), b2, voffB); PG8_STAGE(PG8_SB(0, 1), b2 + hstep, voffB); PG8_STAGE(PG8_SA(0, 0), a2, voffA);
;             PG8_WAIT_V(8); PG8_WAIT_L(0); PG8_BAR; PG8_MMA(1, 0, At, B0); PG8_MMA(1, 1, At, B1); PG8_BAR; PG8_SCHED;
	s_waitcnt lgkmcnt(0)
	v_mfma_f32_16x16x32_bf16 v[124:127], v[128:131], v[178:181], v[124:127]
	v_mfma_f32_16x16x32_bf16 v[120:123], v[136:139], v[178:181], v[120:123]
	v_mfma_f32_16x16x32_bf16 v[116:119], v[128:131], v[186:189], v[116:119]
	v_mfma_f32_16x16x32_bf16 v[108:111], v[136:139], v[186:189], v[108:111]
	v_mfma_f32_16x16x32_bf16 v[96:99], v[128:131], v[194:197], v[96:99]
	v_mfma_f32_16x16x32_bf16 v[88:91], v[136:139], v[194:197], v[88:91]
	v_mfma_f32_16x16x32_bf16 v[80:83], v[128:131], v[202:205], v[80:83]
	v_mfma_f32_16x16x32_bf16 v[72:75], v[136:139], v[202:205], v[72:75]
	v_mfma_f32_16x16x32_bf16 v[124:127], v[132:135], v[182:185], v[124:127]
	v_mfma_f32_16x16x32_bf16 v[120:123], v[140:143], v[182:185], v[120:123]
	v_mfma_f32_16x16x32_bf16 v[116:119], v[132:135], v[190:193], v[116:119]
	v_mfma_f32_16x16x32_bf16 v[108:111], v[140:143], v[190:193], v[108:111]
	v_mfma_f32_16x16x32_bf16 v[96:99], v[132:135], v[198:201], v[96:99]
	v_mfma_f32_16x16x32_bf16 v[88:91], v[140:143], v[198:201], v[88:91]
	v_mfma_f32_16x16x32_bf16 v[80:83], v[132:135], v[206:209], v[80:83]
	v_mfma_f32_16x16x32_bf16 v[72:75], v[140:143], v[206:209], v[72:75]
	v_mfma_f32_16x16x32_bf16 v[112:115], v[156:159], v[178:181], v[112:115]
	v_mfma_f32_16x16x32_bf16 v[104:107], v[170:173], v[178:181], v[104:107]
	v_mfma_f32_16x16x32_bf16 v[100:103], v[156:159], v[186:189], v[100:103]
	v_mfma_f32_16x16x32_bf16 v[92:95], v[170:173], v[186:189], v[92:95]
	v_mfma_f32_16x16x32_bf16 v[84:87], v[156:159], v[194:197], v[84:87]
	v_mfma_f32_16x16x32_bf16 v[76:79], v[170:173], v[194:197], v[76:79]
	v_mfma_f32_16x16x32_bf16 v[68:71], v[156:159], v[202:205], v[68:71]
	v_mfma_f32_16x16x32_bf16 v[64:67], v[170:173], v[202:205], v[64:67]
	v_mfma_f32_16x16x32_bf16 v[112:115], v[160:163], v[182:185], v[112:115]
	v_mfma_f32_16x16x32_bf16 v[104:107], v[174:177], v[182:185], v[104:107]
	v_mfma_f32_16x16x32_bf16 v[100:103], v[160:163], v[190:193], v[100:103]
	v_mfma_f32_16x16x32_bf16 v[92:95], v[174:177], v[190:193], v[92:95]
	v_mfma_f32_16x16x32_bf16 v[84:87], v[160:163], v[198:201], v[84:87]
	v_mfma_f32_16x16x32_bf16 v[76:79], v[174:177], v[198:201], v[76:79]
	v_mfma_f32_16x16x32_bf16 v[68:71], v[160:163], v[206:209], v[68:71]
	v_mfma_f32_16x16x32_bf16 v[64:67], v[174:177], v[206:209], v[64:67]
	s_barrier
	s_add_i32 s53, s45, s33
	v_lshl_add_u64 v[210:211], s[2:3], 0, v[144:145]
	s_mov_b32 m0, s53
	ds_read_b128 v[178:181], v169 offset:16384
	ds_read_b128 v[182:185], v169 offset:17408
	ds_read_b128 v[186:189], v169 offset:18432
	ds_read_b128 v[190:193], v169 offset:19456
	ds_read_b128 v[194:197], v169 offset:20480
	ds_read_b128 v[198:201], v169 offset:21504
	ds_read_b128 v[202:205], v169 offset:22528
	ds_read_b128 v[206:209], v169 offset:23552
	global_load_lds_dwordx4 v[210:211], off
	s_add_i32 m0, s53, 0x2000
	s_add_u32 s54, s2, 0x100000
	v_lshl_add_u64 v[212:213], s[2:3], 0, v[146:147]
	s_addc_u32 s55, s3, 0
	s_add_i32 s53, s46, s33
	global_load_lds_dwordx4 v[212:213], off
	v_lshl_add_u64 v[214:215], s[54:55], 0, v[144:145]
	s_mov_b32 m0, s53
	v_lshl_add_u64 v[216:217], s[26:27], 0, v[146:147]
	global_load_lds_dwordx4 v[214:215], off
	v_lshl_add_u64 v[214:215], s[54:55], 0, v[146:147]
	s_add_i32 m0, s53, 0x2000
	s_nop 0
	global_load_lds_dwordx4 v[214:215], off
	v_lshl_add_u64 v[214:215], s[26:27], 0, v[144:145]
	s_mov_b32 m0, s23
	s_nop 0
	global_load_lds_dwordx4 v[214:215], off
	s_mov_b32 m0, s36
	s_nop 0
	global_load_lds_dwordx4 v[216:217], off
	s_waitcnt vmcnt(8)
	s_waitcnt lgkmcnt(0)
	s_barrier
	s_waitcnt lgkmcnt(0)
	v_mfma_f32_16x16x32_bf16 v[60:63], v[128:131], v[178:181], v[60:63]
	v_mfma_f32_16x16x32_bf16 v[56:59], v[136:139], v[178:181], v[56:59]
	v_mfma_f32_16x16x32_bf16 v[48:51], v[128:131], v[186:189], v[48:51]
	v_mfma_f32_16x16x32_bf16 v[40:43], v[136:139], v[186:189], v[40:43]
	v_mfma_f32_16x16x32_bf16 v[32:35], v[128:131], v[194:197], v[32:35]
	v_mfma_f32_16x16x32_bf16 v[24:27], v[136:139], v[194:197], v[24:27]
	v_mfma_f32_16x16x32_bf16 v[16:19], v[128:131], v[202:205], v[16:19]
	v_mfma_f32_16x16x32_bf16 v[8:11], v[136:139], v[202:205], v[8:11]
	v_mfma_f32_16x16x32_bf16 v[60:63], v[132:135], v[182:185], v[60:63]
	v_mfma_f32_16x16x32_bf16 v[56:59], v[140:143], v[182:185], v[56:59]
	v_mfma_f32_16x16x32_bf16 v[48:51], v[132:135], v[190:193], v[48:51]
	v_mfma_f32_16x16x32_bf16 v[40:43], v[140:143], v[190:193], v[40:43]
	v_mfma_f32_16x16x32_bf16 v[32:35], v[132:135], v[198:201], v[32:35]
	v_mfma_f32_16x16x32_bf16 v[24:27], v[140:143], v[198:201], v[24:27]
	v_mfma_f32_16x16x32_bf16 v[16:19], v[132:135], v[206:209], v[16:19]
	v_mfma_f32_16x16x32_bf16 v[8:11], v[140:143], v[206:209], v[8:11]
	v_mfma_f32_16x16x32_bf16 v[52:55], v[156:159], v[178:181], v[52:55]
	v_mfma_f32_16x16x32_bf16 v[44:47], v[170:173], v[178:181], v[44:47]
	v_mfma_f32_16x16x32_bf16 v[36:39], v[156:159], v[186:189], v[36:39]
	v_mfma_f32_16x16x32_bf16 v[28:31], v[170:173], v[186:189], v[28:31]
	v_mfma_f32_16x16x32_bf16 v[20:23], v[156:159], v[194:197], v[20:23]
	v_mfma_f32_16x16x32_bf16 v[12:15], v[170:173], v[194:197], v[12:15]
	v_mfma_f32_16x16x32_bf16 v[4:7], v[156:159], v[202:205], v[4:7]
	v_mfma_f32_16x16x32_bf16 v[0:3], v[170:173], v[202:205], v[0:3]
	v_mfma_f32_16x16x32_bf16 v[52:55], v[160:163], v[182:185], v[52:55]
	v_mfma_f32_16x16x32_bf16 v[44:47], v[174:177], v[182:185], v[44:47]
	v_mfma_f32_16x16x32_bf16 v[36:39], v[160:163], v[190:193], v[36:39]
	v_mfma_f32_16x16x32_bf16 v[28:31], v[174:177], v[190:193], v[28:31]
	v_mfma_f32_16x16x32_bf16 v[20:23], v[160:163], v[198:201], v[20:23]
	v_mfma_f32_16x16x32_bf16 v[12:15], v[174:177], v[198:201], v[12:15]
	v_mfma_f32_16x16x32_bf16 v[4:7], v[160:163], v[206:209], v[4:7]
	v_mfma_f32_16x16x32_bf16 v[0:3], v[174:177], v[206:209], v[0:3]
	s_barrier
; #define PG8_STAGE(bufoff, gbase, voff) do { _Pragma("unroll") for (int _i = 0; _i < 2; ++_i) \
;         __builtin_amdgcn_global_load_lds((const unsigned*)((const char*)(gbase) + (voff)[_i]), (PG8_LAS unsigned*)(lds + (bufoff) + ldsw + _i * 8192), 16, 0, 0); } while (0)
; #define PG8_LDA(dst, b, h) do { _Pragma("unroll") for (int m = 0; m < 4; ++m) _Pragma("unroll") for (int k = 0; k < 2; ++k) dst[m][k] = *(const PG8_LAS bf16x8*)(lds + PG8_SA(b, h) + aoff + m * 2048 + k * 1024); } while (0)
; #define PG8_LDB(dst, b, h) do { _Pragma("unroll") for (int n = 0; n < 2; ++n) _Pragma("unroll") for (int k = 0; k < 2; ++k) dst[n][k] = *(const PG8_LAS bf16x8*)(lds + PG8_SB(b, h) + boff + n * 2048 + k * 1024); } while (0)
; #define PG8_MMA(ai, bj, At, Bt) do { __builtin_amdgcn_s_setprio(1); _Pragma("unroll") for (int m = 0; m < 4; ++m) _Pragma("unroll") for (int n = 0; n < 2; ++n) _Pragma("unroll") for (int k = 0; k < 2; ++k) \
;         acc[ai][bj][m][n] = __builtin_amdgcn_mfma_f32_16x16x32_bf16(Bt[n][k], At[m][k], acc[ai][bj][m][n], 0, 0, 0); __builtin_amdgcn_s_setprio(0); } while (0)
; #define PG8_WAIT_V(n) asm volatile("s_waitcnt vmcnt(" #n ")" ::: "memory")
; #define PG8_WAIT_L(n) asm volatile("s_waitcnt lgkmcnt(" #n ")" ::: "memory")
; #define PG8_BAR __builtin_amdgcn_s_barrier()
; #define PG8_SCHED __builtin_amdgcn_sched_barrier(0)
; template <class Epi, class Sched, bool ALIGN_EPI = false, bool SP2 = false>
; __device__ __forceinline__ void gemm_phase(PG8_LAS unsigned char* lds, const Gemm g, const Sched& S, const Epi& E) {
;     ...
;             PG8_LDB(B0, 1, 0); PG8_LDB(B1, 1, 1); PG8_SCHED; PG8_LDA(At, 1, 0); PG8_STAGE(PG8_SA(0, 1), a2 + hstep, voffA);
;             PG8_WAIT_V(8); PG8_WAIT_L(0); PG8_BAR; PG8_MMA(0, 0, At, B0); PG8_MMA(0, 1, At, B1); PG8_BAR; PG8_SCHED;
	s_add_i32 s53, 0, 0x18000
	s_add_i32 s54, 0, 0x1c000
	v_add_u32_e32 v140, s53, v165
	v_add_u32_e32 v174, s54, v165
	ds_read_b128 v[128:131], v140
	ds_read_b128 v[132:135], v140 offset:1024
	ds_read_b128 v[136:139], v140 offset:2048
	ds_read_b128 v[140:143], v140 offset:3072
	ds_read_b128 v[156:159], v174
	ds_read_b128 v[160:163], v174 offset:1024
	ds_read_b128 v[170:173], v174 offset:2048
	ds_read_b128 v[174:177], v174 offset:3072
	s_add_u32 s26, s26, 0x100000
	s_addc_u32 s27, s27, 0
	s_mov_b32 m0, s37
	v_lshl_add_u64 v[218:219], s[26:27], 0, v[144:145]
	ds_read_b128 v[178:181], v169 offset:32768
	ds_read_b128 v[182:185], v169 offset:33792
	ds_read_b128 v[186:189], v169 offset:34816
	ds_read_b128 v[190:193], v169 offset:35840
	ds_read_b128 v[194:197], v169 offset:36864
	ds_read_b128 v[198:201], v169 offset:37888
	ds_read_b128 v[202:205], v169 offset:38912
	ds_read_b128 v[206:209], v169 offset:39936
	global_load_lds_dwordx4 v[218:219], off
	v_lshl_add_u64 v[218:219], s[26:27], 0, v[146:147]
	s_mov_b32 m0, s38
	s_nop 0
	global_load_lds_dwordx4 v[218:219], off
	s_waitcnt vmcnt(8)
	s_waitcnt lgkmcnt(0)
	s_barrier
	s_waitcnt lgkmcnt(0)
	v_mfma_f32_16x16x32_bf16 v[124:127], v[128:131], v[178:181], v[124:127]
	v_mfma_f32_16x16x32_bf16 v[120:123], v[136:139], v[178:181], v[120:123]
	v_mfma_f32_16x16x32_bf16 v[116:119], v[128:131], v[186:189], v[116:119]
	v_mfma_f32_16x16x32_bf16 v[108:111], v[136:139], v[186:189], v[108:111]
	v_mfma_f32_16x16x32_bf16 v[96:99], v[128:131], v[194:197], v[96:99]
	v_mfma_f32_16x16x32_bf16 v[88:91], v[136:139], v[194:197], v[88:91]
	v_mfma_f32_16x16x32_bf16 v[80:83], v[128:131], v[202:205], v[80:83]
	v_mfma_f32_16x16x32_bf16 v[72:75], v[136:139], v[202:205], v[72:75]
	v_mfma_f32_16x16x32_bf16 v[124:127], v[132:135], v[182:185], v[124:127]
	v_mfma_f32_16x16x32_bf16 v[120:123], v[140:143], v[182:185], v[120:123]
	v_mfma_f32_16x16x32_bf16 v[116:119], v[132:135], v[190:193], v[116:119]
	v_mfma_f32_16x16x32_bf16 v[108:111], v[140:143], v[190:193], v[108:111]
	v_mfma_f32_16x16x32_bf16 v[96:99], v[132:135], v[198:201], v[96:99]
	v_mfma_f32_16x16x32_bf16 v[88:91], v[140:143], v[198:201], v[88:91]
	v_mfma_f32_16x16x32_bf16 v[80:83], v[132:135], v[206:209], v[80:83]
	v_mfma_f32_16x16x32_bf16 v[72:75], v[140:143], v[206:209], v[72:75]
	v_mfma_f32_16x16x32_bf16 v[112:115], v[156:159], v[178:181], v[112:115]
	v_mfma_f32_16x16x32_bf16 v[104:107], v[170:173], v[178:181], v[104:107]
	v_mfma_f32_16x16x32_bf16 v[100:103], v[156:159], v[186:189], v[100:103]
	v_mfma_f32_16x16x32_bf16 v[92:95], v[170:173], v[186:189], v[92:95]
	v_mfma_f32_16x16x32_bf16 v[84:87], v[156:159], v[194:197], v[84:87]
	v_mfma_f32_16x16x32_bf16 v[76:79], v[170:173], v[194:197], v[76:79]
	v_mfma_f32_16x16x32_bf16 v[68:71], v[156:159], v[202:205], v[68:71]
	v_mfma_f32_16x16x32_bf16 v[64:67], v[170:173], v[202:205], v[64:67]
	v_mfma_f32_16x16x32_bf16 v[112:115], v[160:163], v[182:185], v[112:115]
	v_mfma_f32_16x16x32_bf16 v[104:107], v[174:177], v[182:185], v[104:107]
	v_mfma_f32_16x16x32_bf16 v[100:103], v[160:163], v[190:193], v[100:103]
	v_mfma_f32_16x16x32_bf16 v[92:95], v[174:177], v[190:193], v[92:95]
	v_mfma_f32_16x16x32_bf16 v[84:87], v[160:163], v[198:201], v[84:87]
	v_mfma_f32_16x16x32_bf16 v[76:79], v[174:177], v[198:201], v[76:79]
	v_mfma_f32_16x16x32_bf16 v[68:71], v[160:163], v[206:209], v[68:71]
	v_mfma_f32_16x16x32_bf16 v[64:67], v[174:177], v[206:209], v[64:67]
	s_barrier
; #define PG8_STAGE(bufoff, gbase, voff) do { _Pragma("unroll") for (int _i = 0; _i < 2; ++_i) \
;         __builtin_amdgcn_global_load_lds((const unsigned*)((const char*)(gbase) + (voff)[_i]), (PG8_LAS unsigned*)(lds + (bufoff) + ldsw + _i * 8192), 16, 0, 0); } while (0)
; #define PG8_LDA(dst, b, h) do { _Pragma("unroll") for (int m = 0; m < 4; ++m) _Pragma("unroll") for (int k = 0; k < 2; ++k) dst[m][k] = *(const PG8_LAS bf16x8*)(lds + PG8_SA(b, h) + aoff + m * 2048 + k * 1024); } while (0)
; #define PG8_MMA(ai, bj, At, Bt) do { __builtin_amdgcn_s_setprio(1); _Pragma("unroll") for (int m = 0; m < 4; ++m) _Pragma("unroll") for (int n = 0; n < 2; ++n) _Pragma("unroll") for (int k = 0; k < 2; ++k) \
;         acc[ai][bj][m][n] = __builtin_amdgcn_mfma_f32_16x16x32_bf16(Bt[n][k], At[m][k], acc[ai][bj][m][n], 0, 0, 0); __builtin_amdgcn_s_setprio(0); } while (0)
; #define PG8_WAIT_V(n) asm volatile("s_waitcnt vmcnt(" #n ")" ::: "memory")
; #define PG8_WAIT_L(n) asm volatile("s_waitcnt lgkmcnt(" #n ")" ::: "memory")
; #define PG8_BAR __builtin_amdgcn_s_barrier()
; #define PG8_SCHED __builtin_amdgcn_sched_barrier(0)
; template <class Epi, class Sched, bool ALIGN_EPI = false, bool SP2 = false>
; __device__ __forceinline__ void gemm_phase(PG8_LAS unsigned char* lds, const Gemm g, const Sched& S, const Epi& E) {
;     ...
;         for (int t = 0; t < nt; t += 2) {
;     ...
;             PG8_LDA(At, 1, 1); PG8_STAGE(PG8_SB(1, 0), b3, voffB); PG8_STAGE(PG8_SB(1, 1), b3 + hstep, voffB); PG8_STAGE(PG8_SA(1, 0), a3, voffA);
;             PG8_WAIT_V(8); PG8_WAIT_L(0); PG8_BAR; PG8_MMA(1, 0, At, B0); PG8_MMA(1, 1, At, B1); PG8_BAR; PG8_SCHED;
	s_add_i32 s26, s53, s33
	v_lshl_add_u64 v[210:211], v[210:211], 0, s[6:7]
	s_mov_b32 m0, s26
	ds_read_b128 v[178:181], v169 offset:49152
	ds_read_b128 v[182:185], v169 offset:50176
	ds_read_b128 v[186:189], v169 offset:51200
	ds_read_b128 v[190:193], v169 offset:52224
	ds_read_b128 v[194:197], v169 offset:53248
	ds_read_b128 v[198:201], v169 offset:54272
	ds_read_b128 v[202:205], v169 offset:55296
	ds_read_b128 v[206:209], v169 offset:56320
	global_load_lds_dwordx4 v[210:211], off
	s_add_i32 m0, s26, 0x2000
	s_add_u32 s2, s2, 0x100080
	v_lshl_add_u64 v[210:211], v[212:213], 0, s[6:7]
	s_addc_u32 s3, s3, 0
	s_add_i32 s26, s54, s33
	global_load_lds_dwordx4 v[210:211], off
	v_lshl_add_u64 v[210:211], s[2:3], 0, v[144:145]
	s_mov_b32 m0, s26
	s_nop 0
	global_load_lds_dwordx4 v[210:211], off
	v_lshl_add_u64 v[210:211], s[2:3], 0, v[146:147]
	s_add_i32 m0, s26, 0x2000
	s_nop 0
	global_load_lds_dwordx4 v[210:211], off
	v_lshl_add_u64 v[210:211], v[214:215], 0, s[6:7]
	s_mov_b32 m0, s43
	s_nop 0
	global_load_lds_dwordx4 v[210:211], off
	v_lshl_add_u64 v[210:211], v[216:217], 0, s[6:7]
	s_mov_b32 m0, s44
	s_nop 0
	global_load_lds_dwordx4 v[210:211], off
	s_waitcnt vmcnt(8)
	s_waitcnt lgkmcnt(0)
	s_barrier
	s_waitcnt lgkmcnt(0)
	v_mfma_f32_16x16x32_bf16 v[60:63], v[128:131], v[178:181], v[60:63]
	v_mfma_f32_16x16x32_bf16 v[56:59], v[136:139], v[178:181], v[56:59]
	v_mfma_f32_16x16x32_bf16 v[48:51], v[128:131], v[186:189], v[48:51]
	v_mfma_f32_16x16x32_bf16 v[40:43], v[136:139], v[186:189], v[40:43]
	v_mfma_f32_16x16x32_bf16 v[32:35], v[128:131], v[194:197], v[32:35]
	v_mfma_f32_16x16x32_bf16 v[24:27], v[136:139], v[194:197], v[24:27]
	v_mfma_f32_16x16x32_bf16 v[16:19], v[128:131], v[202:205], v[16:19]
	v_mfma_f32_16x16x32_bf16 v[8:11], v[136:139], v[202:205], v[8:11]
	v_mfma_f32_16x16x32_bf16 v[60:63], v[132:135], v[182:185], v[60:63]
	v_mfma_f32_16x16x32_bf16 v[56:59], v[140:143], v[182:185], v[56:59]
	v_mfma_f32_16x16x32_bf16 v[48:51], v[132:135], v[190:193], v[48:51]
	v_mfma_f32_16x16x32_bf16 v[40:43], v[140:143], v[190:193], v[40:43]
	v_mfma_f32_16x16x32_bf16 v[32:35], v[132:135], v[198:201], v[32:35]
	v_mfma_f32_16x16x32_bf16 v[24:27], v[140:143], v[198:201], v[24:27]
	v_mfma_f32_16x16x32_bf16 v[16:19], v[132:135], v[206:209], v[16:19]
	v_mfma_f32_16x16x32_bf16 v[8:11], v[140:143], v[206:209], v[8:11]
	v_mfma_f32_16x16x32_bf16 v[52:55], v[156:159], v[178:181], v[52:55]
	v_mfma_f32_16x16x32_bf16 v[44:47], v[170:173], v[178:181], v[44:47]
	v_mfma_f32_16x16x32_bf16 v[36:39], v[156:159], v[186:189], v[36:39]
	v_mfma_f32_16x16x32_bf16 v[28:31], v[170:173], v[186:189], v[28:31]
	v_mfma_f32_16x16x32_bf16 v[20:23], v[156:159], v[194:197], v[20:23]
	v_mfma_f32_16x16x32_bf16 v[12:15], v[170:173], v[194:197], v[12:15]
	v_mfma_f32_16x16x32_bf16 v[4:7], v[156:159], v[202:205], v[4:7]
	v_mfma_f32_16x16x32_bf16 v[0:3], v[170:173], v[202:205], v[0:3]
	v_mfma_f32_16x16x32_bf16 v[52:55], v[160:163], v[182:185], v[52:55]
	v_mfma_f32_16x16x32_bf16 v[44:47], v[174:177], v[182:185], v[44:47]
	v_mfma_f32_16x16x32_bf16 v[36:39], v[160:163], v[190:193], v[36:39]
	v_mfma_f32_16x16x32_bf16 v[28:31], v[174:177], v[190:193], v[28:31]
	v_mfma_f32_16x16x32_bf16 v[20:23], v[160:163], v[198:201], v[20:23]
	v_mfma_f32_16x16x32_bf16 v[12:15], v[174:177], v[198:201], v[12:15]
	v_mfma_f32_16x16x32_bf16 v[4:7], v[160:163], v[206:209], v[4:7]
	v_mfma_f32_16x16x32_bf16 v[0:3], v[174:177], v[206:209], v[0:3]
	s_barrier
	s_add_i32 s52, s52, 2
	s_add_u32 s24, s24, 0x100
	s_addc_u32 s25, s25, 0
	s_add_u32 s50, s50, 0x100
	s_addc_u32 s51, s51, 0
	s_cmp_gt_u32 s52, 61
	s_cbranch_scc0 .LBB0_1455
	s_setprio 0
	s_and_b64 vcc, exec, s[12:13]
	s_cbranch_vccz .LBB0_1458
	s_barrier
